# speedup vs baseline: 1.0082x; 1.0040x over previous
; #define PG8_STAGE(bufoff, gbase, voff) do { _Pragma("unroll") for (int _i = 0; _i < 2; ++_i) \
;         __builtin_amdgcn_global_load_lds((const unsigned*)((const char*)(gbase) + (voff)[_i]), (LAS unsigned*)(lds + (bufoff) + ldsw + _i * 8192), 16, 0, 0); } while (0)
; #define PG8_LDA(dst, b, h) do { _Pragma("unroll") for (int m = 0; m < 4; ++m) _Pragma("unroll") for (int k = 0; k < 2; ++k) dst[m][k] = *(const LAS bf16x8*)(lds + PG8_SA(b, h) + aoff + m * 2048 + k * 1024); } while (0)
; #define PG8_WAIT_V(n) asm volatile("s_waitcnt vmcnt(" #n ")" ::: "memory")
; template <class Epi, class Sched>
; __device__ __forceinline__ void gemm_phase(const int tid, LAS unsigned char* lds, const Gemm g, const Sched& S, const Epi& E) {
;     ...
;     for (;;) {
;         const bool has_next = S.next(ui + 1, nxt);
;         const char* nA = has_next ? (const char*)g.A + (size_t)nxt.pm * tstep : cA; const char* nB = has_next ? (const char*)g.Bt + (size_t)nxt.pn * tstep : cB;
;         for (int t = 0; t < nt; t += 2) {
;             const bool last = (t == nt - 2);
;             const char* a1 = cA + (size_t)(t + 1) * kstep;
;             const char* a2 = last ? nA : cA + (size_t)(t + 2) * kstep; const char* b2 = last ? nB : cB + (size_t)(t + 2) * kstep;
;             const char* a3 = a2 + kstep; const char* b3 = b2 + kstep;
;             if (last && has_next) S.a_ready(nxt);
;             PG8_LDB(B0, 0, 0); PG8_LDB(B1, 0, 1); PG8_SCHED; PG8_LDA(At, 0, 0); PG8_STAGE(PG8_SA(1, 1), a1 + hstep, voffA);
;             PG8_WAIT_V(8); PG8_WAIT_L(0); PG8_BAR; PG8_MMA(0, 0, At, B0); PG8_MMA(0, 1, At, B1); PG8_BAR; PG8_SCHED;
;             PG8_LDA(At, 0, 1); PG8_STAGE(PG8_SB(0, 0), b2, voffB); PG8_STAGE(PG8_SB(0, 1), b2 + hstep, voffB); PG8_STAGE(PG8_SA(0, 0), a2, voffA);
;             PG8_WAIT_V(8); PG8_WAIT_L(0); PG8_BAR; PG8_MMA(1, 0, At, B0); PG8_MMA(1, 1, At, B1); PG8_BAR; PG8_SCHED;
;             PG8_LDB(B0, 1, 0); PG8_LDB(B1, 1, 1); PG8_SCHED; PG8_LDA(At, 1, 0); PG8_STAGE(PG8_SA(0, 1), a2 + hstep, voffA);
;             PG8_WAIT_V(8); PG8_WAIT_L(0); PG8_BAR; PG8_MMA(0, 0, At, B0); PG8_MMA(0, 1, At, B1); PG8_BAR; PG8_SCHED;
;             PG8_LDA(At, 1, 1); PG8_STAGE(PG8_SB(1, 0), b3, voffB); PG8_STAGE(PG8_SB(1, 1), b3 + hstep, voffB); PG8_STAGE(PG8_SA(1, 0), a3, voffA);
;             PG8_WAIT_V(8); PG8_WAIT_L(0); PG8_BAR; PG8_MMA(1, 0, At, B0); PG8_MMA(1, 1, At, B1); PG8_BAR; PG8_SCHED;
.LBB0_49:
	s_ashr_i32 s15, s14, 31
	s_lshl_b64 s[16:17], s[14:15], 20
	s_add_u32 s16, s41, s16
	s_addc_u32 s17, s55, s17
	s_and_b64 s[18:19], s[0:1], exec
	s_cselect_b32 s15, s17, s23
	s_cselect_b32 s66, s16, s22
	s_ashr_i32 s13, s12, 31
	s_lshl_b64 s[18:19], s[12:13], 20
	v_readlane_b32 s13, v243, 16
	s_add_u32 s18, s13, s18
	v_readlane_b32 s13, v243, 17
	s_addc_u32 s19, s13, s19
	s_and_b64 s[26:27], s[0:1], exec
	s_cselect_b32 s13, s19, s25
	s_cselect_b32 s67, s18, s24
	s_add_u32 s22, s22, 0x80080
	s_addc_u32 s23, s23, 0
	s_add_u32 s68, s24, 0x100
	v_mov_b32_e32 v0, 0
	s_addc_u32 s69, s25, 0
	s_mov_b32 s70, -2
	s_add_u32 s24, s22, 0xfff80080
	s_addc_u32 s25, s23, -1
	s_add_i32 s71, 0, 0x10000
	s_cmp_eq_u32 s70, 28
	s_cselect_b32 s27, s15, s25
	s_cselect_b32 s26, s66, s24
	v_add_u32_e32 v150, s71, v148
	s_cselect_b32 s25, s13, s69
	s_cselect_b32 s24, s67, s68
	s_add_i32 s74, 0, 0x14000
	ds_read_b128 v[138:141], v150
	ds_read_b128 v[142:145], v150 offset:1024
	ds_read_b128 v[170:173], v150 offset:2048
	ds_read_b128 v[174:177], v150 offset:3072
	v_add_u32_e32 v150, s74, v148
	ds_read_b128 v[178:181], v150
	ds_read_b128 v[182:185], v150 offset:1024
	ds_read_b128 v[186:189], v150 offset:2048
	ds_read_b128 v[200:203], v150 offset:3072
	v_lshl_add_u64 v[150:151], s[22:23], 0, v[134:135]
	s_add_i32 m0, s21, 0xc000
	ds_read_b128 v[204:207], v149
	ds_read_b128 v[208:211], v149 offset:1024
	ds_read_b128 v[212:215], v149 offset:2048
	ds_read_b128 v[216:219], v149 offset:3072
	ds_read_b128 v[220:223], v149 offset:4096
	ds_read_b128 v[224:227], v149 offset:5120
	ds_read_b128 v[228:231], v149 offset:6144
	ds_read_b128 v[232:235], v149 offset:7168
	global_load_lds_dwordx4 v[150:151], off
	v_lshl_add_u64 v[150:151], s[22:23], 0, v[136:137]
	s_add_i32 m0, s21, 0xe000
	s_nop 0
	global_load_lds_dwordx4 v[150:151], off
	s_waitcnt vmcnt(8)
	s_waitcnt lgkmcnt(0)
	s_barrier
	s_setprio 1
	s_waitcnt lgkmcnt(0)
	v_mfma_f32_16x16x32_bf16 v[124:127], v[138:141], v[204:207], 0
	v_mfma_f32_16x16x32_bf16 v[120:123], v[170:173], v[204:207], 0
	v_mfma_f32_16x16x32_bf16 v[112:115], v[138:141], v[212:215], 0
	v_mfma_f32_16x16x32_bf16 v[104:107], v[170:173], v[212:215], 0
	v_mfma_f32_16x16x32_bf16 v[96:99], v[138:141], v[220:223], 0
	v_mfma_f32_16x16x32_bf16 v[88:91], v[170:173], v[220:223], 0
	v_mfma_f32_16x16x32_bf16 v[80:83], v[138:141], v[228:231], 0
	v_mfma_f32_16x16x32_bf16 v[72:75], v[170:173], v[228:231], 0
	v_mfma_f32_16x16x32_bf16 v[124:127], v[142:145], v[208:211], v[124:127]
	v_mfma_f32_16x16x32_bf16 v[120:123], v[174:177], v[208:211], v[120:123]
	v_mfma_f32_16x16x32_bf16 v[112:115], v[142:145], v[216:219], v[112:115]
	v_mfma_f32_16x16x32_bf16 v[104:107], v[174:177], v[216:219], v[104:107]
	v_mfma_f32_16x16x32_bf16 v[96:99], v[142:145], v[224:227], v[96:99]
	v_mfma_f32_16x16x32_bf16 v[88:91], v[174:177], v[224:227], v[88:91]
	v_mfma_f32_16x16x32_bf16 v[80:83], v[142:145], v[232:235], v[80:83]
	v_mfma_f32_16x16x32_bf16 v[72:75], v[174:177], v[232:235], v[72:75]
	s_setprio 0
	s_setprio 1
	v_mfma_f32_16x16x32_bf16 v[116:119], v[178:181], v[204:207], 0
	v_mfma_f32_16x16x32_bf16 v[108:111], v[186:189], v[204:207], 0
	v_mfma_f32_16x16x32_bf16 v[100:103], v[178:181], v[212:215], 0
	v_mfma_f32_16x16x32_bf16 v[92:95], v[186:189], v[212:215], 0
	v_mfma_f32_16x16x32_bf16 v[84:87], v[178:181], v[220:223], 0
	v_mfma_f32_16x16x32_bf16 v[76:79], v[186:189], v[220:223], 0
	v_mfma_f32_16x16x32_bf16 v[68:71], v[178:181], v[228:231], 0
	v_mfma_f32_16x16x32_bf16 v[64:67], v[186:189], v[228:231], 0
	v_mfma_f32_16x16x32_bf16 v[116:119], v[182:185], v[208:211], v[116:119]
	v_mfma_f32_16x16x32_bf16 v[108:111], v[200:203], v[208:211], v[108:111]
	v_mfma_f32_16x16x32_bf16 v[100:103], v[182:185], v[216:219], v[100:103]
	v_mfma_f32_16x16x32_bf16 v[92:95], v[200:203], v[216:219], v[92:95]
	v_mfma_f32_16x16x32_bf16 v[84:87], v[182:185], v[224:227], v[84:87]
	v_mfma_f32_16x16x32_bf16 v[76:79], v[200:203], v[224:227], v[76:79]
	v_mfma_f32_16x16x32_bf16 v[68:71], v[182:185], v[232:235], v[68:71]
	v_mfma_f32_16x16x32_bf16 v[64:67], v[200:203], v[232:235], v[64:67]
	s_setprio 0
	s_barrier
	s_add_i32 s71, s71, s40
	v_lshl_add_u64 v[150:151], s[24:25], 0, v[152:153]
	s_mov_b32 m0, s71
	ds_read_b128 v[204:207], v149 offset:16384
	ds_read_b128 v[208:211], v149 offset:17408
	ds_read_b128 v[212:215], v149 offset:18432
	ds_read_b128 v[216:219], v149 offset:19456
	ds_read_b128 v[220:223], v149 offset:20480
	ds_read_b128 v[224:227], v149 offset:21504
	ds_read_b128 v[228:231], v149 offset:22528
	ds_read_b128 v[232:235], v149 offset:23552
	global_load_lds_dwordx4 v[150:151], off
	s_add_i32 m0, s71, 0x2000
	s_add_u32 s72, s24, 0x80000
	v_lshl_add_u64 v[190:191], s[24:25], 0, v[128:129]
	s_addc_u32 s73, s25, 0
	s_add_i32 s71, s74, s40
	global_load_lds_dwordx4 v[190:191], off
	v_lshl_add_u64 v[236:237], s[72:73], 0, v[152:153]
	s_mov_b32 m0, s71
	v_lshl_add_u64 v[238:239], s[26:27], 0, v[130:131]
	global_load_lds_dwordx4 v[236:237], off
	v_lshl_add_u64 v[236:237], s[72:73], 0, v[128:129]
	s_add_i32 m0, s71, 0x2000
	s_nop 0
	global_load_lds_dwordx4 v[236:237], off
	v_lshl_add_u64 v[236:237], s[26:27], 0, v[132:133]
	s_mov_b32 m0, s21
	s_nop 0
	global_load_lds_dwordx4 v[236:237], off
	s_mov_b32 m0, s56
	s_nop 0
	global_load_lds_dwordx4 v[238:239], off
	s_waitcnt vmcnt(8)
	s_waitcnt lgkmcnt(0)
	s_barrier
; #define PG8_STAGE(bufoff, gbase, voff) do { _Pragma("unroll") for (int _i = 0; _i < 2; ++_i) \
;         __builtin_amdgcn_global_load_lds((const unsigned*)((const char*)(gbase) + (voff)[_i]), (LAS unsigned*)(lds + (bufoff) + ldsw + _i * 8192), 16, 0, 0); } while (0)
; #define PG8_LDA(dst, b, h) do { _Pragma("unroll") for (int m = 0; m < 4; ++m) _Pragma("unroll") for (int k = 0; k < 2; ++k) dst[m][k] = *(const LAS bf16x8*)(lds + PG8_SA(b, h) + aoff + m * 2048 + k * 1024); } while (0)
; #define PG8_LDB(dst, b, h) do { _Pragma("unroll") for (int n = 0; n < 2; ++n) _Pragma("unroll") for (int k = 0; k < 2; ++k) dst[n][k] = *(const LAS bf16x8*)(lds + PG8_SB(b, h) + boff + n * 2048 + k * 1024); } while (0)
; #define PG8_MMA(ai, bj, At, Bt) do { __builtin_amdgcn_s_setprio(1); _Pragma("unroll") for (int m = 0; m < 4; ++m) _Pragma("unroll") for (int n = 0; n < 2; ++n) _Pragma("unroll") for (int k = 0; k < 2; ++k) \
;         acc[ai][bj][m][n] = __builtin_amdgcn_mfma_f32_16x16x32_bf16(Bt[n][k], At[m][k], acc[ai][bj][m][n], 0, 0, 0); __builtin_amdgcn_s_setprio(0); } while (0)
; #define PG8_WAIT_V(n) asm volatile("s_waitcnt vmcnt(" #n ")" ::: "memory")
; #define PG8_WAIT_L(n) asm volatile("s_waitcnt lgkmcnt(" #n ")" ::: "memory")
; #define PG8_BAR __builtin_amdgcn_s_barrier()
; template <class Epi, class Sched>
; __device__ __forceinline__ void gemm_phase(const int tid, LAS unsigned char* lds, const Gemm g, const Sched& S, const Epi& E) {
;     ...
;             PG8_WAIT_V(8); PG8_WAIT_L(0); PG8_BAR; PG8_MMA(0, 0, At, B0); PG8_MMA(0, 1, At, B1); PG8_BAR; PG8_SCHED;
;             PG8_LDA(At, 0, 1); PG8_STAGE(PG8_SB(0, 0), b2, voffB); PG8_STAGE(PG8_SB(0, 1), b2 + hstep, voffB); PG8_STAGE(PG8_SA(0, 0), a2, voffA);
;             PG8_WAIT_V(8); PG8_WAIT_L(0); PG8_BAR; PG8_MMA(1, 0, At, B0); PG8_MMA(1, 1, At, B1); PG8_BAR; PG8_SCHED;
;             PG8_LDB(B0, 1, 0); PG8_LDB(B1, 1, 1); PG8_SCHED; PG8_LDA(At, 1, 0); PG8_STAGE(PG8_SA(0, 1), a2 + hstep, voffA);
;             PG8_WAIT_V(8); PG8_WAIT_L(0); PG8_BAR; PG8_MMA(0, 0, At, B0); PG8_MMA(0, 1, At, B1); PG8_BAR; PG8_SCHED;
;             PG8_LDA(At, 1, 1); PG8_STAGE(PG8_SB(1, 0), b3, voffB); PG8_STAGE(PG8_SB(1, 1), b3 + hstep, voffB); PG8_STAGE(PG8_SA(1, 0), a3, voffA);
;             PG8_WAIT_V(8); PG8_WAIT_L(0); PG8_BAR; PG8_MMA(1, 0, At, B0); PG8_MMA(1, 1, At, B1); PG8_BAR; PG8_SCHED;
	s_setprio 1
	s_waitcnt lgkmcnt(0)
	v_mfma_f32_16x16x32_bf16 v[60:63], v[138:141], v[204:207], 0
	v_mfma_f32_16x16x32_bf16 v[56:59], v[170:173], v[204:207], 0
	v_mfma_f32_16x16x32_bf16 v[48:51], v[138:141], v[212:215], 0
	v_mfma_f32_16x16x32_bf16 v[40:43], v[170:173], v[212:215], 0
	v_mfma_f32_16x16x32_bf16 v[32:35], v[138:141], v[220:223], 0
	v_mfma_f32_16x16x32_bf16 v[24:27], v[170:173], v[220:223], 0
	v_mfma_f32_16x16x32_bf16 v[16:19], v[138:141], v[228:231], 0
	v_mfma_f32_16x16x32_bf16 v[8:11], v[170:173], v[228:231], 0
	v_mfma_f32_16x16x32_bf16 v[60:63], v[142:145], v[208:211], v[60:63]
	v_mfma_f32_16x16x32_bf16 v[56:59], v[174:177], v[208:211], v[56:59]
	v_mfma_f32_16x16x32_bf16 v[48:51], v[142:145], v[216:219], v[48:51]
	v_mfma_f32_16x16x32_bf16 v[40:43], v[174:177], v[216:219], v[40:43]
	v_mfma_f32_16x16x32_bf16 v[32:35], v[142:145], v[224:227], v[32:35]
	v_mfma_f32_16x16x32_bf16 v[24:27], v[174:177], v[224:227], v[24:27]
	v_mfma_f32_16x16x32_bf16 v[16:19], v[142:145], v[232:235], v[16:19]
	v_mfma_f32_16x16x32_bf16 v[8:11], v[174:177], v[232:235], v[8:11]
	s_setprio 0
	s_setprio 1
	v_mfma_f32_16x16x32_bf16 v[52:55], v[178:181], v[204:207], 0
	v_mfma_f32_16x16x32_bf16 v[44:47], v[186:189], v[204:207], 0
	v_mfma_f32_16x16x32_bf16 v[36:39], v[178:181], v[212:215], 0
	v_mfma_f32_16x16x32_bf16 v[28:31], v[186:189], v[212:215], 0
	v_mfma_f32_16x16x32_bf16 v[20:23], v[178:181], v[220:223], 0
	v_mfma_f32_16x16x32_bf16 v[12:15], v[186:189], v[220:223], 0
	v_mfma_f32_16x16x32_bf16 v[4:7], v[178:181], v[228:231], 0
	v_mfma_f32_16x16x32_bf16 v[0:3], v[186:189], v[228:231], 0
	v_mfma_f32_16x16x32_bf16 v[52:55], v[182:185], v[208:211], v[52:55]
	v_mfma_f32_16x16x32_bf16 v[44:47], v[200:203], v[208:211], v[44:47]
	v_mfma_f32_16x16x32_bf16 v[36:39], v[182:185], v[216:219], v[36:39]
	v_mfma_f32_16x16x32_bf16 v[28:31], v[200:203], v[216:219], v[28:31]
	v_mfma_f32_16x16x32_bf16 v[20:23], v[182:185], v[224:227], v[20:23]
	v_mfma_f32_16x16x32_bf16 v[12:15], v[200:203], v[224:227], v[12:15]
	v_mfma_f32_16x16x32_bf16 v[4:7], v[182:185], v[232:235], v[4:7]
	v_mfma_f32_16x16x32_bf16 v[0:3], v[200:203], v[232:235], v[0:3]
	s_setprio 0
	s_barrier
	s_add_i32 s71, 0, 0x18000
	s_add_i32 s72, 0, 0x1c000
	v_add_u32_e32 v174, s71, v148
	v_add_u32_e32 v199, s72, v148
	ds_read_b128 v[138:141], v174
	ds_read_b128 v[142:145], v174 offset:1024
	ds_read_b128 v[170:173], v174 offset:2048
	ds_read_b128 v[174:177], v174 offset:3072
	ds_read_b128 v[178:181], v199
	ds_read_b128 v[182:185], v199 offset:1024
	ds_read_b128 v[186:189], v199 offset:2048
	ds_read_b128 v[200:203], v199 offset:3072
	s_add_u32 s26, s26, 0x80000
	s_addc_u32 s27, s27, 0
	s_mov_b32 m0, s57
	v_lshl_add_u64 v[240:241], s[26:27], 0, v[132:133]
	ds_read_b128 v[204:207], v149 offset:32768
	ds_read_b128 v[208:211], v149 offset:33792
	ds_read_b128 v[212:215], v149 offset:34816
	ds_read_b128 v[216:219], v149 offset:35840
	ds_read_b128 v[220:223], v149 offset:36864
	ds_read_b128 v[224:227], v149 offset:37888
	ds_read_b128 v[228:231], v149 offset:38912
	ds_read_b128 v[232:235], v149 offset:39936
	global_load_lds_dwordx4 v[240:241], off
	v_lshl_add_u64 v[240:241], s[26:27], 0, v[130:131]
	s_mov_b32 m0, s58
	s_nop 0
	global_load_lds_dwordx4 v[240:241], off
	s_waitcnt vmcnt(8)
	s_waitcnt lgkmcnt(0)
	s_barrier
	s_setprio 1
	s_waitcnt lgkmcnt(0)
	v_mfma_f32_16x16x32_bf16 v[124:127], v[138:141], v[204:207], v[124:127]
	v_mfma_f32_16x16x32_bf16 v[120:123], v[170:173], v[204:207], v[120:123]
	v_mfma_f32_16x16x32_bf16 v[112:115], v[138:141], v[212:215], v[112:115]
	v_mfma_f32_16x16x32_bf16 v[104:107], v[170:173], v[212:215], v[104:107]
	v_mfma_f32_16x16x32_bf16 v[96:99], v[138:141], v[220:223], v[96:99]
	v_mfma_f32_16x16x32_bf16 v[88:91], v[170:173], v[220:223], v[88:91]
	v_mfma_f32_16x16x32_bf16 v[80:83], v[138:141], v[228:231], v[80:83]
	v_mfma_f32_16x16x32_bf16 v[72:75], v[170:173], v[228:231], v[72:75]
	v_mfma_f32_16x16x32_bf16 v[124:127], v[142:145], v[208:211], v[124:127]
	v_mfma_f32_16x16x32_bf16 v[120:123], v[174:177], v[208:211], v[120:123]
	v_mfma_f32_16x16x32_bf16 v[112:115], v[142:145], v[216:219], v[112:115]
	v_mfma_f32_16x16x32_bf16 v[104:107], v[174:177], v[216:219], v[104:107]
	v_mfma_f32_16x16x32_bf16 v[96:99], v[142:145], v[224:227], v[96:99]
	v_mfma_f32_16x16x32_bf16 v[88:91], v[174:177], v[224:227], v[88:91]
	v_mfma_f32_16x16x32_bf16 v[80:83], v[142:145], v[232:235], v[80:83]
	v_mfma_f32_16x16x32_bf16 v[72:75], v[174:177], v[232:235], v[72:75]
	s_setprio 0
	s_setprio 1
	v_mfma_f32_16x16x32_bf16 v[116:119], v[178:181], v[204:207], v[116:119]
	v_mfma_f32_16x16x32_bf16 v[108:111], v[186:189], v[204:207], v[108:111]
	v_mfma_f32_16x16x32_bf16 v[100:103], v[178:181], v[212:215], v[100:103]
	v_mfma_f32_16x16x32_bf16 v[92:95], v[186:189], v[212:215], v[92:95]
	v_mfma_f32_16x16x32_bf16 v[84:87], v[178:181], v[220:223], v[84:87]
	v_mfma_f32_16x16x32_bf16 v[76:79], v[186:189], v[220:223], v[76:79]
	v_mfma_f32_16x16x32_bf16 v[68:71], v[178:181], v[228:231], v[68:71]
	v_mfma_f32_16x16x32_bf16 v[64:67], v[186:189], v[228:231], v[64:67]
	v_mfma_f32_16x16x32_bf16 v[116:119], v[182:185], v[208:211], v[116:119]
	v_mfma_f32_16x16x32_bf16 v[108:111], v[200:203], v[208:211], v[108:111]
	v_mfma_f32_16x16x32_bf16 v[100:103], v[182:185], v[216:219], v[100:103]
	v_mfma_f32_16x16x32_bf16 v[92:95], v[200:203], v[216:219], v[92:95]
	v_mfma_f32_16x16x32_bf16 v[84:87], v[182:185], v[224:227], v[84:87]
	v_mfma_f32_16x16x32_bf16 v[76:79], v[200:203], v[224:227], v[76:79]
	v_mfma_f32_16x16x32_bf16 v[68:71], v[182:185], v[232:235], v[68:71]
	v_mfma_f32_16x16x32_bf16 v[64:67], v[200:203], v[232:235], v[64:67]
	s_setprio 0
	s_barrier
; #define PG8_STAGE(bufoff, gbase, voff) do { _Pragma("unroll") for (int _i = 0; _i < 2; ++_i) \
;         __builtin_amdgcn_global_load_lds((const unsigned*)((const char*)(gbase) + (voff)[_i]), (LAS unsigned*)(lds + (bufoff) + ldsw + _i * 8192), 16, 0, 0); } while (0)
; #define PG8_LDA(dst, b, h) do { _Pragma("unroll") for (int m = 0; m < 4; ++m) _Pragma("unroll") for (int k = 0; k < 2; ++k) dst[m][k] = *(const LAS bf16x8*)(lds + PG8_SA(b, h) + aoff + m * 2048 + k * 1024); } while (0)
; #define PG8_MMA(ai, bj, At, Bt) do { __builtin_amdgcn_s_setprio(1); _Pragma("unroll") for (int m = 0; m < 4; ++m) _Pragma("unroll") for (int n = 0; n < 2; ++n) _Pragma("unroll") for (int k = 0; k < 2; ++k) \
;         acc[ai][bj][m][n] = __builtin_amdgcn_mfma_f32_16x16x32_bf16(Bt[n][k], At[m][k], acc[ai][bj][m][n], 0, 0, 0); __builtin_amdgcn_s_setprio(0); } while (0)
; #define PG8_WAIT_V(n) asm volatile("s_waitcnt vmcnt(" #n ")" ::: "memory")
; #define PG8_WAIT_L(n) asm volatile("s_waitcnt lgkmcnt(" #n ")" ::: "memory")
; #define PG8_BAR __builtin_amdgcn_s_barrier()
; #define PG8_SCHED __builtin_amdgcn_sched_barrier(0)
; template <class Epi, class Sched>
; __device__ __forceinline__ void gemm_phase(const int tid, LAS unsigned char* lds, const Gemm g, const Sched& S, const Epi& E) {
;     ...
;             PG8_LDA(At, 1, 1); PG8_STAGE(PG8_SB(1, 0), b3, voffB); PG8_STAGE(PG8_SB(1, 1), b3 + hstep, voffB); PG8_STAGE(PG8_SA(1, 0), a3, voffA);
;             PG8_WAIT_V(8); PG8_WAIT_L(0); PG8_BAR; PG8_MMA(1, 0, At, B0); PG8_MMA(1, 1, At, B1); PG8_BAR; PG8_SCHED;
;         }
	s_add_i32 s26, s71, s40
	v_lshl_add_u64 v[150:151], v[150:151], 0, s[34:35]
	s_mov_b32 m0, s26
	ds_read_b128 v[204:207], v149 offset:49152
	ds_read_b128 v[208:211], v149 offset:50176
	ds_read_b128 v[212:215], v149 offset:51200
	ds_read_b128 v[216:219], v149 offset:52224
	ds_read_b128 v[220:223], v149 offset:53248
	ds_read_b128 v[224:227], v149 offset:54272
	ds_read_b128 v[228:231], v149 offset:55296
	ds_read_b128 v[232:235], v149 offset:56320
	global_load_lds_dwordx4 v[150:151], off
	s_add_i32 m0, s26, 0x2000
	s_add_u32 s24, s24, 0x80080
	v_lshl_add_u64 v[150:151], v[190:191], 0, s[34:35]
	s_addc_u32 s25, s25, 0
	s_add_i32 s26, s72, s40
	global_load_lds_dwordx4 v[150:151], off
	v_lshl_add_u64 v[150:151], s[24:25], 0, v[152:153]
	s_mov_b32 m0, s26
	s_nop 0
	global_load_lds_dwordx4 v[150:151], off
	v_lshl_add_u64 v[150:151], s[24:25], 0, v[128:129]
	s_add_i32 m0, s26, 0x2000
	s_nop 0
	global_load_lds_dwordx4 v[150:151], off
	v_lshl_add_u64 v[150:151], v[236:237], 0, s[34:35]
	s_mov_b32 m0, s61
	s_nop 0
	global_load_lds_dwordx4 v[150:151], off
	v_lshl_add_u64 v[150:151], v[238:239], 0, s[34:35]
	s_mov_b32 m0, s62
	s_nop 0
	global_load_lds_dwordx4 v[150:151], off
	s_waitcnt vmcnt(8)
	s_waitcnt lgkmcnt(0)
	s_barrier
	s_setprio 1
	s_waitcnt lgkmcnt(0)
	v_mfma_f32_16x16x32_bf16 v[60:63], v[138:141], v[204:207], v[60:63]
	v_mfma_f32_16x16x32_bf16 v[56:59], v[170:173], v[204:207], v[56:59]
	v_mfma_f32_16x16x32_bf16 v[48:51], v[138:141], v[212:215], v[48:51]
	v_mfma_f32_16x16x32_bf16 v[40:43], v[170:173], v[212:215], v[40:43]
	v_mfma_f32_16x16x32_bf16 v[32:35], v[138:141], v[220:223], v[32:35]
	v_mfma_f32_16x16x32_bf16 v[24:27], v[170:173], v[220:223], v[24:27]
	v_mfma_f32_16x16x32_bf16 v[16:19], v[138:141], v[228:231], v[16:19]
	v_mfma_f32_16x16x32_bf16 v[8:11], v[170:173], v[228:231], v[8:11]
	v_mfma_f32_16x16x32_bf16 v[60:63], v[142:145], v[208:211], v[60:63]
	v_mfma_f32_16x16x32_bf16 v[56:59], v[174:177], v[208:211], v[56:59]
	v_mfma_f32_16x16x32_bf16 v[48:51], v[142:145], v[216:219], v[48:51]
	v_mfma_f32_16x16x32_bf16 v[40:43], v[174:177], v[216:219], v[40:43]
	v_mfma_f32_16x16x32_bf16 v[32:35], v[142:145], v[224:227], v[32:35]
	v_mfma_f32_16x16x32_bf16 v[24:27], v[174:177], v[224:227], v[24:27]
	v_mfma_f32_16x16x32_bf16 v[16:19], v[142:145], v[232:235], v[16:19]
	v_mfma_f32_16x16x32_bf16 v[8:11], v[174:177], v[232:235], v[8:11]
	s_setprio 0
	s_setprio 1
	v_mfma_f32_16x16x32_bf16 v[52:55], v[178:181], v[204:207], v[52:55]
	v_mfma_f32_16x16x32_bf16 v[44:47], v[186:189], v[204:207], v[44:47]
	v_mfma_f32_16x16x32_bf16 v[36:39], v[178:181], v[212:215], v[36:39]
	v_mfma_f32_16x16x32_bf16 v[28:31], v[186:189], v[212:215], v[28:31]
	v_mfma_f32_16x16x32_bf16 v[20:23], v[178:181], v[220:223], v[20:23]
	v_mfma_f32_16x16x32_bf16 v[12:15], v[186:189], v[220:223], v[12:15]
	v_mfma_f32_16x16x32_bf16 v[4:7], v[178:181], v[228:231], v[4:7]
	v_mfma_f32_16x16x32_bf16 v[0:3], v[186:189], v[228:231], v[0:3]
	v_mfma_f32_16x16x32_bf16 v[52:55], v[182:185], v[208:211], v[52:55]
	v_mfma_f32_16x16x32_bf16 v[44:47], v[200:203], v[208:211], v[44:47]
	v_mfma_f32_16x16x32_bf16 v[36:39], v[182:185], v[216:219], v[36:39]
	v_mfma_f32_16x16x32_bf16 v[28:31], v[200:203], v[216:219], v[28:31]
	v_mfma_f32_16x16x32_bf16 v[20:23], v[182:185], v[224:227], v[20:23]
	v_mfma_f32_16x16x32_bf16 v[12:15], v[200:203], v[224:227], v[12:15]
	v_mfma_f32_16x16x32_bf16 v[4:7], v[182:185], v[232:235], v[4:7]
	v_mfma_f32_16x16x32_bf16 v[0:3], v[200:203], v[232:235], v[0:3]
	s_setprio 0
	s_barrier
	s_add_i32 s70, s70, 2
	s_add_u32 s22, s22, 0x100
	s_addc_u32 s23, s23, 0
	s_add_u32 s68, s68, 0x100
	s_addc_u32 s69, s69, 0
	s_cmp_gt_u32 s70, 29

; __device__ __forceinline__ unsigned pk2(float lo, float hi) { return f2bf(lo) | (f2bf(hi) << 16); }
; __device__ __forceinline__ void gmlp_fast(KArgs ap, int l, LAS unsigned char* lds, const Ctx cx) {
;     ...
;             const size_t t = t0 + tl; const float bsv = bsp[g * 128 + tl];
;             const bf16_t* zu = z + t * DIN + ZGU + g * 128 + 4 * hh; bf16_t* yo = y + t * DM + YG + g * 128 + 4 * hh;
; #pragma unroll
;             for (int ht = 0; ht < 4; ++ht)
; #pragma unroll
;                 for (int q4 = 0; q4 < 4; ++q4) { const u32x2 uu = *(const u32x2*)(zu + ht * 32 + 8 * q4);
;                     const float o0 = gelu_tanh(bflo(uu.x)) * (acc[ht][4 * q4] + bsv), o1 = gelu_tanh(bfhi(uu.x)) * (acc[ht][4 * q4 + 1] + bsv);
;                     const float o2 = gelu_tanh(bflo(uu.y)) * (acc[ht][4 * q4 + 2] + bsv), o3 = gelu_tanh(bfhi(uu.y)) * (acc[ht][4 * q4 + 3] + bsv);
;                     u32x2 w; w.x = pk2(o0, o1); w.y = pk2(o2, o3); *(u32x2*)(yo + ht * 32 + 8 * q4) = w; }
.LBB0_160:
	s_lshl_b32 s20, s20, 7
	s_ashr_i32 s21, s20, 31
	v_or_b32_e32 v64, s20, v80
	s_lshl_b64 s[20:21], s[20:21], 1
	v_lshl_add_u64 v[68:69], v[94:95], 0, s[20:21]
	global_load_dwordx2 v[70:71], v[68:69], off offset:3584
	v_ashrrev_i32_e32 v65, 31, v64
	v_lshl_add_u64 v[64:65], v[64:65], 2, s[14:15]
	global_load_dword v64, v[64:65], off
	global_load_dwordx2 v[200:201], v[68:69], off offset:3600
	global_load_dwordx2 v[202:203], v[68:69], off offset:3616
	global_load_dwordx2 v[204:205], v[68:69], off offset:3632
	global_load_dwordx2 v[206:207], v[68:69], off offset:3648
	global_load_dwordx2 v[208:209], v[68:69], off offset:3664
	global_load_dwordx2 v[210:211], v[68:69], off offset:3680
	global_load_dwordx2 v[212:213], v[68:69], off offset:3696
	global_load_dwordx2 v[214:215], v[68:69], off offset:3712
	global_load_dwordx2 v[216:217], v[68:69], off offset:3728
	global_load_dwordx2 v[218:219], v[68:69], off offset:3744
	global_load_dwordx2 v[220:221], v[68:69], off offset:3760
	global_load_dwordx2 v[222:223], v[68:69], off offset:3776
	global_load_dwordx2 v[224:225], v[68:69], off offset:3792
	global_load_dwordx2 v[226:227], v[68:69], off offset:3808
	global_load_dwordx2 v[228:229], v[68:69], off offset:3824
	v_lshl_add_u64 v[66:67], v[96:97], 0, s[20:21]
	s_mov_b32 s13, 1
	s_mov_b64 s[20:21], 0
	s_and_b64 vcc, exec, s[0:1]
	s_waitcnt vmcnt(16)
	v_lshlrev_b32_e32 v72, 16, v70
	v_mul_f32_e32 v65, 0x3d372713, v72
	v_mul_f32_e32 v65, v65, v72
	v_mov_b32_e32 v74, v72
	v_fmac_f32_e32 v74, v65, v74
	v_mul_f32_e32 v65, 0x3f4c422a, v74
	v_add_f32_e32 v65, v65, v65
	v_mul_f32_e32 v65, 0x3fb8aa3b, v65
	v_exp_f32_e32 v65, v65
	v_and_b32_e32 v70, 0xffff0000, v70
	v_mov_b32_e32 v75, v70
	v_lshlrev_b32_e32 v73, 16, v71
	v_add_f32_e32 v65, 1.0, v65
	v_rcp_f32_e32 v74, v65
	v_mul_f32_e32 v65, 0x3d372713, v70
	v_mul_f32_e32 v65, v65, v70
	v_fmac_f32_e32 v75, v65, v75
	v_mul_f32_e32 v65, 0x3f4c422a, v75
	v_add_f32_e32 v65, v65, v65
	v_mul_f32_e32 v65, 0x3fb8aa3b, v65
	v_exp_f32_e32 v65, v65
	v_mov_b32_e32 v75, v73
	v_and_b32_e32 v71, 0xffff0000, v71
	v_add_f32_e32 v65, 1.0, v65
	v_rcp_f32_e32 v76, v65
	v_mul_f32_e32 v65, 0x3d372713, v73
	v_mul_f32_e32 v65, v65, v73
	v_fmac_f32_e32 v75, v65, v75
	v_mul_f32_e32 v65, 0x3f4c422a, v75
	v_add_f32_e32 v65, v65, v65
	v_mul_f32_e32 v65, 0x3fb8aa3b, v65
	v_exp_f32_e32 v65, v65
	v_pk_mul_f32 v[72:73], v[72:73], 0.5 op_sel_hi:[1,0]
	v_add_f32_e32 v65, 1.0, v65
	v_rcp_f32_e32 v75, v65
	s_nop 0
	v_pk_fma_f32 v[74:75], v[74:75], 2.0, 1.0 op_sel_hi:[1,0,0] neg_lo:[1,0,0] neg_hi:[1,0,0]
	s_nop 0
	v_pk_add_f32 v[74:75], v[74:75], 1.0 op_sel_hi:[1,0]
	s_nop 0
	v_pk_mul_f32 v[72:73], v[72:73], v[74:75]
	v_mov_b32_e32 v74, v48
	v_mul_f32_e32 v48, 0x3d372713, v71
	v_mov_b32_e32 v75, v50
	v_mul_f32_e32 v48, v48, v71
	v_mov_b32_e32 v50, v71
	v_fmac_f32_e32 v50, v48, v50
	v_mul_f32_e32 v48, 0x3f4c422a, v50
	v_add_f32_e32 v48, v48, v48
	v_mul_f32_e32 v48, 0x3fb8aa3b, v48
	v_exp_f32_e32 v48, v48
	s_waitcnt vmcnt(15)
	v_pk_add_f32 v[74:75], v[74:75], v[64:65] op_sel_hi:[1,0]
	v_pk_mul_f32 v[70:71], v[70:71], 0.5 op_sel_hi:[1,0]
	v_pk_mul_f32 v[72:73], v[74:75], v[72:73]
	v_add_f32_e32 v48, 1.0, v48
	v_rcp_f32_e32 v77, v48
	v_mov_b32_e32 v50, v49
	v_pk_add_f32 v[48:49], v[50:51], v[64:65] op_sel_hi:[1,0]
	v_and_b32_sdwa v50, v73, v196 dst_sel:DWORD dst_unused:UNUSED_PAD src0_sel:WORD_1 src1_sel:DWORD
	v_pk_fma_f32 v[74:75], v[76:77], 2.0, 1.0 op_sel_hi:[1,0,0] neg_lo:[1,0,0] neg_hi:[1,0,0]
	v_and_b32_sdwa v51, v72, v196 dst_sel:DWORD dst_unused:UNUSED_PAD src0_sel:WORD_1 src1_sel:DWORD
	v_pk_add_f32 v[74:75], v[74:75], 1.0 op_sel_hi:[1,0]
	v_add3_u32 v51, v72, v51, s45
	v_pk_mul_f32 v[70:71], v[70:71], v[74:75]
	v_add3_u32 v50, v73, v50, s45
	v_pk_mul_f32 v[48:49], v[48:49], v[70:71]
	s_nop 0
	v_and_b32_sdwa v65, v49, v196 dst_sel:DWORD dst_unused:UNUSED_PAD src0_sel:WORD_1 src1_sel:DWORD
	v_and_b32_sdwa v70, v48, v196 dst_sel:DWORD dst_unused:UNUSED_PAD src0_sel:WORD_1 src1_sel:DWORD
	v_add3_u32 v49, v49, v65, s45
	v_add3_u32 v48, v48, v70, s45
	v_and_b32_e32 v49, 0xffff0000, v49
	v_and_b32_e32 v48, 0xffff0000, v48
	v_or_b32_sdwa v49, v49, v50 dst_sel:DWORD dst_unused:UNUSED_PAD src0_sel:DWORD src1_sel:WORD_1
	v_or_b32_sdwa v48, v48, v51 dst_sel:DWORD dst_unused:UNUSED_PAD src0_sel:DWORD src1_sel:WORD_1
	global_store_dwordx2 v[66:67], v[48:49], off
	s_waitcnt vmcnt(15)
; __device__ __forceinline__ unsigned pk2(float lo, float hi) { return f2bf(lo) | (f2bf(hi) << 16); }
; __device__ __forceinline__ void gmlp_fast(KArgs ap, int l, LAS unsigned char* lds, const Ctx cx) {
;     ...
;                 for (int q4 = 0; q4 < 4; ++q4) { const u32x2 uu = *(const u32x2*)(zu + ht * 32 + 8 * q4);
;                     const float o0 = gelu_tanh(bflo(uu.x)) * (acc[ht][4 * q4] + bsv), o1 = gelu_tanh(bfhi(uu.x)) * (acc[ht][4 * q4 + 1] + bsv);
;                     const float o2 = gelu_tanh(bflo(uu.y)) * (acc[ht][4 * q4 + 2] + bsv), o3 = gelu_tanh(bfhi(uu.y)) * (acc[ht][4 * q4 + 3] + bsv);
;                     u32x2 w; w.x = pk2(o0, o1); w.y = pk2(o2, o3); *(u32x2*)(yo + ht * 32 + 8 * q4) = w; }
	v_mov_b64_e32 v[48:49], v[200:201]
	v_lshlrev_b32_e32 v50, 16, v48
	v_mul_f32_e32 v65, 0x3d372713, v50
	v_mul_f32_e32 v65, v65, v50
	v_mov_b32_e32 v70, v50
	v_fmac_f32_e32 v70, v65, v70
	v_mul_f32_e32 v65, 0x3f4c422a, v70
	v_add_f32_e32 v65, v65, v65
	v_mul_f32_e32 v65, 0x3fb8aa3b, v65
	v_exp_f32_e32 v65, v65
	v_and_b32_e32 v48, 0xffff0000, v48
	v_mov_b32_e32 v71, v48
	v_lshlrev_b32_e32 v51, 16, v49
	v_add_f32_e32 v65, 1.0, v65
	v_rcp_f32_e32 v70, v65
	v_mul_f32_e32 v65, 0x3d372713, v48
	v_mul_f32_e32 v65, v65, v48
	v_fmac_f32_e32 v71, v65, v71
	v_mul_f32_e32 v65, 0x3f4c422a, v71
	v_add_f32_e32 v65, v65, v65
	v_mul_f32_e32 v65, 0x3fb8aa3b, v65
	v_exp_f32_e32 v65, v65
	v_mov_b32_e32 v71, v51
	v_and_b32_e32 v49, 0xffff0000, v49
	v_add_f32_e32 v65, 1.0, v65
	v_rcp_f32_e32 v72, v65
	v_mul_f32_e32 v65, 0x3d372713, v51
	v_mul_f32_e32 v65, v65, v51
	v_fmac_f32_e32 v71, v65, v71
	v_mul_f32_e32 v65, 0x3f4c422a, v71
	v_add_f32_e32 v65, v65, v65
	v_mul_f32_e32 v65, 0x3fb8aa3b, v65
	v_exp_f32_e32 v65, v65
	v_pk_mul_f32 v[50:51], v[50:51], 0.5 op_sel_hi:[1,0]
	v_add_f32_e32 v65, 1.0, v65
	v_rcp_f32_e32 v71, v65
	s_nop 0
	v_pk_fma_f32 v[70:71], v[70:71], 2.0, 1.0 op_sel_hi:[1,0,0] neg_lo:[1,0,0] neg_hi:[1,0,0]
	s_nop 0
	v_pk_add_f32 v[70:71], v[70:71], 1.0 op_sel_hi:[1,0]
	s_nop 0
	v_pk_mul_f32 v[50:51], v[50:51], v[70:71]
	v_mov_b32_e32 v70, v52
	v_mul_f32_e32 v52, 0x3d372713, v49
	v_mov_b32_e32 v71, v54
	v_mul_f32_e32 v52, v52, v49
	v_mov_b32_e32 v54, v49
	v_fmac_f32_e32 v54, v52, v54
	v_mul_f32_e32 v52, 0x3f4c422a, v54
	v_add_f32_e32 v52, v52, v52
	v_mul_f32_e32 v52, 0x3fb8aa3b, v52
	v_exp_f32_e32 v52, v52
	v_pk_add_f32 v[70:71], v[70:71], v[64:65] op_sel_hi:[1,0]
	v_pk_mul_f32 v[48:49], v[48:49], 0.5 op_sel_hi:[1,0]
	v_pk_mul_f32 v[50:51], v[70:71], v[50:51]
	v_add_f32_e32 v52, 1.0, v52
	v_rcp_f32_e32 v73, v52
	v_mov_b32_e32 v54, v53
	v_pk_add_f32 v[52:53], v[54:55], v[64:65] op_sel_hi:[1,0]
	v_pk_fma_f32 v[70:71], v[72:73], 2.0, 1.0 op_sel_hi:[1,0,0] neg_lo:[1,0,0] neg_hi:[1,0,0]
	s_nop 0
	v_pk_add_f32 v[70:71], v[70:71], 1.0 op_sel_hi:[1,0]
	s_nop 0
	v_pk_mul_f32 v[48:49], v[48:49], v[70:71]
	s_nop 0
	v_pk_mul_f32 v[48:49], v[52:53], v[48:49]
	v_and_b32_sdwa v52, v51, v196 dst_sel:DWORD dst_unused:UNUSED_PAD src0_sel:WORD_1 src1_sel:DWORD
	v_and_b32_sdwa v53, v50, v196 dst_sel:DWORD dst_unused:UNUSED_PAD src0_sel:WORD_1 src1_sel:DWORD
	v_add3_u32 v50, v50, v53, s45
	v_add3_u32 v51, v51, v52, s45
	v_and_b32_sdwa v52, v49, v196 dst_sel:DWORD dst_unused:UNUSED_PAD src0_sel:WORD_1 src1_sel:DWORD
	v_and_b32_sdwa v53, v48, v196 dst_sel:DWORD dst_unused:UNUSED_PAD src0_sel:WORD_1 src1_sel:DWORD
	v_add3_u32 v49, v49, v52, s45
	v_add3_u32 v48, v48, v53, s45
	v_and_b32_e32 v49, 0xffff0000, v49
	v_and_b32_e32 v48, 0xffff0000, v48
	v_or_b32_sdwa v49, v49, v51 dst_sel:DWORD dst_unused:UNUSED_PAD src0_sel:DWORD src1_sel:WORD_1
	v_or_b32_sdwa v48, v48, v50 dst_sel:DWORD dst_unused:UNUSED_PAD src0_sel:DWORD src1_sel:WORD_1
	global_store_dwordx2 v[66:67], v[48:49], off offset:16
	s_waitcnt vmcnt(15)
	v_mov_b64_e32 v[48:49], v[202:203]
	v_lshlrev_b32_e32 v50, 16, v48
	v_mul_f32_e32 v52, 0x3d372713, v50
	v_mul_f32_e32 v52, v52, v50
	v_mov_b32_e32 v53, v50
	v_fmac_f32_e32 v53, v52, v53
	v_and_b32_e32 v48, 0xffff0000, v48
	v_mul_f32_e32 v52, 0x3f4c422a, v53
	v_mul_f32_e32 v53, 0x3d372713, v48
	v_mul_f32_e32 v53, v53, v48
	v_mov_b32_e32 v54, v48
	v_fmac_f32_e32 v54, v53, v54
	v_mul_f32_e32 v53, 0x3f4c422a, v54
	v_add_f32_e32 v53, v53, v53
	v_mul_f32_e32 v53, 0x3fb8aa3b, v53
	v_exp_f32_e32 v53, v53
	v_lshlrev_b32_e32 v51, 16, v49
	v_mov_b32_e32 v55, v51
	v_add_f32_e32 v52, v52, v52
	v_add_f32_e32 v53, 1.0, v53
	v_rcp_f32_e32 v54, v53
	v_mul_f32_e32 v53, 0x3d372713, v51
	v_mul_f32_e32 v53, v53, v51
	v_fmac_f32_e32 v55, v53, v55
	v_mul_f32_e32 v53, 0x3f4c422a, v55
	v_add_f32_e32 v53, v53, v53
	v_mul_f32_e32 v52, 0x3fb8aa3b, v52
	v_mul_f32_e32 v53, 0x3fb8aa3b, v53
	v_exp_f32_e32 v52, v52
	v_exp_f32_e32 v53, v53
	v_pk_mul_f32 v[50:51], v[50:51], 0.5 op_sel_hi:[1,0]
	v_and_b32_e32 v49, 0xffff0000, v49
	v_add_f32_e32 v52, 1.0, v52
	v_add_f32_e32 v53, 1.0, v53
	v_rcp_f32_e32 v52, v52
	v_rcp_f32_e32 v53, v53
	s_nop 0
	v_pk_fma_f32 v[52:53], v[52:53], 2.0, 1.0 op_sel_hi:[1,0,0] neg_lo:[1,0,0] neg_hi:[1,0,0]
	s_nop 0
	v_pk_add_f32 v[52:53], v[52:53], 1.0 op_sel_hi:[1,0]
	s_nop 0
	v_pk_mul_f32 v[50:51], v[50:51], v[52:53]
	v_mov_b32_e32 v52, v56
	v_mov_b32_e32 v53, v58
	v_pk_add_f32 v[52:53], v[52:53], v[64:65] op_sel_hi:[1,0]
	v_mov_b32_e32 v58, v57
	v_pk_mul_f32 v[50:51], v[52:53], v[50:51]
	v_mul_f32_e32 v52, 0x3d372713, v49
	v_mul_f32_e32 v52, v52, v49
	v_mov_b32_e32 v53, v49
	v_fmac_f32_e32 v53, v52, v53
	v_mul_f32_e32 v52, 0x3f4c422a, v53
	v_add_f32_e32 v52, v52, v52
	v_mul_f32_e32 v52, 0x3fb8aa3b, v52
	v_exp_f32_e32 v52, v52
	v_pk_mul_f32 v[48:49], v[48:49], 0.5 op_sel_hi:[1,0]
	v_add_f32_e32 v52, 1.0, v52
	v_rcp_f32_e32 v55, v52
	s_nop 0
	v_pk_fma_f32 v[52:53], v[54:55], 2.0, 1.0 op_sel_hi:[1,0,0] neg_lo:[1,0,0] neg_hi:[1,0,0]
	s_nop 0
	v_pk_add_f32 v[52:53], v[52:53], 1.0 op_sel_hi:[1,0]
	s_nop 0
	v_pk_mul_f32 v[48:49], v[48:49], v[52:53]
	v_pk_add_f32 v[52:53], v[58:59], v[64:65] op_sel_hi:[1,0]
	s_nop 0
	v_pk_mul_f32 v[48:49], v[52:53], v[48:49]
	v_and_b32_sdwa v52, v51, v196 dst_sel:DWORD dst_unused:UNUSED_PAD src0_sel:WORD_1 src1_sel:DWORD
	v_and_b32_sdwa v53, v50, v196 dst_sel:DWORD dst_unused:UNUSED_PAD src0_sel:WORD_1 src1_sel:DWORD
	v_add3_u32 v50, v50, v53, s45
	v_add3_u32 v51, v51, v52, s45
	v_and_b32_sdwa v52, v49, v196 dst_sel:DWORD dst_unused:UNUSED_PAD src0_sel:WORD_1 src1_sel:DWORD
	v_and_b32_sdwa v53, v48, v196 dst_sel:DWORD dst_unused:UNUSED_PAD src0_sel:WORD_1 src1_sel:DWORD
	v_add3_u32 v49, v49, v52, s45
	v_add3_u32 v48, v48, v53, s45
	v_and_b32_e32 v49, 0xffff0000, v49
	v_and_b32_e32 v48, 0xffff0000, v48
	v_or_b32_sdwa v49, v49, v51 dst_sel:DWORD dst_unused:UNUSED_PAD src0_sel:DWORD src1_sel:WORD_1
	v_or_b32_sdwa v48, v48, v50 dst_sel:DWORD dst_unused:UNUSED_PAD src0_sel:DWORD src1_sel:WORD_1
	global_store_dwordx2 v[66:67], v[48:49], off offset:32
	s_waitcnt vmcnt(15)
; __device__ __forceinline__ unsigned pk2(float lo, float hi) { return f2bf(lo) | (f2bf(hi) << 16); }
; __device__ __forceinline__ void gmlp_fast(KArgs ap, int l, LAS unsigned char* lds, const Ctx cx) {
;     ...
;                 for (int q4 = 0; q4 < 4; ++q4) { const u32x2 uu = *(const u32x2*)(zu + ht * 32 + 8 * q4);
;                     const float o0 = gelu_tanh(bflo(uu.x)) * (acc[ht][4 * q4] + bsv), o1 = gelu_tanh(bfhi(uu.x)) * (acc[ht][4 * q4 + 1] + bsv);
;                     const float o2 = gelu_tanh(bflo(uu.y)) * (acc[ht][4 * q4 + 2] + bsv), o3 = gelu_tanh(bfhi(uu.y)) * (acc[ht][4 * q4 + 3] + bsv);
;                     u32x2 w; w.x = pk2(o0, o1); w.y = pk2(o2, o3); *(u32x2*)(yo + ht * 32 + 8 * q4) = w; }
	v_mov_b64_e32 v[48:49], v[204:205]
	v_lshlrev_b32_e32 v50, 16, v48
	v_mul_f32_e32 v52, 0x3d372713, v50
	v_mul_f32_e32 v52, v52, v50
	v_mov_b32_e32 v53, v50
	v_fmac_f32_e32 v53, v52, v53
	v_and_b32_e32 v48, 0xffff0000, v48
	v_mul_f32_e32 v52, 0x3f4c422a, v53
	v_mul_f32_e32 v53, 0x3d372713, v48
	v_mul_f32_e32 v53, v53, v48
	v_mov_b32_e32 v54, v48
	v_fmac_f32_e32 v54, v53, v54
	v_mul_f32_e32 v53, 0x3f4c422a, v54
	v_add_f32_e32 v53, v53, v53
	v_mul_f32_e32 v53, 0x3fb8aa3b, v53
	v_exp_f32_e32 v53, v53
	v_lshlrev_b32_e32 v51, 16, v49
	v_mov_b32_e32 v55, v51
	v_add_f32_e32 v52, v52, v52
	v_add_f32_e32 v53, 1.0, v53
	v_rcp_f32_e32 v54, v53
	v_mul_f32_e32 v53, 0x3d372713, v51
	v_mul_f32_e32 v53, v53, v51
	v_fmac_f32_e32 v55, v53, v55
	v_mul_f32_e32 v53, 0x3f4c422a, v55
	v_add_f32_e32 v53, v53, v53
	v_mul_f32_e32 v52, 0x3fb8aa3b, v52
	v_mul_f32_e32 v53, 0x3fb8aa3b, v53
	v_exp_f32_e32 v52, v52
	v_exp_f32_e32 v53, v53
	v_pk_mul_f32 v[50:51], v[50:51], 0.5 op_sel_hi:[1,0]
	v_and_b32_e32 v49, 0xffff0000, v49
	v_add_f32_e32 v52, 1.0, v52
	v_add_f32_e32 v53, 1.0, v53
	v_rcp_f32_e32 v52, v52
	v_rcp_f32_e32 v53, v53
	s_nop 0
	v_pk_fma_f32 v[52:53], v[52:53], 2.0, 1.0 op_sel_hi:[1,0,0] neg_lo:[1,0,0] neg_hi:[1,0,0]
	s_nop 0
	v_pk_add_f32 v[52:53], v[52:53], 1.0 op_sel_hi:[1,0]
	s_nop 0
	v_pk_mul_f32 v[50:51], v[50:51], v[52:53]
	v_mov_b32_e32 v52, v60
	v_mov_b32_e32 v53, v62
	v_pk_add_f32 v[52:53], v[52:53], v[64:65] op_sel_hi:[1,0]
	v_mov_b32_e32 v62, v61
	v_pk_mul_f32 v[50:51], v[52:53], v[50:51]
	v_mul_f32_e32 v52, 0x3d372713, v49
	v_mul_f32_e32 v52, v52, v49
	v_mov_b32_e32 v53, v49
	v_fmac_f32_e32 v53, v52, v53
	v_mul_f32_e32 v52, 0x3f4c422a, v53
	v_add_f32_e32 v52, v52, v52
	v_mul_f32_e32 v52, 0x3fb8aa3b, v52
	v_exp_f32_e32 v52, v52
	v_pk_mul_f32 v[48:49], v[48:49], 0.5 op_sel_hi:[1,0]
	v_add_f32_e32 v52, 1.0, v52
	v_rcp_f32_e32 v55, v52
	s_nop 0
	v_pk_fma_f32 v[52:53], v[54:55], 2.0, 1.0 op_sel_hi:[1,0,0] neg_lo:[1,0,0] neg_hi:[1,0,0]
	s_nop 0
	v_pk_add_f32 v[52:53], v[52:53], 1.0 op_sel_hi:[1,0]
	s_nop 0
	v_pk_mul_f32 v[48:49], v[48:49], v[52:53]
	v_pk_add_f32 v[52:53], v[62:63], v[64:65] op_sel_hi:[1,0]
	s_nop 0
	v_pk_mul_f32 v[48:49], v[52:53], v[48:49]
	v_and_b32_sdwa v52, v51, v196 dst_sel:DWORD dst_unused:UNUSED_PAD src0_sel:WORD_1 src1_sel:DWORD
	v_and_b32_sdwa v53, v50, v196 dst_sel:DWORD dst_unused:UNUSED_PAD src0_sel:WORD_1 src1_sel:DWORD
	v_add3_u32 v50, v50, v53, s45
	v_add3_u32 v51, v51, v52, s45
	v_and_b32_sdwa v52, v49, v196 dst_sel:DWORD dst_unused:UNUSED_PAD src0_sel:WORD_1 src1_sel:DWORD
	v_and_b32_sdwa v53, v48, v196 dst_sel:DWORD dst_unused:UNUSED_PAD src0_sel:WORD_1 src1_sel:DWORD
	v_add3_u32 v49, v49, v52, s45
	v_add3_u32 v48, v48, v53, s45
	v_and_b32_e32 v49, 0xffff0000, v49
	v_and_b32_e32 v48, 0xffff0000, v48
	v_or_b32_sdwa v49, v49, v51 dst_sel:DWORD dst_unused:UNUSED_PAD src0_sel:DWORD src1_sel:WORD_1
	v_or_b32_sdwa v48, v48, v50 dst_sel:DWORD dst_unused:UNUSED_PAD src0_sel:DWORD src1_sel:WORD_1
	global_store_dwordx2 v[66:67], v[48:49], off offset:48
	s_waitcnt vmcnt(15)
	v_mov_b64_e32 v[48:49], v[206:207]
	v_lshlrev_b32_e32 v50, 16, v48
	v_mul_f32_e32 v52, 0x3d372713, v50
	v_mul_f32_e32 v52, v52, v50
	v_mov_b32_e32 v53, v50
	v_fmac_f32_e32 v53, v52, v53
	v_and_b32_e32 v48, 0xffff0000, v48
	v_mul_f32_e32 v52, 0x3f4c422a, v53
	v_mul_f32_e32 v53, 0x3d372713, v48
	v_mul_f32_e32 v53, v53, v48
	v_mov_b32_e32 v54, v48
	v_fmac_f32_e32 v54, v53, v54
	v_mul_f32_e32 v53, 0x3f4c422a, v54
	v_add_f32_e32 v53, v53, v53
	v_mul_f32_e32 v53, 0x3fb8aa3b, v53
	v_exp_f32_e32 v53, v53
	v_lshlrev_b32_e32 v51, 16, v49
	v_mov_b32_e32 v55, v51
	v_add_f32_e32 v52, v52, v52
	v_add_f32_e32 v53, 1.0, v53
	v_rcp_f32_e32 v54, v53
	v_mul_f32_e32 v53, 0x3d372713, v51
	v_mul_f32_e32 v53, v53, v51
	v_fmac_f32_e32 v55, v53, v55
	v_mul_f32_e32 v53, 0x3f4c422a, v55
	v_add_f32_e32 v53, v53, v53
	v_mul_f32_e32 v52, 0x3fb8aa3b, v52
	v_mul_f32_e32 v53, 0x3fb8aa3b, v53
	v_exp_f32_e32 v52, v52
	v_exp_f32_e32 v53, v53
	v_and_b32_e32 v49, 0xffff0000, v49
	v_pk_mul_f32 v[50:51], v[50:51], 0.5 op_sel_hi:[1,0]
	v_add_f32_e32 v52, 1.0, v52
	v_add_f32_e32 v53, 1.0, v53
	v_rcp_f32_e32 v52, v52
	v_rcp_f32_e32 v53, v53
	s_nop 0
	v_pk_fma_f32 v[52:53], v[52:53], 2.0, 1.0 op_sel_hi:[1,0,0] neg_lo:[1,0,0] neg_hi:[1,0,0]
	s_nop 0
	v_pk_add_f32 v[52:53], v[52:53], 1.0 op_sel_hi:[1,0]
	s_nop 0
	v_pk_mul_f32 v[50:51], v[50:51], v[52:53]
	v_mov_b32_e32 v52, v32
	v_mul_f32_e32 v32, 0x3d372713, v49
	v_mov_b32_e32 v53, v34
	v_mul_f32_e32 v32, v32, v49
	v_mov_b32_e32 v34, v49
	v_fmac_f32_e32 v34, v32, v34
	v_mul_f32_e32 v32, 0x3f4c422a, v34
	v_add_f32_e32 v32, v32, v32
	v_mul_f32_e32 v32, 0x3fb8aa3b, v32
	v_exp_f32_e32 v32, v32
	v_pk_add_f32 v[52:53], v[52:53], v[64:65] op_sel_hi:[1,0]
	v_pk_mul_f32 v[48:49], v[48:49], 0.5 op_sel_hi:[1,0]
	v_pk_mul_f32 v[50:51], v[52:53], v[50:51]
	v_add_f32_e32 v32, 1.0, v32
	v_rcp_f32_e32 v55, v32
	v_mov_b32_e32 v34, v33
	v_pk_add_f32 v[32:33], v[34:35], v[64:65] op_sel_hi:[1,0]
	v_and_b32_sdwa v34, v51, v196 dst_sel:DWORD dst_unused:UNUSED_PAD src0_sel:WORD_1 src1_sel:DWORD
	v_pk_fma_f32 v[52:53], v[54:55], 2.0, 1.0 op_sel_hi:[1,0,0] neg_lo:[1,0,0] neg_hi:[1,0,0]
	v_and_b32_sdwa v35, v50, v196 dst_sel:DWORD dst_unused:UNUSED_PAD src0_sel:WORD_1 src1_sel:DWORD
	v_pk_add_f32 v[52:53], v[52:53], 1.0 op_sel_hi:[1,0]
	v_add3_u32 v35, v50, v35, s45
	v_pk_mul_f32 v[48:49], v[48:49], v[52:53]
	v_add3_u32 v34, v51, v34, s45
	v_pk_mul_f32 v[32:33], v[32:33], v[48:49]
	s_nop 0
	v_and_b32_sdwa v48, v33, v196 dst_sel:DWORD dst_unused:UNUSED_PAD src0_sel:WORD_1 src1_sel:DWORD
	v_and_b32_sdwa v49, v32, v196 dst_sel:DWORD dst_unused:UNUSED_PAD src0_sel:WORD_1 src1_sel:DWORD
	v_add3_u32 v33, v33, v48, s45
	v_add3_u32 v32, v32, v49, s45
	v_and_b32_e32 v33, 0xffff0000, v33
	v_and_b32_e32 v32, 0xffff0000, v32
	v_or_b32_sdwa v33, v33, v34 dst_sel:DWORD dst_unused:UNUSED_PAD src0_sel:DWORD src1_sel:WORD_1
	v_or_b32_sdwa v32, v32, v35 dst_sel:DWORD dst_unused:UNUSED_PAD src0_sel:DWORD src1_sel:WORD_1
	global_store_dwordx2 v[66:67], v[32:33], off offset:64
	s_waitcnt vmcnt(15)
; __device__ __forceinline__ unsigned pk2(float lo, float hi) { return f2bf(lo) | (f2bf(hi) << 16); }
; __device__ __forceinline__ void gmlp_fast(KArgs ap, int l, LAS unsigned char* lds, const Ctx cx) {
;     ...
;                 for (int q4 = 0; q4 < 4; ++q4) { const u32x2 uu = *(const u32x2*)(zu + ht * 32 + 8 * q4);
;                     const float o0 = gelu_tanh(bflo(uu.x)) * (acc[ht][4 * q4] + bsv), o1 = gelu_tanh(bfhi(uu.x)) * (acc[ht][4 * q4 + 1] + bsv);
;                     const float o2 = gelu_tanh(bflo(uu.y)) * (acc[ht][4 * q4 + 2] + bsv), o3 = gelu_tanh(bfhi(uu.y)) * (acc[ht][4 * q4 + 3] + bsv);
;                     u32x2 w; w.x = pk2(o0, o1); w.y = pk2(o2, o3); *(u32x2*)(yo + ht * 32 + 8 * q4) = w; }
	v_mov_b64_e32 v[32:33], v[208:209]
	v_lshlrev_b32_e32 v34, 16, v32
	v_mul_f32_e32 v48, 0x3d372713, v34
	v_mul_f32_e32 v48, v48, v34
	v_mov_b32_e32 v49, v34
	v_fmac_f32_e32 v49, v48, v49
	v_and_b32_e32 v32, 0xffff0000, v32
	v_mul_f32_e32 v48, 0x3f4c422a, v49
	v_mul_f32_e32 v49, 0x3d372713, v32
	v_mul_f32_e32 v49, v49, v32
	v_mov_b32_e32 v50, v32
	v_fmac_f32_e32 v50, v49, v50
	v_mul_f32_e32 v49, 0x3f4c422a, v50
	v_add_f32_e32 v49, v49, v49
	v_mul_f32_e32 v49, 0x3fb8aa3b, v49
	v_exp_f32_e32 v49, v49
	v_lshlrev_b32_e32 v35, 16, v33
	v_mov_b32_e32 v51, v35
	v_add_f32_e32 v48, v48, v48
	v_add_f32_e32 v49, 1.0, v49
	v_rcp_f32_e32 v50, v49
	v_mul_f32_e32 v49, 0x3d372713, v35
	v_mul_f32_e32 v49, v49, v35
	v_fmac_f32_e32 v51, v49, v51
	v_mul_f32_e32 v49, 0x3f4c422a, v51
	v_add_f32_e32 v49, v49, v49
	v_mul_f32_e32 v48, 0x3fb8aa3b, v48
	v_mul_f32_e32 v49, 0x3fb8aa3b, v49
	v_exp_f32_e32 v48, v48
	v_exp_f32_e32 v49, v49
	v_and_b32_e32 v33, 0xffff0000, v33
	v_pk_mul_f32 v[34:35], v[34:35], 0.5 op_sel_hi:[1,0]
	v_add_f32_e32 v48, 1.0, v48
	v_add_f32_e32 v49, 1.0, v49
	v_rcp_f32_e32 v48, v48
	v_rcp_f32_e32 v49, v49
	s_nop 0
	v_pk_fma_f32 v[48:49], v[48:49], 2.0, 1.0 op_sel_hi:[1,0,0] neg_lo:[1,0,0] neg_hi:[1,0,0]
	s_nop 0
	v_pk_add_f32 v[48:49], v[48:49], 1.0 op_sel_hi:[1,0]
	s_nop 0
	v_pk_mul_f32 v[34:35], v[34:35], v[48:49]
	v_mov_b32_e32 v48, v36
	v_mul_f32_e32 v36, 0x3d372713, v33
	v_mov_b32_e32 v49, v38
	v_mul_f32_e32 v36, v36, v33
	v_mov_b32_e32 v38, v33
	v_fmac_f32_e32 v38, v36, v38
	v_mul_f32_e32 v36, 0x3f4c422a, v38
	v_add_f32_e32 v36, v36, v36
	v_mul_f32_e32 v36, 0x3fb8aa3b, v36
	v_exp_f32_e32 v36, v36
	v_pk_add_f32 v[48:49], v[48:49], v[64:65] op_sel_hi:[1,0]
	v_pk_mul_f32 v[32:33], v[32:33], 0.5 op_sel_hi:[1,0]
	v_pk_mul_f32 v[34:35], v[48:49], v[34:35]
	v_add_f32_e32 v36, 1.0, v36
	v_rcp_f32_e32 v51, v36
	v_mov_b32_e32 v38, v37
	v_pk_add_f32 v[36:37], v[38:39], v[64:65] op_sel_hi:[1,0]
	v_pk_fma_f32 v[48:49], v[50:51], 2.0, 1.0 op_sel_hi:[1,0,0] neg_lo:[1,0,0] neg_hi:[1,0,0]
	s_nop 0
	v_pk_add_f32 v[48:49], v[48:49], 1.0 op_sel_hi:[1,0]
	s_nop 0
	v_pk_mul_f32 v[32:33], v[32:33], v[48:49]
	s_nop 0
	v_pk_mul_f32 v[32:33], v[36:37], v[32:33]
	v_and_b32_sdwa v36, v35, v196 dst_sel:DWORD dst_unused:UNUSED_PAD src0_sel:WORD_1 src1_sel:DWORD
	v_and_b32_sdwa v37, v34, v196 dst_sel:DWORD dst_unused:UNUSED_PAD src0_sel:WORD_1 src1_sel:DWORD
	v_add3_u32 v34, v34, v37, s45
	v_add3_u32 v35, v35, v36, s45
	v_and_b32_sdwa v36, v33, v196 dst_sel:DWORD dst_unused:UNUSED_PAD src0_sel:WORD_1 src1_sel:DWORD
	v_and_b32_sdwa v37, v32, v196 dst_sel:DWORD dst_unused:UNUSED_PAD src0_sel:WORD_1 src1_sel:DWORD
	v_add3_u32 v33, v33, v36, s45
	v_add3_u32 v32, v32, v37, s45
	v_and_b32_e32 v33, 0xffff0000, v33
	v_and_b32_e32 v32, 0xffff0000, v32
	v_or_b32_sdwa v33, v33, v35 dst_sel:DWORD dst_unused:UNUSED_PAD src0_sel:DWORD src1_sel:WORD_1
	v_or_b32_sdwa v32, v32, v34 dst_sel:DWORD dst_unused:UNUSED_PAD src0_sel:DWORD src1_sel:WORD_1
	global_store_dwordx2 v[66:67], v[32:33], off offset:80
	s_waitcnt vmcnt(15)
	v_mov_b64_e32 v[32:33], v[210:211]
	v_lshlrev_b32_e32 v34, 16, v32
	v_mul_f32_e32 v36, 0x3d372713, v34
	v_mul_f32_e32 v36, v36, v34
	v_mov_b32_e32 v37, v34
	v_fmac_f32_e32 v37, v36, v37
	v_and_b32_e32 v32, 0xffff0000, v32
	v_mul_f32_e32 v36, 0x3f4c422a, v37
	v_mul_f32_e32 v37, 0x3d372713, v32
	v_mul_f32_e32 v37, v37, v32
	v_mov_b32_e32 v38, v32
	v_fmac_f32_e32 v38, v37, v38
	v_mul_f32_e32 v37, 0x3f4c422a, v38
	v_add_f32_e32 v37, v37, v37
	v_mul_f32_e32 v37, 0x3fb8aa3b, v37
	v_exp_f32_e32 v37, v37
	v_lshlrev_b32_e32 v35, 16, v33
	v_mov_b32_e32 v39, v35
	v_add_f32_e32 v36, v36, v36
	v_add_f32_e32 v37, 1.0, v37
	v_rcp_f32_e32 v38, v37
	v_mul_f32_e32 v37, 0x3d372713, v35
	v_mul_f32_e32 v37, v37, v35
	v_fmac_f32_e32 v39, v37, v39
	v_mul_f32_e32 v37, 0x3f4c422a, v39
	v_add_f32_e32 v37, v37, v37
	v_mul_f32_e32 v36, 0x3fb8aa3b, v36
	v_mul_f32_e32 v37, 0x3fb8aa3b, v37
	v_exp_f32_e32 v36, v36
	v_exp_f32_e32 v37, v37
	v_pk_mul_f32 v[34:35], v[34:35], 0.5 op_sel_hi:[1,0]
	v_and_b32_e32 v33, 0xffff0000, v33
	v_add_f32_e32 v36, 1.0, v36
	v_add_f32_e32 v37, 1.0, v37
	v_rcp_f32_e32 v36, v36
	v_rcp_f32_e32 v37, v37
	s_nop 0
	v_pk_fma_f32 v[36:37], v[36:37], 2.0, 1.0 op_sel_hi:[1,0,0] neg_lo:[1,0,0] neg_hi:[1,0,0]
	s_nop 0
	v_pk_add_f32 v[36:37], v[36:37], 1.0 op_sel_hi:[1,0]
	s_nop 0
	v_pk_mul_f32 v[34:35], v[34:35], v[36:37]
	v_mov_b32_e32 v36, v40
	v_mov_b32_e32 v37, v42
	v_pk_add_f32 v[36:37], v[36:37], v[64:65] op_sel_hi:[1,0]
	v_mov_b32_e32 v42, v41
	v_pk_mul_f32 v[34:35], v[36:37], v[34:35]
	v_mul_f32_e32 v36, 0x3d372713, v33
	v_mul_f32_e32 v36, v36, v33
	v_mov_b32_e32 v37, v33
	v_fmac_f32_e32 v37, v36, v37
	v_mul_f32_e32 v36, 0x3f4c422a, v37
	v_add_f32_e32 v36, v36, v36
	v_mul_f32_e32 v36, 0x3fb8aa3b, v36
	v_exp_f32_e32 v36, v36
	v_pk_mul_f32 v[32:33], v[32:33], 0.5 op_sel_hi:[1,0]
	v_add_f32_e32 v36, 1.0, v36
	v_rcp_f32_e32 v39, v36
	s_nop 0
	v_pk_fma_f32 v[36:37], v[38:39], 2.0, 1.0 op_sel_hi:[1,0,0] neg_lo:[1,0,0] neg_hi:[1,0,0]
	s_nop 0
	v_pk_add_f32 v[36:37], v[36:37], 1.0 op_sel_hi:[1,0]
	s_nop 0
	v_pk_mul_f32 v[32:33], v[32:33], v[36:37]
	v_pk_add_f32 v[36:37], v[42:43], v[64:65] op_sel_hi:[1,0]
	s_nop 0
	v_pk_mul_f32 v[32:33], v[36:37], v[32:33]
	v_and_b32_sdwa v36, v35, v196 dst_sel:DWORD dst_unused:UNUSED_PAD src0_sel:WORD_1 src1_sel:DWORD
	v_and_b32_sdwa v37, v34, v196 dst_sel:DWORD dst_unused:UNUSED_PAD src0_sel:WORD_1 src1_sel:DWORD
	v_add3_u32 v34, v34, v37, s45
	v_add3_u32 v35, v35, v36, s45
	v_and_b32_sdwa v36, v33, v196 dst_sel:DWORD dst_unused:UNUSED_PAD src0_sel:WORD_1 src1_sel:DWORD
	v_and_b32_sdwa v37, v32, v196 dst_sel:DWORD dst_unused:UNUSED_PAD src0_sel:WORD_1 src1_sel:DWORD
	v_add3_u32 v33, v33, v36, s45
	v_add3_u32 v32, v32, v37, s45
	v_and_b32_e32 v33, 0xffff0000, v33
	v_and_b32_e32 v32, 0xffff0000, v32
	v_or_b32_sdwa v33, v33, v35 dst_sel:DWORD dst_unused:UNUSED_PAD src0_sel:DWORD src1_sel:WORD_1
	v_or_b32_sdwa v32, v32, v34 dst_sel:DWORD dst_unused:UNUSED_PAD src0_sel:DWORD src1_sel:WORD_1
	global_store_dwordx2 v[66:67], v[32:33], off offset:96
	s_waitcnt vmcnt(15)
; __device__ __forceinline__ unsigned pk2(float lo, float hi) { return f2bf(lo) | (f2bf(hi) << 16); }
; __device__ __forceinline__ void gmlp_fast(KArgs ap, int l, LAS unsigned char* lds, const Ctx cx) {
;     ...
;                 for (int q4 = 0; q4 < 4; ++q4) { const u32x2 uu = *(const u32x2*)(zu + ht * 32 + 8 * q4);
;                     const float o0 = gelu_tanh(bflo(uu.x)) * (acc[ht][4 * q4] + bsv), o1 = gelu_tanh(bfhi(uu.x)) * (acc[ht][4 * q4 + 1] + bsv);
;                     const float o2 = gelu_tanh(bflo(uu.y)) * (acc[ht][4 * q4 + 2] + bsv), o3 = gelu_tanh(bfhi(uu.y)) * (acc[ht][4 * q4 + 3] + bsv);
;                     u32x2 w; w.x = pk2(o0, o1); w.y = pk2(o2, o3); *(u32x2*)(yo + ht * 32 + 8 * q4) = w; }
	v_mov_b64_e32 v[32:33], v[212:213]
	v_lshlrev_b32_e32 v34, 16, v32
	v_mul_f32_e32 v36, 0x3d372713, v34
	v_mul_f32_e32 v36, v36, v34
	v_mov_b32_e32 v37, v34
	v_fmac_f32_e32 v37, v36, v37
	v_and_b32_e32 v32, 0xffff0000, v32
	v_mul_f32_e32 v36, 0x3f4c422a, v37
	v_mul_f32_e32 v37, 0x3d372713, v32
	v_mul_f32_e32 v37, v37, v32
	v_mov_b32_e32 v38, v32
	v_fmac_f32_e32 v38, v37, v38
	v_mul_f32_e32 v37, 0x3f4c422a, v38
	v_add_f32_e32 v37, v37, v37
	v_mul_f32_e32 v37, 0x3fb8aa3b, v37
	v_exp_f32_e32 v37, v37
	v_lshlrev_b32_e32 v35, 16, v33
	v_mov_b32_e32 v39, v35
	v_add_f32_e32 v36, v36, v36
	v_add_f32_e32 v37, 1.0, v37
	v_rcp_f32_e32 v38, v37
	v_mul_f32_e32 v37, 0x3d372713, v35
	v_mul_f32_e32 v37, v37, v35
	v_fmac_f32_e32 v39, v37, v39
	v_mul_f32_e32 v37, 0x3f4c422a, v39
	v_add_f32_e32 v37, v37, v37
	v_mul_f32_e32 v36, 0x3fb8aa3b, v36
	v_mul_f32_e32 v37, 0x3fb8aa3b, v37
	v_exp_f32_e32 v36, v36
	v_exp_f32_e32 v37, v37
	v_pk_mul_f32 v[34:35], v[34:35], 0.5 op_sel_hi:[1,0]
	v_and_b32_e32 v33, 0xffff0000, v33
	v_add_f32_e32 v36, 1.0, v36
	v_add_f32_e32 v37, 1.0, v37
	v_rcp_f32_e32 v36, v36
	v_rcp_f32_e32 v37, v37
	s_nop 0
	v_pk_fma_f32 v[36:37], v[36:37], 2.0, 1.0 op_sel_hi:[1,0,0] neg_lo:[1,0,0] neg_hi:[1,0,0]
	s_nop 0
	v_pk_add_f32 v[36:37], v[36:37], 1.0 op_sel_hi:[1,0]
	s_nop 0
	v_pk_mul_f32 v[34:35], v[34:35], v[36:37]
	v_mov_b32_e32 v36, v44
	v_mov_b32_e32 v37, v46
	v_pk_add_f32 v[36:37], v[36:37], v[64:65] op_sel_hi:[1,0]
	v_mov_b32_e32 v46, v45
	v_pk_mul_f32 v[34:35], v[36:37], v[34:35]
	v_mul_f32_e32 v36, 0x3d372713, v33
	v_mul_f32_e32 v36, v36, v33
	v_mov_b32_e32 v37, v33
	v_fmac_f32_e32 v37, v36, v37
	v_mul_f32_e32 v36, 0x3f4c422a, v37
	v_add_f32_e32 v36, v36, v36
	v_mul_f32_e32 v36, 0x3fb8aa3b, v36
	v_exp_f32_e32 v36, v36
	v_pk_mul_f32 v[32:33], v[32:33], 0.5 op_sel_hi:[1,0]
	v_add_f32_e32 v36, 1.0, v36
	v_rcp_f32_e32 v39, v36
	s_nop 0
	v_pk_fma_f32 v[36:37], v[38:39], 2.0, 1.0 op_sel_hi:[1,0,0] neg_lo:[1,0,0] neg_hi:[1,0,0]
	s_nop 0
	v_pk_add_f32 v[36:37], v[36:37], 1.0 op_sel_hi:[1,0]
	s_nop 0
	v_pk_mul_f32 v[32:33], v[32:33], v[36:37]
	v_pk_add_f32 v[36:37], v[46:47], v[64:65] op_sel_hi:[1,0]
	s_nop 0
	v_pk_mul_f32 v[32:33], v[36:37], v[32:33]
	v_and_b32_sdwa v36, v35, v196 dst_sel:DWORD dst_unused:UNUSED_PAD src0_sel:WORD_1 src1_sel:DWORD
	v_and_b32_sdwa v37, v34, v196 dst_sel:DWORD dst_unused:UNUSED_PAD src0_sel:WORD_1 src1_sel:DWORD
	v_add3_u32 v34, v34, v37, s45
	v_add3_u32 v35, v35, v36, s45
	v_and_b32_sdwa v36, v33, v196 dst_sel:DWORD dst_unused:UNUSED_PAD src0_sel:WORD_1 src1_sel:DWORD
	v_and_b32_sdwa v37, v32, v196 dst_sel:DWORD dst_unused:UNUSED_PAD src0_sel:WORD_1 src1_sel:DWORD
	v_add3_u32 v33, v33, v36, s45
	v_add3_u32 v32, v32, v37, s45
	v_and_b32_e32 v33, 0xffff0000, v33
	v_and_b32_e32 v32, 0xffff0000, v32
	v_or_b32_sdwa v33, v33, v35 dst_sel:DWORD dst_unused:UNUSED_PAD src0_sel:DWORD src1_sel:WORD_1
	v_or_b32_sdwa v32, v32, v34 dst_sel:DWORD dst_unused:UNUSED_PAD src0_sel:DWORD src1_sel:WORD_1
	global_store_dwordx2 v[66:67], v[32:33], off offset:112
	s_waitcnt vmcnt(15)
	v_mov_b64_e32 v[32:33], v[214:215]
	v_lshlrev_b32_e32 v34, 16, v32
	v_mul_f32_e32 v36, 0x3d372713, v34
	v_mul_f32_e32 v36, v36, v34
	v_mov_b32_e32 v37, v34
	v_fmac_f32_e32 v37, v36, v37
	v_and_b32_e32 v32, 0xffff0000, v32
	v_mul_f32_e32 v36, 0x3f4c422a, v37
	v_mul_f32_e32 v37, 0x3d372713, v32
	v_mul_f32_e32 v37, v37, v32
	v_mov_b32_e32 v38, v32
	v_fmac_f32_e32 v38, v37, v38
	v_mul_f32_e32 v37, 0x3f4c422a, v38
	v_add_f32_e32 v37, v37, v37
	v_mul_f32_e32 v37, 0x3fb8aa3b, v37
	v_exp_f32_e32 v37, v37
	v_lshlrev_b32_e32 v35, 16, v33
	v_mov_b32_e32 v39, v35
	v_add_f32_e32 v36, v36, v36
	v_add_f32_e32 v37, 1.0, v37
	v_rcp_f32_e32 v38, v37
	v_mul_f32_e32 v37, 0x3d372713, v35
	v_mul_f32_e32 v37, v37, v35
	v_fmac_f32_e32 v39, v37, v39
	v_mul_f32_e32 v37, 0x3f4c422a, v39
	v_add_f32_e32 v37, v37, v37
	v_mul_f32_e32 v36, 0x3fb8aa3b, v36
	v_mul_f32_e32 v37, 0x3fb8aa3b, v37
	v_exp_f32_e32 v36, v36
	v_exp_f32_e32 v37, v37
	v_and_b32_e32 v33, 0xffff0000, v33
	v_pk_mul_f32 v[34:35], v[34:35], 0.5 op_sel_hi:[1,0]
	v_add_f32_e32 v36, 1.0, v36
	v_add_f32_e32 v37, 1.0, v37
	v_rcp_f32_e32 v36, v36
	v_rcp_f32_e32 v37, v37
	s_nop 0
	v_pk_fma_f32 v[36:37], v[36:37], 2.0, 1.0 op_sel_hi:[1,0,0] neg_lo:[1,0,0] neg_hi:[1,0,0]
	s_nop 0
	v_pk_add_f32 v[36:37], v[36:37], 1.0 op_sel_hi:[1,0]
	s_nop 0
	v_pk_mul_f32 v[34:35], v[34:35], v[36:37]
	v_mov_b32_e32 v36, v16
	v_mul_f32_e32 v16, 0x3d372713, v33
	v_mov_b32_e32 v37, v18
	v_mul_f32_e32 v16, v16, v33
	v_mov_b32_e32 v18, v33
	v_fmac_f32_e32 v18, v16, v18
	v_mul_f32_e32 v16, 0x3f4c422a, v18
	v_add_f32_e32 v16, v16, v16
	v_mul_f32_e32 v16, 0x3fb8aa3b, v16
	v_exp_f32_e32 v16, v16
	v_pk_add_f32 v[36:37], v[36:37], v[64:65] op_sel_hi:[1,0]
	v_pk_mul_f32 v[32:33], v[32:33], 0.5 op_sel_hi:[1,0]
	v_pk_mul_f32 v[34:35], v[36:37], v[34:35]
	v_add_f32_e32 v16, 1.0, v16
	v_rcp_f32_e32 v39, v16
	v_mov_b32_e32 v18, v17
	v_pk_add_f32 v[16:17], v[18:19], v[64:65] op_sel_hi:[1,0]
	v_and_b32_sdwa v18, v35, v196 dst_sel:DWORD dst_unused:UNUSED_PAD src0_sel:WORD_1 src1_sel:DWORD
	v_pk_fma_f32 v[36:37], v[38:39], 2.0, 1.0 op_sel_hi:[1,0,0] neg_lo:[1,0,0] neg_hi:[1,0,0]
	v_and_b32_sdwa v19, v34, v196 dst_sel:DWORD dst_unused:UNUSED_PAD src0_sel:WORD_1 src1_sel:DWORD
	v_pk_add_f32 v[36:37], v[36:37], 1.0 op_sel_hi:[1,0]
	v_add3_u32 v19, v34, v19, s45
	v_pk_mul_f32 v[32:33], v[32:33], v[36:37]
	v_add3_u32 v18, v35, v18, s45
	v_pk_mul_f32 v[16:17], v[16:17], v[32:33]
	s_nop 0
	v_and_b32_sdwa v32, v17, v196 dst_sel:DWORD dst_unused:UNUSED_PAD src0_sel:WORD_1 src1_sel:DWORD
	v_and_b32_sdwa v33, v16, v196 dst_sel:DWORD dst_unused:UNUSED_PAD src0_sel:WORD_1 src1_sel:DWORD
	v_add3_u32 v17, v17, v32, s45
	v_add3_u32 v16, v16, v33, s45
	v_and_b32_e32 v17, 0xffff0000, v17
	v_and_b32_e32 v16, 0xffff0000, v16
	v_or_b32_sdwa v17, v17, v18 dst_sel:DWORD dst_unused:UNUSED_PAD src0_sel:DWORD src1_sel:WORD_1
	v_or_b32_sdwa v16, v16, v19 dst_sel:DWORD dst_unused:UNUSED_PAD src0_sel:DWORD src1_sel:WORD_1
	global_store_dwordx2 v[66:67], v[16:17], off offset:128
	s_waitcnt vmcnt(15)
; __device__ __forceinline__ unsigned pk2(float lo, float hi) { return f2bf(lo) | (f2bf(hi) << 16); }
; __device__ __forceinline__ void gmlp_fast(KArgs ap, int l, LAS unsigned char* lds, const Ctx cx) {
;     ...
;                 for (int q4 = 0; q4 < 4; ++q4) { const u32x2 uu = *(const u32x2*)(zu + ht * 32 + 8 * q4);
;                     const float o0 = gelu_tanh(bflo(uu.x)) * (acc[ht][4 * q4] + bsv), o1 = gelu_tanh(bfhi(uu.x)) * (acc[ht][4 * q4 + 1] + bsv);
;                     const float o2 = gelu_tanh(bflo(uu.y)) * (acc[ht][4 * q4 + 2] + bsv), o3 = gelu_tanh(bfhi(uu.y)) * (acc[ht][4 * q4 + 3] + bsv);
;                     u32x2 w; w.x = pk2(o0, o1); w.y = pk2(o2, o3); *(u32x2*)(yo + ht * 32 + 8 * q4) = w; }
	v_mov_b64_e32 v[16:17], v[216:217]
	v_lshlrev_b32_e32 v18, 16, v16
	v_mul_f32_e32 v32, 0x3d372713, v18
	v_mul_f32_e32 v32, v32, v18
	v_mov_b32_e32 v33, v18
	v_fmac_f32_e32 v33, v32, v33
	v_and_b32_e32 v16, 0xffff0000, v16
	v_mul_f32_e32 v32, 0x3f4c422a, v33
	v_mul_f32_e32 v33, 0x3d372713, v16
	v_mul_f32_e32 v33, v33, v16
	v_mov_b32_e32 v34, v16
	v_fmac_f32_e32 v34, v33, v34
	v_mul_f32_e32 v33, 0x3f4c422a, v34
	v_add_f32_e32 v33, v33, v33
	v_mul_f32_e32 v33, 0x3fb8aa3b, v33
	v_exp_f32_e32 v33, v33
	v_lshlrev_b32_e32 v19, 16, v17
	v_mov_b32_e32 v35, v19
	v_add_f32_e32 v32, v32, v32
	v_add_f32_e32 v33, 1.0, v33
	v_rcp_f32_e32 v34, v33
	v_mul_f32_e32 v33, 0x3d372713, v19
	v_mul_f32_e32 v33, v33, v19
	v_fmac_f32_e32 v35, v33, v35
	v_mul_f32_e32 v33, 0x3f4c422a, v35
	v_add_f32_e32 v33, v33, v33
	v_mul_f32_e32 v32, 0x3fb8aa3b, v32
	v_mul_f32_e32 v33, 0x3fb8aa3b, v33
	v_exp_f32_e32 v32, v32
	v_exp_f32_e32 v33, v33
	v_and_b32_e32 v17, 0xffff0000, v17
	v_pk_mul_f32 v[18:19], v[18:19], 0.5 op_sel_hi:[1,0]
	v_add_f32_e32 v32, 1.0, v32
	v_add_f32_e32 v33, 1.0, v33
	v_rcp_f32_e32 v32, v32
	v_rcp_f32_e32 v33, v33
	s_nop 0
	v_pk_fma_f32 v[32:33], v[32:33], 2.0, 1.0 op_sel_hi:[1,0,0] neg_lo:[1,0,0] neg_hi:[1,0,0]
	s_nop 0
	v_pk_add_f32 v[32:33], v[32:33], 1.0 op_sel_hi:[1,0]
	s_nop 0
	v_pk_mul_f32 v[18:19], v[18:19], v[32:33]
	v_mov_b32_e32 v32, v20
	v_mul_f32_e32 v20, 0x3d372713, v17
	v_mov_b32_e32 v33, v22
	v_mul_f32_e32 v20, v20, v17
	v_mov_b32_e32 v22, v17
	v_fmac_f32_e32 v22, v20, v22
	v_mul_f32_e32 v20, 0x3f4c422a, v22
	v_add_f32_e32 v20, v20, v20
	v_mul_f32_e32 v20, 0x3fb8aa3b, v20
	v_exp_f32_e32 v20, v20
	v_pk_add_f32 v[32:33], v[32:33], v[64:65] op_sel_hi:[1,0]
	v_pk_mul_f32 v[16:17], v[16:17], 0.5 op_sel_hi:[1,0]
	v_pk_mul_f32 v[18:19], v[32:33], v[18:19]
	v_add_f32_e32 v20, 1.0, v20
	v_rcp_f32_e32 v35, v20
	v_mov_b32_e32 v22, v21
	v_pk_add_f32 v[20:21], v[22:23], v[64:65] op_sel_hi:[1,0]
	v_pk_fma_f32 v[32:33], v[34:35], 2.0, 1.0 op_sel_hi:[1,0,0] neg_lo:[1,0,0] neg_hi:[1,0,0]
	s_nop 0
	v_pk_add_f32 v[32:33], v[32:33], 1.0 op_sel_hi:[1,0]
	s_nop 0
	v_pk_mul_f32 v[16:17], v[16:17], v[32:33]
	s_nop 0
	v_pk_mul_f32 v[16:17], v[20:21], v[16:17]
	v_and_b32_sdwa v20, v19, v196 dst_sel:DWORD dst_unused:UNUSED_PAD src0_sel:WORD_1 src1_sel:DWORD
	v_and_b32_sdwa v21, v18, v196 dst_sel:DWORD dst_unused:UNUSED_PAD src0_sel:WORD_1 src1_sel:DWORD
	v_add3_u32 v18, v18, v21, s45
	v_add3_u32 v19, v19, v20, s45
	v_and_b32_sdwa v20, v17, v196 dst_sel:DWORD dst_unused:UNUSED_PAD src0_sel:WORD_1 src1_sel:DWORD
	v_and_b32_sdwa v21, v16, v196 dst_sel:DWORD dst_unused:UNUSED_PAD src0_sel:WORD_1 src1_sel:DWORD
	v_add3_u32 v17, v17, v20, s45
	v_add3_u32 v16, v16, v21, s45
	v_and_b32_e32 v17, 0xffff0000, v17
	v_and_b32_e32 v16, 0xffff0000, v16
	v_or_b32_sdwa v17, v17, v19 dst_sel:DWORD dst_unused:UNUSED_PAD src0_sel:DWORD src1_sel:WORD_1
	v_or_b32_sdwa v16, v16, v18 dst_sel:DWORD dst_unused:UNUSED_PAD src0_sel:DWORD src1_sel:WORD_1
	global_store_dwordx2 v[66:67], v[16:17], off offset:144
	s_waitcnt vmcnt(15)
	v_mov_b64_e32 v[16:17], v[218:219]
	v_lshlrev_b32_e32 v18, 16, v16
	v_mul_f32_e32 v20, 0x3d372713, v18
	v_mul_f32_e32 v20, v20, v18
	v_mov_b32_e32 v21, v18
	v_fmac_f32_e32 v21, v20, v21
	v_and_b32_e32 v16, 0xffff0000, v16
	v_mul_f32_e32 v20, 0x3f4c422a, v21
	v_mul_f32_e32 v21, 0x3d372713, v16
	v_mul_f32_e32 v21, v21, v16
	v_mov_b32_e32 v22, v16
	v_fmac_f32_e32 v22, v21, v22
	v_mul_f32_e32 v21, 0x3f4c422a, v22
	v_add_f32_e32 v21, v21, v21
	v_mul_f32_e32 v21, 0x3fb8aa3b, v21
	v_exp_f32_e32 v21, v21
	v_lshlrev_b32_e32 v19, 16, v17
	v_mov_b32_e32 v23, v19
	v_add_f32_e32 v20, v20, v20
	v_add_f32_e32 v21, 1.0, v21
	v_rcp_f32_e32 v22, v21
	v_mul_f32_e32 v21, 0x3d372713, v19
	v_mul_f32_e32 v21, v21, v19
	v_fmac_f32_e32 v23, v21, v23
	v_mul_f32_e32 v21, 0x3f4c422a, v23
	v_add_f32_e32 v21, v21, v21
	v_mul_f32_e32 v20, 0x3fb8aa3b, v20
	v_mul_f32_e32 v21, 0x3fb8aa3b, v21
	v_exp_f32_e32 v20, v20
	v_exp_f32_e32 v21, v21
	v_pk_mul_f32 v[18:19], v[18:19], 0.5 op_sel_hi:[1,0]
	v_and_b32_e32 v17, 0xffff0000, v17
	v_add_f32_e32 v20, 1.0, v20
	v_add_f32_e32 v21, 1.0, v21
	v_rcp_f32_e32 v20, v20
	v_rcp_f32_e32 v21, v21
	s_nop 0
	v_pk_fma_f32 v[20:21], v[20:21], 2.0, 1.0 op_sel_hi:[1,0,0] neg_lo:[1,0,0] neg_hi:[1,0,0]
	s_nop 0
	v_pk_add_f32 v[20:21], v[20:21], 1.0 op_sel_hi:[1,0]
	s_nop 0
	v_pk_mul_f32 v[18:19], v[18:19], v[20:21]
	v_mov_b32_e32 v20, v24
	v_mov_b32_e32 v21, v26
	v_pk_add_f32 v[20:21], v[20:21], v[64:65] op_sel_hi:[1,0]
	v_mov_b32_e32 v26, v25
	v_pk_mul_f32 v[18:19], v[20:21], v[18:19]
	v_mul_f32_e32 v20, 0x3d372713, v17
	v_mul_f32_e32 v20, v20, v17
	v_mov_b32_e32 v21, v17
	v_fmac_f32_e32 v21, v20, v21
	v_mul_f32_e32 v20, 0x3f4c422a, v21
	v_add_f32_e32 v20, v20, v20
	v_mul_f32_e32 v20, 0x3fb8aa3b, v20
	v_exp_f32_e32 v20, v20
	v_pk_mul_f32 v[16:17], v[16:17], 0.5 op_sel_hi:[1,0]
	v_add_f32_e32 v20, 1.0, v20
	v_rcp_f32_e32 v23, v20
	s_nop 0
	v_pk_fma_f32 v[20:21], v[22:23], 2.0, 1.0 op_sel_hi:[1,0,0] neg_lo:[1,0,0] neg_hi:[1,0,0]
	s_nop 0
	v_pk_add_f32 v[20:21], v[20:21], 1.0 op_sel_hi:[1,0]
	s_nop 0
	v_pk_mul_f32 v[16:17], v[16:17], v[20:21]
	v_pk_add_f32 v[20:21], v[26:27], v[64:65] op_sel_hi:[1,0]
	s_nop 0
	v_pk_mul_f32 v[16:17], v[20:21], v[16:17]
	v_and_b32_sdwa v20, v19, v196 dst_sel:DWORD dst_unused:UNUSED_PAD src0_sel:WORD_1 src1_sel:DWORD
	v_and_b32_sdwa v21, v18, v196 dst_sel:DWORD dst_unused:UNUSED_PAD src0_sel:WORD_1 src1_sel:DWORD
	v_add3_u32 v18, v18, v21, s45
	v_add3_u32 v19, v19, v20, s45
	v_and_b32_sdwa v20, v17, v196 dst_sel:DWORD dst_unused:UNUSED_PAD src0_sel:WORD_1 src1_sel:DWORD
	v_and_b32_sdwa v21, v16, v196 dst_sel:DWORD dst_unused:UNUSED_PAD src0_sel:WORD_1 src1_sel:DWORD
	v_add3_u32 v17, v17, v20, s45
	v_add3_u32 v16, v16, v21, s45
	v_and_b32_e32 v17, 0xffff0000, v17
	v_and_b32_e32 v16, 0xffff0000, v16
	v_or_b32_sdwa v17, v17, v19 dst_sel:DWORD dst_unused:UNUSED_PAD src0_sel:DWORD src1_sel:WORD_1
	v_or_b32_sdwa v16, v16, v18 dst_sel:DWORD dst_unused:UNUSED_PAD src0_sel:DWORD src1_sel:WORD_1
	global_store_dwordx2 v[66:67], v[16:17], off offset:160
	s_waitcnt vmcnt(15)
; __device__ __forceinline__ unsigned pk2(float lo, float hi) { return f2bf(lo) | (f2bf(hi) << 16); }
; __device__ __forceinline__ void gmlp_fast(KArgs ap, int l, LAS unsigned char* lds, const Ctx cx) {
;     ...
;                 for (int q4 = 0; q4 < 4; ++q4) { const u32x2 uu = *(const u32x2*)(zu + ht * 32 + 8 * q4);
;                     const float o0 = gelu_tanh(bflo(uu.x)) * (acc[ht][4 * q4] + bsv), o1 = gelu_tanh(bfhi(uu.x)) * (acc[ht][4 * q4 + 1] + bsv);
;                     const float o2 = gelu_tanh(bflo(uu.y)) * (acc[ht][4 * q4 + 2] + bsv), o3 = gelu_tanh(bfhi(uu.y)) * (acc[ht][4 * q4 + 3] + bsv);
;                     u32x2 w; w.x = pk2(o0, o1); w.y = pk2(o2, o3); *(u32x2*)(yo + ht * 32 + 8 * q4) = w; }
	v_mov_b64_e32 v[16:17], v[220:221]
	v_lshlrev_b32_e32 v18, 16, v16
	v_mul_f32_e32 v20, 0x3d372713, v18
	v_mul_f32_e32 v20, v20, v18
	v_mov_b32_e32 v21, v18
	v_fmac_f32_e32 v21, v20, v21
	v_and_b32_e32 v16, 0xffff0000, v16
	v_mul_f32_e32 v20, 0x3f4c422a, v21
	v_mul_f32_e32 v21, 0x3d372713, v16
	v_mul_f32_e32 v21, v21, v16
	v_mov_b32_e32 v22, v16
	v_fmac_f32_e32 v22, v21, v22
	v_mul_f32_e32 v21, 0x3f4c422a, v22
	v_add_f32_e32 v21, v21, v21
	v_mul_f32_e32 v21, 0x3fb8aa3b, v21
	v_exp_f32_e32 v21, v21
	v_lshlrev_b32_e32 v19, 16, v17
	v_mov_b32_e32 v23, v19
	v_add_f32_e32 v20, v20, v20
	v_add_f32_e32 v21, 1.0, v21
	v_rcp_f32_e32 v22, v21
	v_mul_f32_e32 v21, 0x3d372713, v19
	v_mul_f32_e32 v21, v21, v19
	v_fmac_f32_e32 v23, v21, v23
	v_mul_f32_e32 v21, 0x3f4c422a, v23
	v_add_f32_e32 v21, v21, v21
	v_mul_f32_e32 v20, 0x3fb8aa3b, v20
	v_mul_f32_e32 v21, 0x3fb8aa3b, v21
	v_exp_f32_e32 v20, v20
	v_exp_f32_e32 v21, v21
	v_pk_mul_f32 v[18:19], v[18:19], 0.5 op_sel_hi:[1,0]
	v_and_b32_e32 v17, 0xffff0000, v17
	v_add_f32_e32 v20, 1.0, v20
	v_add_f32_e32 v21, 1.0, v21
	v_rcp_f32_e32 v20, v20
	v_rcp_f32_e32 v21, v21
	s_nop 0
	v_pk_fma_f32 v[20:21], v[20:21], 2.0, 1.0 op_sel_hi:[1,0,0] neg_lo:[1,0,0] neg_hi:[1,0,0]
	s_nop 0
	v_pk_add_f32 v[20:21], v[20:21], 1.0 op_sel_hi:[1,0]
	s_nop 0
	v_pk_mul_f32 v[18:19], v[18:19], v[20:21]
	v_mov_b32_e32 v20, v28
	v_mov_b32_e32 v21, v30
	v_pk_add_f32 v[20:21], v[20:21], v[64:65] op_sel_hi:[1,0]
	v_mov_b32_e32 v30, v29
	v_pk_mul_f32 v[18:19], v[20:21], v[18:19]
	v_mul_f32_e32 v20, 0x3d372713, v17
	v_mul_f32_e32 v20, v20, v17
	v_mov_b32_e32 v21, v17
	v_fmac_f32_e32 v21, v20, v21
	v_mul_f32_e32 v20, 0x3f4c422a, v21
	v_add_f32_e32 v20, v20, v20
	v_mul_f32_e32 v20, 0x3fb8aa3b, v20
	v_exp_f32_e32 v20, v20
	v_pk_mul_f32 v[16:17], v[16:17], 0.5 op_sel_hi:[1,0]
	v_add_f32_e32 v20, 1.0, v20
	v_rcp_f32_e32 v23, v20
	s_nop 0
	v_pk_fma_f32 v[20:21], v[22:23], 2.0, 1.0 op_sel_hi:[1,0,0] neg_lo:[1,0,0] neg_hi:[1,0,0]
	s_nop 0
	v_pk_add_f32 v[20:21], v[20:21], 1.0 op_sel_hi:[1,0]
	s_nop 0
	v_pk_mul_f32 v[16:17], v[16:17], v[20:21]
	v_pk_add_f32 v[20:21], v[30:31], v[64:65] op_sel_hi:[1,0]
	s_nop 0
	v_pk_mul_f32 v[16:17], v[20:21], v[16:17]
	v_and_b32_sdwa v20, v19, v196 dst_sel:DWORD dst_unused:UNUSED_PAD src0_sel:WORD_1 src1_sel:DWORD
	v_and_b32_sdwa v21, v18, v196 dst_sel:DWORD dst_unused:UNUSED_PAD src0_sel:WORD_1 src1_sel:DWORD
	v_add3_u32 v18, v18, v21, s45
	v_add3_u32 v19, v19, v20, s45
	v_and_b32_sdwa v20, v17, v196 dst_sel:DWORD dst_unused:UNUSED_PAD src0_sel:WORD_1 src1_sel:DWORD
	v_and_b32_sdwa v21, v16, v196 dst_sel:DWORD dst_unused:UNUSED_PAD src0_sel:WORD_1 src1_sel:DWORD
	v_add3_u32 v17, v17, v20, s45
	v_add3_u32 v16, v16, v21, s45
	v_and_b32_e32 v17, 0xffff0000, v17
	v_and_b32_e32 v16, 0xffff0000, v16
	v_or_b32_sdwa v17, v17, v19 dst_sel:DWORD dst_unused:UNUSED_PAD src0_sel:DWORD src1_sel:WORD_1
	v_or_b32_sdwa v16, v16, v18 dst_sel:DWORD dst_unused:UNUSED_PAD src0_sel:DWORD src1_sel:WORD_1
	global_store_dwordx2 v[66:67], v[16:17], off offset:176
	s_waitcnt vmcnt(15)
	v_mov_b64_e32 v[16:17], v[222:223]
	v_lshlrev_b32_e32 v18, 16, v16
	v_mul_f32_e32 v20, 0x3d372713, v18
	v_mul_f32_e32 v20, v20, v18
	v_mov_b32_e32 v21, v18
	v_fmac_f32_e32 v21, v20, v21
	v_and_b32_e32 v16, 0xffff0000, v16
	v_mul_f32_e32 v20, 0x3f4c422a, v21
	v_mul_f32_e32 v21, 0x3d372713, v16
	v_mul_f32_e32 v21, v21, v16
	v_mov_b32_e32 v22, v16
	v_fmac_f32_e32 v22, v21, v22
	v_mul_f32_e32 v21, 0x3f4c422a, v22
	v_add_f32_e32 v21, v21, v21
	v_mul_f32_e32 v21, 0x3fb8aa3b, v21
	v_exp_f32_e32 v21, v21
	v_lshlrev_b32_e32 v19, 16, v17
	v_mov_b32_e32 v23, v19
	v_add_f32_e32 v20, v20, v20
	v_add_f32_e32 v21, 1.0, v21
	v_rcp_f32_e32 v22, v21
	v_mul_f32_e32 v21, 0x3d372713, v19
	v_mul_f32_e32 v21, v21, v19
	v_fmac_f32_e32 v23, v21, v23
	v_mul_f32_e32 v21, 0x3f4c422a, v23
	v_add_f32_e32 v21, v21, v21
	v_mul_f32_e32 v20, 0x3fb8aa3b, v20
	v_mul_f32_e32 v21, 0x3fb8aa3b, v21
	v_exp_f32_e32 v20, v20
	v_exp_f32_e32 v21, v21
	v_and_b32_e32 v17, 0xffff0000, v17
	v_pk_mul_f32 v[18:19], v[18:19], 0.5 op_sel_hi:[1,0]
	v_add_f32_e32 v20, 1.0, v20
	v_add_f32_e32 v21, 1.0, v21
	v_rcp_f32_e32 v20, v20
	v_rcp_f32_e32 v21, v21
	s_nop 0
	v_pk_fma_f32 v[20:21], v[20:21], 2.0, 1.0 op_sel_hi:[1,0,0] neg_lo:[1,0,0] neg_hi:[1,0,0]
	s_nop 0
	v_pk_add_f32 v[20:21], v[20:21], 1.0 op_sel_hi:[1,0]
	s_nop 0
	v_pk_mul_f32 v[18:19], v[18:19], v[20:21]
	v_mov_b32_e32 v20, v0
	v_mul_f32_e32 v0, 0x3d372713, v17
	v_mov_b32_e32 v21, v2
	v_mul_f32_e32 v0, v0, v17
	v_mov_b32_e32 v2, v17
	v_fmac_f32_e32 v2, v0, v2
	v_mul_f32_e32 v0, 0x3f4c422a, v2
	v_add_f32_e32 v0, v0, v0
	v_mul_f32_e32 v0, 0x3fb8aa3b, v0
	v_exp_f32_e32 v0, v0
	v_pk_add_f32 v[20:21], v[20:21], v[64:65] op_sel_hi:[1,0]
	v_pk_mul_f32 v[16:17], v[16:17], 0.5 op_sel_hi:[1,0]
	v_pk_mul_f32 v[18:19], v[20:21], v[18:19]
	v_add_f32_e32 v0, 1.0, v0
	v_rcp_f32_e32 v23, v0
	v_mov_b32_e32 v2, v1
	v_pk_add_f32 v[0:1], v[2:3], v[64:65] op_sel_hi:[1,0]
	v_and_b32_sdwa v2, v19, v196 dst_sel:DWORD dst_unused:UNUSED_PAD src0_sel:WORD_1 src1_sel:DWORD
	v_pk_fma_f32 v[20:21], v[22:23], 2.0, 1.0 op_sel_hi:[1,0,0] neg_lo:[1,0,0] neg_hi:[1,0,0]
	v_and_b32_sdwa v3, v18, v196 dst_sel:DWORD dst_unused:UNUSED_PAD src0_sel:WORD_1 src1_sel:DWORD
	v_pk_add_f32 v[20:21], v[20:21], 1.0 op_sel_hi:[1,0]
	v_add3_u32 v3, v18, v3, s45
	v_pk_mul_f32 v[16:17], v[16:17], v[20:21]
	v_add3_u32 v2, v19, v2, s45
	v_pk_mul_f32 v[0:1], v[0:1], v[16:17]
	s_nop 0
	v_and_b32_sdwa v16, v1, v196 dst_sel:DWORD dst_unused:UNUSED_PAD src0_sel:WORD_1 src1_sel:DWORD
	v_and_b32_sdwa v17, v0, v196 dst_sel:DWORD dst_unused:UNUSED_PAD src0_sel:WORD_1 src1_sel:DWORD
	v_add3_u32 v1, v1, v16, s45
	v_add3_u32 v0, v0, v17, s45
	v_and_b32_e32 v1, 0xffff0000, v1
	v_and_b32_e32 v0, 0xffff0000, v0
	v_or_b32_sdwa v1, v1, v2 dst_sel:DWORD dst_unused:UNUSED_PAD src0_sel:DWORD src1_sel:WORD_1
	v_or_b32_sdwa v0, v0, v3 dst_sel:DWORD dst_unused:UNUSED_PAD src0_sel:DWORD src1_sel:WORD_1
	global_store_dwordx2 v[66:67], v[0:1], off offset:192
	s_waitcnt vmcnt(15)
; __device__ __forceinline__ unsigned pk2(float lo, float hi) { return f2bf(lo) | (f2bf(hi) << 16); }
; __device__ __forceinline__ void gmlp_fast(KArgs ap, int l, LAS unsigned char* lds, const Ctx cx) {
;     ...
;                 for (int q4 = 0; q4 < 4; ++q4) { const u32x2 uu = *(const u32x2*)(zu + ht * 32 + 8 * q4);
;                     const float o0 = gelu_tanh(bflo(uu.x)) * (acc[ht][4 * q4] + bsv), o1 = gelu_tanh(bfhi(uu.x)) * (acc[ht][4 * q4 + 1] + bsv);
;                     const float o2 = gelu_tanh(bflo(uu.y)) * (acc[ht][4 * q4 + 2] + bsv), o3 = gelu_tanh(bfhi(uu.y)) * (acc[ht][4 * q4 + 3] + bsv);
;                     u32x2 w; w.x = pk2(o0, o1); w.y = pk2(o2, o3); *(u32x2*)(yo + ht * 32 + 8 * q4) = w; }
	v_mov_b64_e32 v[0:1], v[224:225]
	v_lshlrev_b32_e32 v2, 16, v0
	v_mul_f32_e32 v16, 0x3d372713, v2
	v_mul_f32_e32 v16, v16, v2
	v_mov_b32_e32 v17, v2
	v_fmac_f32_e32 v17, v16, v17
	v_and_b32_e32 v0, 0xffff0000, v0
	v_mul_f32_e32 v16, 0x3f4c422a, v17
	v_mul_f32_e32 v17, 0x3d372713, v0
	v_mul_f32_e32 v17, v17, v0
	v_mov_b32_e32 v18, v0
	v_fmac_f32_e32 v18, v17, v18
	v_mul_f32_e32 v17, 0x3f4c422a, v18
	v_add_f32_e32 v17, v17, v17
	v_mul_f32_e32 v17, 0x3fb8aa3b, v17
	v_exp_f32_e32 v17, v17
	v_lshlrev_b32_e32 v3, 16, v1
	v_mov_b32_e32 v19, v3
	v_add_f32_e32 v16, v16, v16
	v_add_f32_e32 v17, 1.0, v17
	v_rcp_f32_e32 v18, v17
	v_mul_f32_e32 v17, 0x3d372713, v3
	v_mul_f32_e32 v17, v17, v3
	v_fmac_f32_e32 v19, v17, v19
	v_mul_f32_e32 v17, 0x3f4c422a, v19
	v_add_f32_e32 v17, v17, v17
	v_mul_f32_e32 v16, 0x3fb8aa3b, v16
	v_mul_f32_e32 v17, 0x3fb8aa3b, v17
	v_exp_f32_e32 v16, v16
	v_exp_f32_e32 v17, v17
	v_and_b32_e32 v1, 0xffff0000, v1
	v_pk_mul_f32 v[2:3], v[2:3], 0.5 op_sel_hi:[1,0]
	v_add_f32_e32 v16, 1.0, v16
	v_add_f32_e32 v17, 1.0, v17
	v_rcp_f32_e32 v16, v16
	v_rcp_f32_e32 v17, v17
	s_nop 0
	v_pk_fma_f32 v[16:17], v[16:17], 2.0, 1.0 op_sel_hi:[1,0,0] neg_lo:[1,0,0] neg_hi:[1,0,0]
	s_nop 0
	v_pk_add_f32 v[16:17], v[16:17], 1.0 op_sel_hi:[1,0]
	s_nop 0
	v_pk_mul_f32 v[2:3], v[2:3], v[16:17]
	v_mov_b32_e32 v16, v4
	v_mul_f32_e32 v4, 0x3d372713, v1
	v_mov_b32_e32 v17, v6
	v_mul_f32_e32 v4, v4, v1
	v_mov_b32_e32 v6, v1
	v_fmac_f32_e32 v6, v4, v6
	v_mul_f32_e32 v4, 0x3f4c422a, v6
	v_add_f32_e32 v4, v4, v4
	v_mul_f32_e32 v4, 0x3fb8aa3b, v4
	v_exp_f32_e32 v4, v4
	v_pk_add_f32 v[16:17], v[16:17], v[64:65] op_sel_hi:[1,0]
	v_pk_mul_f32 v[0:1], v[0:1], 0.5 op_sel_hi:[1,0]
	v_pk_mul_f32 v[2:3], v[16:17], v[2:3]
	v_add_f32_e32 v4, 1.0, v4
	v_rcp_f32_e32 v19, v4
	v_mov_b32_e32 v6, v5
	v_pk_add_f32 v[4:5], v[6:7], v[64:65] op_sel_hi:[1,0]
	v_pk_fma_f32 v[16:17], v[18:19], 2.0, 1.0 op_sel_hi:[1,0,0] neg_lo:[1,0,0] neg_hi:[1,0,0]
	s_nop 0
	v_pk_add_f32 v[16:17], v[16:17], 1.0 op_sel_hi:[1,0]
	s_nop 0
	v_pk_mul_f32 v[0:1], v[0:1], v[16:17]
	s_nop 0
	v_pk_mul_f32 v[0:1], v[4:5], v[0:1]
	v_and_b32_sdwa v4, v3, v196 dst_sel:DWORD dst_unused:UNUSED_PAD src0_sel:WORD_1 src1_sel:DWORD
	v_and_b32_sdwa v5, v2, v196 dst_sel:DWORD dst_unused:UNUSED_PAD src0_sel:WORD_1 src1_sel:DWORD
	v_add3_u32 v2, v2, v5, s45
	v_add3_u32 v3, v3, v4, s45
	v_and_b32_sdwa v4, v1, v196 dst_sel:DWORD dst_unused:UNUSED_PAD src0_sel:WORD_1 src1_sel:DWORD
	v_and_b32_sdwa v5, v0, v196 dst_sel:DWORD dst_unused:UNUSED_PAD src0_sel:WORD_1 src1_sel:DWORD
	v_add3_u32 v1, v1, v4, s45
	v_add3_u32 v0, v0, v5, s45
	v_and_b32_e32 v1, 0xffff0000, v1
	v_and_b32_e32 v0, 0xffff0000, v0
	v_or_b32_sdwa v1, v1, v3 dst_sel:DWORD dst_unused:UNUSED_PAD src0_sel:DWORD src1_sel:WORD_1
	v_or_b32_sdwa v0, v0, v2 dst_sel:DWORD dst_unused:UNUSED_PAD src0_sel:DWORD src1_sel:WORD_1
	global_store_dwordx2 v[66:67], v[0:1], off offset:208
	s_waitcnt vmcnt(15)
; __device__ __forceinline__ unsigned pk2(float lo, float hi) { return f2bf(lo) | (f2bf(hi) << 16); }
; __device__ __forceinline__ void gmlp_fast(KArgs ap, int l, LAS unsigned char* lds, const Ctx cx) {
;     ...
;             const size_t t = t0 + tl; const float bsv = bsp[g * 128 + tl];
;             const bf16_t* zu = z + t * DIN + ZGU + g * 128 + 4 * hh; bf16_t* yo = y + t * DM + YG + g * 128 + 4 * hh;
; #pragma unroll
;             for (int ht = 0; ht < 4; ++ht)
; #pragma unroll
;                 for (int q4 = 0; q4 < 4; ++q4) { const u32x2 uu = *(const u32x2*)(zu + ht * 32 + 8 * q4);
;                     const float o0 = gelu_tanh(bflo(uu.x)) * (acc[ht][4 * q4] + bsv), o1 = gelu_tanh(bfhi(uu.x)) * (acc[ht][4 * q4 + 1] + bsv);
;                     const float o2 = gelu_tanh(bflo(uu.y)) * (acc[ht][4 * q4 + 2] + bsv), o3 = gelu_tanh(bfhi(uu.y)) * (acc[ht][4 * q4 + 3] + bsv);
;                     u32x2 w; w.x = pk2(o0, o1); w.y = pk2(o2, o3); *(u32x2*)(yo + ht * 32 + 8 * q4) = w; }
	v_mov_b64_e32 v[0:1], v[226:227]
	v_lshlrev_b32_e32 v2, 16, v0
	v_mul_f32_e32 v4, 0x3d372713, v2
	v_mul_f32_e32 v4, v4, v2
	v_mov_b32_e32 v5, v2
	v_fmac_f32_e32 v5, v4, v5
	v_and_b32_e32 v0, 0xffff0000, v0
	v_mul_f32_e32 v4, 0x3f4c422a, v5
	v_mul_f32_e32 v5, 0x3d372713, v0
	v_mul_f32_e32 v5, v5, v0
	v_mov_b32_e32 v6, v0
	v_fmac_f32_e32 v6, v5, v6
	v_mul_f32_e32 v5, 0x3f4c422a, v6
	v_add_f32_e32 v5, v5, v5
	v_mul_f32_e32 v5, 0x3fb8aa3b, v5
	v_exp_f32_e32 v5, v5
	v_lshlrev_b32_e32 v3, 16, v1
	v_mov_b32_e32 v7, v3
	v_add_f32_e32 v4, v4, v4
	v_add_f32_e32 v5, 1.0, v5
	v_rcp_f32_e32 v6, v5
	v_mul_f32_e32 v5, 0x3d372713, v3
	v_mul_f32_e32 v5, v5, v3
	v_fmac_f32_e32 v7, v5, v7
	v_mul_f32_e32 v5, 0x3f4c422a, v7
	v_add_f32_e32 v5, v5, v5
	v_mul_f32_e32 v4, 0x3fb8aa3b, v4
	v_mul_f32_e32 v5, 0x3fb8aa3b, v5
	v_exp_f32_e32 v4, v4
	v_exp_f32_e32 v5, v5
	v_pk_mul_f32 v[2:3], v[2:3], 0.5 op_sel_hi:[1,0]
	v_and_b32_e32 v1, 0xffff0000, v1
	v_add_f32_e32 v4, 1.0, v4
	v_add_f32_e32 v5, 1.0, v5
	v_rcp_f32_e32 v4, v4
	v_rcp_f32_e32 v5, v5
	s_nop 0
	v_pk_fma_f32 v[4:5], v[4:5], 2.0, 1.0 op_sel_hi:[1,0,0] neg_lo:[1,0,0] neg_hi:[1,0,0]
	s_nop 0
	v_pk_add_f32 v[4:5], v[4:5], 1.0 op_sel_hi:[1,0]
	s_nop 0
	v_pk_mul_f32 v[2:3], v[2:3], v[4:5]
	v_mov_b32_e32 v4, v8
	v_mov_b32_e32 v5, v10
	v_pk_add_f32 v[4:5], v[4:5], v[64:65] op_sel_hi:[1,0]
	v_mov_b32_e32 v10, v9
	v_pk_mul_f32 v[2:3], v[4:5], v[2:3]
	v_mul_f32_e32 v4, 0x3d372713, v1
	v_mul_f32_e32 v4, v4, v1
	v_mov_b32_e32 v5, v1
	v_fmac_f32_e32 v5, v4, v5
	v_mul_f32_e32 v4, 0x3f4c422a, v5
	v_add_f32_e32 v4, v4, v4
	v_mul_f32_e32 v4, 0x3fb8aa3b, v4
	v_exp_f32_e32 v4, v4
	v_pk_mul_f32 v[0:1], v[0:1], 0.5 op_sel_hi:[1,0]
	v_add_f32_e32 v4, 1.0, v4
	v_rcp_f32_e32 v7, v4
	s_nop 0
	v_pk_fma_f32 v[4:5], v[6:7], 2.0, 1.0 op_sel_hi:[1,0,0] neg_lo:[1,0,0] neg_hi:[1,0,0]
	s_nop 0
	v_pk_add_f32 v[4:5], v[4:5], 1.0 op_sel_hi:[1,0]
	s_nop 0
	v_pk_mul_f32 v[0:1], v[0:1], v[4:5]
	v_pk_add_f32 v[4:5], v[10:11], v[64:65] op_sel_hi:[1,0]
	s_nop 0
	v_pk_mul_f32 v[0:1], v[4:5], v[0:1]
	v_and_b32_sdwa v4, v3, v196 dst_sel:DWORD dst_unused:UNUSED_PAD src0_sel:WORD_1 src1_sel:DWORD
	v_and_b32_sdwa v5, v2, v196 dst_sel:DWORD dst_unused:UNUSED_PAD src0_sel:WORD_1 src1_sel:DWORD
	v_add3_u32 v2, v2, v5, s45
	v_add3_u32 v3, v3, v4, s45
	v_and_b32_sdwa v4, v1, v196 dst_sel:DWORD dst_unused:UNUSED_PAD src0_sel:WORD_1 src1_sel:DWORD
	v_and_b32_sdwa v5, v0, v196 dst_sel:DWORD dst_unused:UNUSED_PAD src0_sel:WORD_1 src1_sel:DWORD
	v_add3_u32 v1, v1, v4, s45
	v_add3_u32 v0, v0, v5, s45
	v_and_b32_e32 v1, 0xffff0000, v1
	v_and_b32_e32 v0, 0xffff0000, v0
	v_or_b32_sdwa v1, v1, v3 dst_sel:DWORD dst_unused:UNUSED_PAD src0_sel:DWORD src1_sel:WORD_1
	v_or_b32_sdwa v0, v0, v2 dst_sel:DWORD dst_unused:UNUSED_PAD src0_sel:DWORD src1_sel:WORD_1
	s_nop 0
	global_store_dwordx2 v[66:67], v[0:1], off offset:224
	s_waitcnt vmcnt(15)
	v_mov_b64_e32 v[2:3], v[228:229]
	v_lshlrev_b32_e32 v0, 16, v2
	v_mul_f32_e32 v4, 0x3d372713, v0
	v_mul_f32_e32 v4, v4, v0
	v_mov_b32_e32 v5, v0
	v_fmac_f32_e32 v5, v4, v5
	v_and_b32_e32 v2, 0xffff0000, v2
	v_mul_f32_e32 v4, 0x3f4c422a, v5
	v_mul_f32_e32 v5, 0x3d372713, v2
	v_mul_f32_e32 v5, v5, v2
	v_mov_b32_e32 v6, v2
	v_fmac_f32_e32 v6, v5, v6
	v_mul_f32_e32 v5, 0x3f4c422a, v6
	v_add_f32_e32 v5, v5, v5
	v_mul_f32_e32 v5, 0x3fb8aa3b, v5
	v_exp_f32_e32 v5, v5
	v_lshlrev_b32_e32 v1, 16, v3
	v_mov_b32_e32 v7, v1
	v_add_f32_e32 v4, v4, v4
	v_add_f32_e32 v5, 1.0, v5
	v_rcp_f32_e32 v6, v5
	v_mul_f32_e32 v5, 0x3d372713, v1
	v_mul_f32_e32 v5, v5, v1
	v_fmac_f32_e32 v7, v5, v7
	v_mul_f32_e32 v5, 0x3f4c422a, v7
	v_add_f32_e32 v5, v5, v5
	v_mul_f32_e32 v4, 0x3fb8aa3b, v4
	v_mul_f32_e32 v5, 0x3fb8aa3b, v5
	v_exp_f32_e32 v4, v4
	v_exp_f32_e32 v5, v5
	v_pk_mul_f32 v[0:1], v[0:1], 0.5 op_sel_hi:[1,0]
	v_and_b32_e32 v3, 0xffff0000, v3
	v_add_f32_e32 v4, 1.0, v4
	v_add_f32_e32 v5, 1.0, v5
	v_rcp_f32_e32 v4, v4
	v_rcp_f32_e32 v5, v5
	s_nop 0
	v_pk_fma_f32 v[4:5], v[4:5], 2.0, 1.0 op_sel_hi:[1,0,0] neg_lo:[1,0,0] neg_hi:[1,0,0]
	s_nop 0
	v_pk_add_f32 v[4:5], v[4:5], 1.0 op_sel_hi:[1,0]
	s_nop 0
	v_pk_mul_f32 v[0:1], v[0:1], v[4:5]
	v_mov_b32_e32 v4, v12
	v_mov_b32_e32 v5, v14
	v_pk_add_f32 v[4:5], v[4:5], v[64:65] op_sel_hi:[1,0]
	v_mov_b32_e32 v14, v13
	v_pk_mul_f32 v[0:1], v[4:5], v[0:1]
	v_mul_f32_e32 v4, 0x3d372713, v3
	v_mul_f32_e32 v4, v4, v3
	v_mov_b32_e32 v5, v3
	v_fmac_f32_e32 v5, v4, v5
	v_mul_f32_e32 v4, 0x3f4c422a, v5
	v_add_f32_e32 v4, v4, v4
	v_mul_f32_e32 v4, 0x3fb8aa3b, v4
	v_exp_f32_e32 v4, v4
	v_pk_mul_f32 v[2:3], v[2:3], 0.5 op_sel_hi:[1,0]
	v_add_f32_e32 v4, 1.0, v4
	v_rcp_f32_e32 v7, v4
	s_nop 0
	v_pk_fma_f32 v[4:5], v[6:7], 2.0, 1.0 op_sel_hi:[1,0,0] neg_lo:[1,0,0] neg_hi:[1,0,0]
	s_nop 0
	v_pk_add_f32 v[4:5], v[4:5], 1.0 op_sel_hi:[1,0]
	s_nop 0
	v_pk_mul_f32 v[2:3], v[2:3], v[4:5]
	v_pk_add_f32 v[4:5], v[14:15], v[64:65] op_sel_hi:[1,0]
	s_nop 0
	v_pk_mul_f32 v[2:3], v[4:5], v[2:3]
	v_and_b32_sdwa v4, v1, v196 dst_sel:DWORD dst_unused:UNUSED_PAD src0_sel:WORD_1 src1_sel:DWORD
	v_and_b32_sdwa v5, v0, v196 dst_sel:DWORD dst_unused:UNUSED_PAD src0_sel:WORD_1 src1_sel:DWORD
	v_add3_u32 v0, v0, v5, s45
	v_add3_u32 v1, v1, v4, s45
	v_and_b32_sdwa v4, v3, v196 dst_sel:DWORD dst_unused:UNUSED_PAD src0_sel:WORD_1 src1_sel:DWORD
	v_and_b32_sdwa v5, v2, v196 dst_sel:DWORD dst_unused:UNUSED_PAD src0_sel:WORD_1 src1_sel:DWORD
	v_add3_u32 v3, v3, v4, s45
	v_add3_u32 v2, v2, v5, s45
	v_and_b32_e32 v3, 0xffff0000, v3
	v_and_b32_e32 v2, 0xffff0000, v2
	v_or_b32_sdwa v1, v3, v1 dst_sel:DWORD dst_unused:UNUSED_PAD src0_sel:DWORD src1_sel:WORD_1
	v_or_b32_sdwa v0, v2, v0 dst_sel:DWORD dst_unused:UNUSED_PAD src0_sel:DWORD src1_sel:WORD_1
	global_store_dwordx2 v[66:67], v[0:1], off offset:240
	s_cbranch_vccnz .LBB0_140

; #define PG8_STAGE(bufoff, gbase, voff) do { _Pragma("unroll") for (int _i = 0; _i < 2; ++_i) \
;         __builtin_amdgcn_global_load_lds((const unsigned*)((const char*)(gbase) + (voff)[_i]), (LAS unsigned*)(lds + (bufoff) + ldsw + _i * 8192), 16, 0, 0); } while (0)
; #define PG8_LDA(dst, b, h) do { _Pragma("unroll") for (int m = 0; m < 4; ++m) _Pragma("unroll") for (int k = 0; k < 2; ++k) dst[m][k] = *(const LAS bf16x8*)(lds + PG8_SA(b, h) + aoff + m * 2048 + k * 1024); } while (0)
; #define PG8_WAIT_V(n) asm volatile("s_waitcnt vmcnt(" #n ")" ::: "memory")
; template <class Epi, class Sched>
; __device__ __forceinline__ void gemm_phase(const int tid, LAS unsigned char* lds, const Gemm g, const Sched& S, const Epi& E) {
;     ...
;     for (;;) {
;         const bool has_next = S.next(ui + 1, nxt);
;         const char* nA = has_next ? (const char*)g.A + (size_t)nxt.pm * tstep : cA; const char* nB = has_next ? (const char*)g.Bt + (size_t)nxt.pn * tstep : cB;
;         for (int t = 0; t < nt; t += 2) {
;             const bool last = (t == nt - 2);
;             const char* a1 = cA + (size_t)(t + 1) * kstep;
;             const char* a2 = last ? nA : cA + (size_t)(t + 2) * kstep; const char* b2 = last ? nB : cB + (size_t)(t + 2) * kstep;
;             const char* a3 = a2 + kstep; const char* b3 = b2 + kstep;
;             if (last && has_next) S.a_ready(nxt);
;             PG8_LDB(B0, 0, 0); PG8_LDB(B1, 0, 1); PG8_SCHED; PG8_LDA(At, 0, 0); PG8_STAGE(PG8_SA(1, 1), a1 + hstep, voffA);
;             PG8_WAIT_V(8); PG8_WAIT_L(0); PG8_BAR; PG8_MMA(0, 0, At, B0); PG8_MMA(0, 1, At, B1); PG8_BAR; PG8_SCHED;
;             PG8_LDA(At, 0, 1); PG8_STAGE(PG8_SB(0, 0), b2, voffB); PG8_STAGE(PG8_SB(0, 1), b2 + hstep, voffB); PG8_STAGE(PG8_SA(0, 0), a2, voffA);
;             PG8_WAIT_V(8); PG8_WAIT_L(0); PG8_BAR; PG8_MMA(1, 0, At, B0); PG8_MMA(1, 1, At, B1); PG8_BAR; PG8_SCHED;
;             PG8_LDB(B0, 1, 0); PG8_LDB(B1, 1, 1); PG8_SCHED; PG8_LDA(At, 1, 0); PG8_STAGE(PG8_SA(0, 1), a2 + hstep, voffA);
;             PG8_WAIT_V(8); PG8_WAIT_L(0); PG8_BAR; PG8_MMA(0, 0, At, B0); PG8_MMA(0, 1, At, B1); PG8_BAR; PG8_SCHED;
;             PG8_LDA(At, 1, 1); PG8_STAGE(PG8_SB(1, 0), b3, voffB); PG8_STAGE(PG8_SB(1, 1), b3 + hstep, voffB); PG8_STAGE(PG8_SA(1, 0), a3, voffA);
;             PG8_WAIT_V(8); PG8_WAIT_L(0); PG8_BAR; PG8_MMA(1, 0, At, B0); PG8_MMA(1, 1, At, B1); PG8_BAR; PG8_SCHED;
.LBB0_394:
	s_ashr_i32 s15, s14, 31
	s_lshl_b64 s[16:17], s[14:15], 18
	s_add_u32 s16, s40, s16
	s_addc_u32 s17, s41, s17
	s_and_b64 s[18:19], s[0:1], exec
	s_cselect_b32 s15, s17, s23
	s_cselect_b32 s66, s16, s22
	s_ashr_i32 s13, s12, 31
	s_lshl_b64 s[18:19], s[12:13], 18
	s_add_u32 s18, s38, s18
	s_addc_u32 s19, s39, s19
	s_and_b64 s[26:27], s[0:1], exec
	s_cselect_b32 s13, s19, s25
	s_cselect_b32 s67, s18, s24
	s_add_u32 s22, s22, 0x20080
	s_addc_u32 s23, s23, 0
	s_add_u32 s68, s24, 0x100
	v_mov_b32_e32 v0, 0
	s_addc_u32 s69, s25, 0
	s_mov_b32 s70, -2
	s_add_u32 s24, s22, 0xfffe0080
	s_addc_u32 s25, s23, -1
	s_add_i32 s71, 0, 0x10000
	s_cmp_eq_u32 s70, 4
	s_cselect_b32 s27, s15, s25
	s_cselect_b32 s26, s66, s24
	v_add_u32_e32 v150, s71, v144
	s_cselect_b32 s25, s13, s69
	s_cselect_b32 s24, s67, s68
	s_add_i32 s74, 0, 0x14000
	ds_read_b128 v[138:141], v150
	ds_read_b128 v[146:149], v150 offset:1024
	ds_read_b128 v[170:173], v150 offset:2048
	ds_read_b128 v[174:177], v150 offset:3072
	v_add_u32_e32 v150, s74, v144
	ds_read_b128 v[178:181], v150
	ds_read_b128 v[182:185], v150 offset:1024
	ds_read_b128 v[186:189], v150 offset:2048
	ds_read_b128 v[200:203], v150 offset:3072
	v_lshl_add_u64 v[150:151], s[22:23], 0, v[134:135]
	s_add_i32 m0, s21, 0xc000
	ds_read_b128 v[204:207], v145
	ds_read_b128 v[208:211], v145 offset:1024
	ds_read_b128 v[212:215], v145 offset:2048
	ds_read_b128 v[216:219], v145 offset:3072
	ds_read_b128 v[220:223], v145 offset:4096
	ds_read_b128 v[224:227], v145 offset:5120
	ds_read_b128 v[228:231], v145 offset:6144
	ds_read_b128 v[232:235], v145 offset:7168
	global_load_lds_dwordx4 v[150:151], off
	v_lshl_add_u64 v[150:151], s[22:23], 0, v[136:137]
	s_add_i32 m0, s21, 0xe000
	s_nop 0
	global_load_lds_dwordx4 v[150:151], off
	s_waitcnt vmcnt(8)
	s_waitcnt lgkmcnt(0)
	s_barrier
	s_setprio 1
	s_waitcnt lgkmcnt(0)
	v_mfma_f32_16x16x32_bf16 v[124:127], v[138:141], v[204:207], 0
	v_mfma_f32_16x16x32_bf16 v[120:123], v[170:173], v[204:207], 0
	v_mfma_f32_16x16x32_bf16 v[108:111], v[138:141], v[212:215], 0
	v_mfma_f32_16x16x32_bf16 v[104:107], v[170:173], v[212:215], 0
	v_mfma_f32_16x16x32_bf16 v[92:95], v[138:141], v[220:223], 0
	v_mfma_f32_16x16x32_bf16 v[88:91], v[170:173], v[220:223], 0
	v_mfma_f32_16x16x32_bf16 v[76:79], v[138:141], v[228:231], 0
	v_mfma_f32_16x16x32_bf16 v[72:75], v[170:173], v[228:231], 0
	v_mfma_f32_16x16x32_bf16 v[124:127], v[146:149], v[208:211], v[124:127]
	v_mfma_f32_16x16x32_bf16 v[120:123], v[174:177], v[208:211], v[120:123]
	v_mfma_f32_16x16x32_bf16 v[108:111], v[146:149], v[216:219], v[108:111]
	v_mfma_f32_16x16x32_bf16 v[104:107], v[174:177], v[216:219], v[104:107]
	v_mfma_f32_16x16x32_bf16 v[92:95], v[146:149], v[224:227], v[92:95]
	v_mfma_f32_16x16x32_bf16 v[88:91], v[174:177], v[224:227], v[88:91]
	v_mfma_f32_16x16x32_bf16 v[76:79], v[146:149], v[232:235], v[76:79]
	v_mfma_f32_16x16x32_bf16 v[72:75], v[174:177], v[232:235], v[72:75]
	s_setprio 0
	s_setprio 1
	v_mfma_f32_16x16x32_bf16 v[116:119], v[178:181], v[204:207], 0
	v_mfma_f32_16x16x32_bf16 v[112:115], v[186:189], v[204:207], 0
	v_mfma_f32_16x16x32_bf16 v[100:103], v[178:181], v[212:215], 0
	v_mfma_f32_16x16x32_bf16 v[96:99], v[186:189], v[212:215], 0
	v_mfma_f32_16x16x32_bf16 v[84:87], v[178:181], v[220:223], 0
	v_mfma_f32_16x16x32_bf16 v[80:83], v[186:189], v[220:223], 0
	v_mfma_f32_16x16x32_bf16 v[68:71], v[178:181], v[228:231], 0
	v_mfma_f32_16x16x32_bf16 v[64:67], v[186:189], v[228:231], 0
	v_mfma_f32_16x16x32_bf16 v[116:119], v[182:185], v[208:211], v[116:119]
	v_mfma_f32_16x16x32_bf16 v[112:115], v[200:203], v[208:211], v[112:115]
	v_mfma_f32_16x16x32_bf16 v[100:103], v[182:185], v[216:219], v[100:103]
	v_mfma_f32_16x16x32_bf16 v[96:99], v[200:203], v[216:219], v[96:99]
	v_mfma_f32_16x16x32_bf16 v[84:87], v[182:185], v[224:227], v[84:87]
	v_mfma_f32_16x16x32_bf16 v[80:83], v[200:203], v[224:227], v[80:83]
	v_mfma_f32_16x16x32_bf16 v[68:71], v[182:185], v[232:235], v[68:71]
	v_mfma_f32_16x16x32_bf16 v[64:67], v[200:203], v[232:235], v[64:67]
	s_setprio 0
	s_barrier
	s_add_i32 s71, s71, s55
	v_lshl_add_u64 v[150:151], s[24:25], 0, v[152:153]
	s_mov_b32 m0, s71
	ds_read_b128 v[204:207], v145 offset:16384
	ds_read_b128 v[208:211], v145 offset:17408
	ds_read_b128 v[212:215], v145 offset:18432
	ds_read_b128 v[216:219], v145 offset:19456
	ds_read_b128 v[220:223], v145 offset:20480
	ds_read_b128 v[224:227], v145 offset:21504
	ds_read_b128 v[228:231], v145 offset:22528
	ds_read_b128 v[232:235], v145 offset:23552
	global_load_lds_dwordx4 v[150:151], off
	s_add_i32 m0, s71, 0x2000
	s_add_u32 s72, s24, 0x20000
	v_lshl_add_u64 v[190:191], s[24:25], 0, v[132:133]
	s_addc_u32 s73, s25, 0
	s_add_i32 s71, s74, s55
	global_load_lds_dwordx4 v[190:191], off
	v_lshl_add_u64 v[236:237], s[72:73], 0, v[152:153]
	s_mov_b32 m0, s71
	v_lshl_add_u64 v[238:239], s[26:27], 0, v[130:131]
	global_load_lds_dwordx4 v[236:237], off
	v_lshl_add_u64 v[236:237], s[72:73], 0, v[132:133]
	s_add_i32 m0, s71, 0x2000
	s_nop 0
	global_load_lds_dwordx4 v[236:237], off
	v_lshl_add_u64 v[236:237], s[26:27], 0, v[128:129]
	s_mov_b32 m0, s21
	s_nop 0
	global_load_lds_dwordx4 v[236:237], off
	s_mov_b32 m0, s56
	s_nop 0
	global_load_lds_dwordx4 v[238:239], off
	s_waitcnt vmcnt(8)
	s_waitcnt lgkmcnt(0)
	s_barrier
; #define PG8_STAGE(bufoff, gbase, voff) do { _Pragma("unroll") for (int _i = 0; _i < 2; ++_i) \
;         __builtin_amdgcn_global_load_lds((const unsigned*)((const char*)(gbase) + (voff)[_i]), (LAS unsigned*)(lds + (bufoff) + ldsw + _i * 8192), 16, 0, 0); } while (0)
; #define PG8_LDA(dst, b, h) do { _Pragma("unroll") for (int m = 0; m < 4; ++m) _Pragma("unroll") for (int k = 0; k < 2; ++k) dst[m][k] = *(const LAS bf16x8*)(lds + PG8_SA(b, h) + aoff + m * 2048 + k * 1024); } while (0)
; #define PG8_LDB(dst, b, h) do { _Pragma("unroll") for (int n = 0; n < 2; ++n) _Pragma("unroll") for (int k = 0; k < 2; ++k) dst[n][k] = *(const LAS bf16x8*)(lds + PG8_SB(b, h) + boff + n * 2048 + k * 1024); } while (0)
; #define PG8_MMA(ai, bj, At, Bt) do { __builtin_amdgcn_s_setprio(1); _Pragma("unroll") for (int m = 0; m < 4; ++m) _Pragma("unroll") for (int n = 0; n < 2; ++n) _Pragma("unroll") for (int k = 0; k < 2; ++k) \
;         acc[ai][bj][m][n] = __builtin_amdgcn_mfma_f32_16x16x32_bf16(Bt[n][k], At[m][k], acc[ai][bj][m][n], 0, 0, 0); __builtin_amdgcn_s_setprio(0); } while (0)
; #define PG8_WAIT_V(n) asm volatile("s_waitcnt vmcnt(" #n ")" ::: "memory")
; #define PG8_WAIT_L(n) asm volatile("s_waitcnt lgkmcnt(" #n ")" ::: "memory")
; #define PG8_BAR __builtin_amdgcn_s_barrier()
; template <class Epi, class Sched>
; __device__ __forceinline__ void gemm_phase(const int tid, LAS unsigned char* lds, const Gemm g, const Sched& S, const Epi& E) {
;     ...
;             PG8_WAIT_V(8); PG8_WAIT_L(0); PG8_BAR; PG8_MMA(0, 0, At, B0); PG8_MMA(0, 1, At, B1); PG8_BAR; PG8_SCHED;
;             PG8_LDA(At, 0, 1); PG8_STAGE(PG8_SB(0, 0), b2, voffB); PG8_STAGE(PG8_SB(0, 1), b2 + hstep, voffB); PG8_STAGE(PG8_SA(0, 0), a2, voffA);
;             PG8_WAIT_V(8); PG8_WAIT_L(0); PG8_BAR; PG8_MMA(1, 0, At, B0); PG8_MMA(1, 1, At, B1); PG8_BAR; PG8_SCHED;
;             PG8_LDB(B0, 1, 0); PG8_LDB(B1, 1, 1); PG8_SCHED; PG8_LDA(At, 1, 0); PG8_STAGE(PG8_SA(0, 1), a2 + hstep, voffA);
;             PG8_WAIT_V(8); PG8_WAIT_L(0); PG8_BAR; PG8_MMA(0, 0, At, B0); PG8_MMA(0, 1, At, B1); PG8_BAR; PG8_SCHED;
;             PG8_LDA(At, 1, 1); PG8_STAGE(PG8_SB(1, 0), b3, voffB); PG8_STAGE(PG8_SB(1, 1), b3 + hstep, voffB); PG8_STAGE(PG8_SA(1, 0), a3, voffA);
;             PG8_WAIT_V(8); PG8_WAIT_L(0); PG8_BAR; PG8_MMA(1, 0, At, B0); PG8_MMA(1, 1, At, B1); PG8_BAR; PG8_SCHED;
	s_setprio 1
	s_waitcnt lgkmcnt(0)
	v_mfma_f32_16x16x32_bf16 v[60:63], v[138:141], v[204:207], 0
	v_mfma_f32_16x16x32_bf16 v[56:59], v[170:173], v[204:207], 0
	v_mfma_f32_16x16x32_bf16 v[44:47], v[138:141], v[212:215], 0
	v_mfma_f32_16x16x32_bf16 v[40:43], v[170:173], v[212:215], 0
	v_mfma_f32_16x16x32_bf16 v[28:31], v[138:141], v[220:223], 0
	v_mfma_f32_16x16x32_bf16 v[24:27], v[170:173], v[220:223], 0
	v_mfma_f32_16x16x32_bf16 v[12:15], v[138:141], v[228:231], 0
	v_mfma_f32_16x16x32_bf16 v[8:11], v[170:173], v[228:231], 0
	v_mfma_f32_16x16x32_bf16 v[60:63], v[146:149], v[208:211], v[60:63]
	v_mfma_f32_16x16x32_bf16 v[56:59], v[174:177], v[208:211], v[56:59]
	v_mfma_f32_16x16x32_bf16 v[44:47], v[146:149], v[216:219], v[44:47]
	v_mfma_f32_16x16x32_bf16 v[40:43], v[174:177], v[216:219], v[40:43]
	v_mfma_f32_16x16x32_bf16 v[28:31], v[146:149], v[224:227], v[28:31]
	v_mfma_f32_16x16x32_bf16 v[24:27], v[174:177], v[224:227], v[24:27]
	v_mfma_f32_16x16x32_bf16 v[12:15], v[146:149], v[232:235], v[12:15]
	v_mfma_f32_16x16x32_bf16 v[8:11], v[174:177], v[232:235], v[8:11]
	s_setprio 0
	s_setprio 1
	v_mfma_f32_16x16x32_bf16 v[52:55], v[178:181], v[204:207], 0
	v_mfma_f32_16x16x32_bf16 v[48:51], v[186:189], v[204:207], 0
	v_mfma_f32_16x16x32_bf16 v[36:39], v[178:181], v[212:215], 0
	v_mfma_f32_16x16x32_bf16 v[32:35], v[186:189], v[212:215], 0
	v_mfma_f32_16x16x32_bf16 v[20:23], v[178:181], v[220:223], 0
	v_mfma_f32_16x16x32_bf16 v[16:19], v[186:189], v[220:223], 0
	v_mfma_f32_16x16x32_bf16 v[4:7], v[178:181], v[228:231], 0
	v_mfma_f32_16x16x32_bf16 v[0:3], v[186:189], v[228:231], 0
	v_mfma_f32_16x16x32_bf16 v[52:55], v[182:185], v[208:211], v[52:55]
	v_mfma_f32_16x16x32_bf16 v[48:51], v[200:203], v[208:211], v[48:51]
	v_mfma_f32_16x16x32_bf16 v[36:39], v[182:185], v[216:219], v[36:39]
	v_mfma_f32_16x16x32_bf16 v[32:35], v[200:203], v[216:219], v[32:35]
	v_mfma_f32_16x16x32_bf16 v[20:23], v[182:185], v[224:227], v[20:23]
	v_mfma_f32_16x16x32_bf16 v[16:19], v[200:203], v[224:227], v[16:19]
	v_mfma_f32_16x16x32_bf16 v[4:7], v[182:185], v[232:235], v[4:7]
	v_mfma_f32_16x16x32_bf16 v[0:3], v[200:203], v[232:235], v[0:3]
	s_setprio 0
	s_barrier
	s_add_i32 s71, 0, 0x18000
	s_add_i32 s72, 0, 0x1c000
	v_add_u32_e32 v174, s71, v144
	v_add_u32_e32 v199, s72, v144
	ds_read_b128 v[138:141], v174
	ds_read_b128 v[146:149], v174 offset:1024
	ds_read_b128 v[170:173], v174 offset:2048
	ds_read_b128 v[174:177], v174 offset:3072
	ds_read_b128 v[178:181], v199
	ds_read_b128 v[182:185], v199 offset:1024
	ds_read_b128 v[186:189], v199 offset:2048
	ds_read_b128 v[200:203], v199 offset:3072
	s_add_u32 s26, s26, 0x20000
	s_addc_u32 s27, s27, 0
	s_mov_b32 m0, s57
	v_lshl_add_u64 v[240:241], s[26:27], 0, v[128:129]
	ds_read_b128 v[204:207], v145 offset:32768
	ds_read_b128 v[208:211], v145 offset:33792
	ds_read_b128 v[212:215], v145 offset:34816
	ds_read_b128 v[216:219], v145 offset:35840
	ds_read_b128 v[220:223], v145 offset:36864
	ds_read_b128 v[224:227], v145 offset:37888
	ds_read_b128 v[228:231], v145 offset:38912
	ds_read_b128 v[232:235], v145 offset:39936
	global_load_lds_dwordx4 v[240:241], off
	v_lshl_add_u64 v[240:241], s[26:27], 0, v[130:131]
	s_mov_b32 m0, s58
	s_nop 0
	global_load_lds_dwordx4 v[240:241], off
	s_waitcnt vmcnt(8)
	s_waitcnt lgkmcnt(0)
	s_barrier
	s_setprio 1
	s_waitcnt lgkmcnt(0)
	v_mfma_f32_16x16x32_bf16 v[124:127], v[138:141], v[204:207], v[124:127]
	v_mfma_f32_16x16x32_bf16 v[120:123], v[170:173], v[204:207], v[120:123]
	v_mfma_f32_16x16x32_bf16 v[108:111], v[138:141], v[212:215], v[108:111]
	v_mfma_f32_16x16x32_bf16 v[104:107], v[170:173], v[212:215], v[104:107]
	v_mfma_f32_16x16x32_bf16 v[92:95], v[138:141], v[220:223], v[92:95]
	v_mfma_f32_16x16x32_bf16 v[88:91], v[170:173], v[220:223], v[88:91]
	v_mfma_f32_16x16x32_bf16 v[76:79], v[138:141], v[228:231], v[76:79]
	v_mfma_f32_16x16x32_bf16 v[72:75], v[170:173], v[228:231], v[72:75]
	v_mfma_f32_16x16x32_bf16 v[124:127], v[146:149], v[208:211], v[124:127]
	v_mfma_f32_16x16x32_bf16 v[120:123], v[174:177], v[208:211], v[120:123]
	v_mfma_f32_16x16x32_bf16 v[108:111], v[146:149], v[216:219], v[108:111]
	v_mfma_f32_16x16x32_bf16 v[104:107], v[174:177], v[216:219], v[104:107]
	v_mfma_f32_16x16x32_bf16 v[92:95], v[146:149], v[224:227], v[92:95]
	v_mfma_f32_16x16x32_bf16 v[88:91], v[174:177], v[224:227], v[88:91]
	v_mfma_f32_16x16x32_bf16 v[76:79], v[146:149], v[232:235], v[76:79]
	v_mfma_f32_16x16x32_bf16 v[72:75], v[174:177], v[232:235], v[72:75]
	s_setprio 0
	s_setprio 1
	v_mfma_f32_16x16x32_bf16 v[116:119], v[178:181], v[204:207], v[116:119]
	v_mfma_f32_16x16x32_bf16 v[112:115], v[186:189], v[204:207], v[112:115]
	v_mfma_f32_16x16x32_bf16 v[100:103], v[178:181], v[212:215], v[100:103]
	v_mfma_f32_16x16x32_bf16 v[96:99], v[186:189], v[212:215], v[96:99]
	v_mfma_f32_16x16x32_bf16 v[84:87], v[178:181], v[220:223], v[84:87]
	v_mfma_f32_16x16x32_bf16 v[80:83], v[186:189], v[220:223], v[80:83]
	v_mfma_f32_16x16x32_bf16 v[68:71], v[178:181], v[228:231], v[68:71]
	v_mfma_f32_16x16x32_bf16 v[64:67], v[186:189], v[228:231], v[64:67]
	v_mfma_f32_16x16x32_bf16 v[116:119], v[182:185], v[208:211], v[116:119]
	v_mfma_f32_16x16x32_bf16 v[112:115], v[200:203], v[208:211], v[112:115]
	v_mfma_f32_16x16x32_bf16 v[100:103], v[182:185], v[216:219], v[100:103]
	v_mfma_f32_16x16x32_bf16 v[96:99], v[200:203], v[216:219], v[96:99]
	v_mfma_f32_16x16x32_bf16 v[84:87], v[182:185], v[224:227], v[84:87]
	v_mfma_f32_16x16x32_bf16 v[80:83], v[200:203], v[224:227], v[80:83]
	v_mfma_f32_16x16x32_bf16 v[68:71], v[182:185], v[232:235], v[68:71]
	v_mfma_f32_16x16x32_bf16 v[64:67], v[200:203], v[232:235], v[64:67]
	s_setprio 0
	s_barrier
; #define PG8_STAGE(bufoff, gbase, voff) do { _Pragma("unroll") for (int _i = 0; _i < 2; ++_i) \
;         __builtin_amdgcn_global_load_lds((const unsigned*)((const char*)(gbase) + (voff)[_i]), (LAS unsigned*)(lds + (bufoff) + ldsw + _i * 8192), 16, 0, 0); } while (0)
; #define PG8_LDA(dst, b, h) do { _Pragma("unroll") for (int m = 0; m < 4; ++m) _Pragma("unroll") for (int k = 0; k < 2; ++k) dst[m][k] = *(const LAS bf16x8*)(lds + PG8_SA(b, h) + aoff + m * 2048 + k * 1024); } while (0)
; #define PG8_MMA(ai, bj, At, Bt) do { __builtin_amdgcn_s_setprio(1); _Pragma("unroll") for (int m = 0; m < 4; ++m) _Pragma("unroll") for (int n = 0; n < 2; ++n) _Pragma("unroll") for (int k = 0; k < 2; ++k) \
;         acc[ai][bj][m][n] = __builtin_amdgcn_mfma_f32_16x16x32_bf16(Bt[n][k], At[m][k], acc[ai][bj][m][n], 0, 0, 0); __builtin_amdgcn_s_setprio(0); } while (0)
; #define PG8_WAIT_V(n) asm volatile("s_waitcnt vmcnt(" #n ")" ::: "memory")
; #define PG8_WAIT_L(n) asm volatile("s_waitcnt lgkmcnt(" #n ")" ::: "memory")
; #define PG8_BAR __builtin_amdgcn_s_barrier()
; #define PG8_SCHED __builtin_amdgcn_sched_barrier(0)
; template <class Epi, class Sched>
; __device__ __forceinline__ void gemm_phase(const int tid, LAS unsigned char* lds, const Gemm g, const Sched& S, const Epi& E) {
;     ...
;             PG8_LDA(At, 1, 1); PG8_STAGE(PG8_SB(1, 0), b3, voffB); PG8_STAGE(PG8_SB(1, 1), b3 + hstep, voffB); PG8_STAGE(PG8_SA(1, 0), a3, voffA);
;             PG8_WAIT_V(8); PG8_WAIT_L(0); PG8_BAR; PG8_MMA(1, 0, At, B0); PG8_MMA(1, 1, At, B1); PG8_BAR; PG8_SCHED;
;         }
	s_add_i32 s26, s71, s55
	v_lshl_add_u64 v[150:151], v[150:151], 0, s[34:35]
	s_mov_b32 m0, s26
	ds_read_b128 v[204:207], v145 offset:49152
	ds_read_b128 v[208:211], v145 offset:50176
	ds_read_b128 v[212:215], v145 offset:51200
	ds_read_b128 v[216:219], v145 offset:52224
	ds_read_b128 v[220:223], v145 offset:53248
	ds_read_b128 v[224:227], v145 offset:54272
	ds_read_b128 v[228:231], v145 offset:55296
	ds_read_b128 v[232:235], v145 offset:56320
	global_load_lds_dwordx4 v[150:151], off
	s_add_i32 m0, s26, 0x2000
	s_add_u32 s24, s24, 0x20080
	v_lshl_add_u64 v[150:151], v[190:191], 0, s[34:35]
	s_addc_u32 s25, s25, 0
	s_add_i32 s26, s72, s55
	global_load_lds_dwordx4 v[150:151], off
	v_lshl_add_u64 v[150:151], s[24:25], 0, v[152:153]
	s_mov_b32 m0, s26
	s_nop 0
	global_load_lds_dwordx4 v[150:151], off
	v_lshl_add_u64 v[150:151], s[24:25], 0, v[132:133]
	s_add_i32 m0, s26, 0x2000
	s_nop 0
	global_load_lds_dwordx4 v[150:151], off
	v_lshl_add_u64 v[150:151], v[236:237], 0, s[34:35]
	s_mov_b32 m0, s61
	s_nop 0
	global_load_lds_dwordx4 v[150:151], off
	v_lshl_add_u64 v[150:151], v[238:239], 0, s[34:35]
	s_mov_b32 m0, s62
	s_nop 0
	global_load_lds_dwordx4 v[150:151], off
	s_waitcnt vmcnt(8)
	s_waitcnt lgkmcnt(0)
	s_barrier
	s_setprio 1
	s_waitcnt lgkmcnt(0)
	v_mfma_f32_16x16x32_bf16 v[60:63], v[138:141], v[204:207], v[60:63]
	v_mfma_f32_16x16x32_bf16 v[56:59], v[170:173], v[204:207], v[56:59]
	v_mfma_f32_16x16x32_bf16 v[44:47], v[138:141], v[212:215], v[44:47]
	v_mfma_f32_16x16x32_bf16 v[40:43], v[170:173], v[212:215], v[40:43]
	v_mfma_f32_16x16x32_bf16 v[28:31], v[138:141], v[220:223], v[28:31]
	v_mfma_f32_16x16x32_bf16 v[24:27], v[170:173], v[220:223], v[24:27]
	v_mfma_f32_16x16x32_bf16 v[12:15], v[138:141], v[228:231], v[12:15]
	v_mfma_f32_16x16x32_bf16 v[8:11], v[170:173], v[228:231], v[8:11]
	v_mfma_f32_16x16x32_bf16 v[60:63], v[146:149], v[208:211], v[60:63]
	v_mfma_f32_16x16x32_bf16 v[56:59], v[174:177], v[208:211], v[56:59]
	v_mfma_f32_16x16x32_bf16 v[44:47], v[146:149], v[216:219], v[44:47]
	v_mfma_f32_16x16x32_bf16 v[40:43], v[174:177], v[216:219], v[40:43]
	v_mfma_f32_16x16x32_bf16 v[28:31], v[146:149], v[224:227], v[28:31]
	v_mfma_f32_16x16x32_bf16 v[24:27], v[174:177], v[224:227], v[24:27]
	v_mfma_f32_16x16x32_bf16 v[12:15], v[146:149], v[232:235], v[12:15]
	v_mfma_f32_16x16x32_bf16 v[8:11], v[174:177], v[232:235], v[8:11]
	s_setprio 0
	s_setprio 1
	v_mfma_f32_16x16x32_bf16 v[52:55], v[178:181], v[204:207], v[52:55]
	v_mfma_f32_16x16x32_bf16 v[48:51], v[186:189], v[204:207], v[48:51]
	v_mfma_f32_16x16x32_bf16 v[36:39], v[178:181], v[212:215], v[36:39]
	v_mfma_f32_16x16x32_bf16 v[32:35], v[186:189], v[212:215], v[32:35]
	v_mfma_f32_16x16x32_bf16 v[20:23], v[178:181], v[220:223], v[20:23]
	v_mfma_f32_16x16x32_bf16 v[16:19], v[186:189], v[220:223], v[16:19]
	v_mfma_f32_16x16x32_bf16 v[4:7], v[178:181], v[228:231], v[4:7]
	v_mfma_f32_16x16x32_bf16 v[0:3], v[186:189], v[228:231], v[0:3]
	v_mfma_f32_16x16x32_bf16 v[52:55], v[182:185], v[208:211], v[52:55]
	v_mfma_f32_16x16x32_bf16 v[48:51], v[200:203], v[208:211], v[48:51]
	v_mfma_f32_16x16x32_bf16 v[36:39], v[182:185], v[216:219], v[36:39]
	v_mfma_f32_16x16x32_bf16 v[32:35], v[200:203], v[216:219], v[32:35]
	v_mfma_f32_16x16x32_bf16 v[20:23], v[182:185], v[224:227], v[20:23]
	v_mfma_f32_16x16x32_bf16 v[16:19], v[200:203], v[224:227], v[16:19]
	v_mfma_f32_16x16x32_bf16 v[4:7], v[182:185], v[232:235], v[4:7]
	v_mfma_f32_16x16x32_bf16 v[0:3], v[200:203], v[232:235], v[0:3]
	s_setprio 0
	s_barrier
	s_add_i32 s70, s70, 2
	s_add_u32 s22, s22, 0x100
	s_addc_u32 s23, s23, 0
	s_add_u32 s68, s68, 0x100
	s_addc_u32 s69, s69, 0
	s_cmp_gt_u32 s70, 5

; __device__ __forceinline__ unsigned cvt_pk_bf16(float lo, float hi) { unsigned r; asm volatile("v_cvt_pk_bf16_f32 %0, %1, %2" : "=v"(r) : "v"(lo), "v"(hi)); return r; }
; __device__ __forceinline__ float sigmoidf_(float x) { return __builtin_amdgcn_rcpf(1.0f + __expf(-x)); }
;     __device__ __forceinline__ void operator()(const f32x4 (&acc)[2][2][4][2], const Unit& u, int wr, int wc, int fr, int fq) const {
;         asm volatile("" : "+v"(fr), "+v"(fq));
;         const int row0 = u.pm * BM + wr * 64 + fr, col0 = u.pn * BM + wc * 32 + 8 * fq;
; #pragma unroll
;         for (int ai = 0; ai < 2; ++ai)
; #pragma unroll
;             for (int m = 0; m < 4; ++m) { const size_t row = (size_t)(row0 + ai * HALF + m * 16);
; #pragma unroll
;                 for (int bj = 0; bj < 2; ++bj) { const int c = col0 + bj * HALF;
;                     const u32x4 yv = *(const u32x4*)(Y + row * ldy + c);
;                     const f32x4 v0 = acc[ai][bj][m][0], v1 = acc[ai][bj][m][1];
;                     u32x4 w;
;                     w.x = cvt_pk_bf16(bflo(yv.x) * sigmoidf_(v0[0]), bfhi(yv.x) * sigmoidf_(v0[1]));
;                     w.y = cvt_pk_bf16(bflo(yv.y) * sigmoidf_(v0[2]), bfhi(yv.y) * sigmoidf_(v0[3]));
;                     w.z = cvt_pk_bf16(bflo(yv.z) * sigmoidf_(v1[0]), bfhi(yv.z) * sigmoidf_(v1[1]));
;                     w.w = cvt_pk_bf16(bflo(yv.w) * sigmoidf_(v1[2]), bfhi(yv.w) * sigmoidf_(v1[3]));
;                     *(u32x4*)(O + row * ldc + ocol0 + c) = w; } }
;     }
.LBB0_398:
	s_lshl_b32 s13, s20, 8
	v_mov_b32_e32 v138, v142
	v_mov_b32_e32 v139, v143
	s_add_i32 s13, s13, s59
	s_nop 7
	s_nop 7
	v_mul_f32_e32 v124, 0xbfb8aa3b, v124
	v_add_u32_e32 v140, s13, v138
	s_lshl_b32 s13, s65, 8
	s_or_b32 s13, s13, s60
	v_lshl_add_u32 v138, v139, 3, s13
	v_ashrrev_i32_e32 v141, 31, v140
	v_lshlrev_b64 v[146:147], 10, v[140:141]
	v_ashrrev_i32_e32 v139, 31, v138
	v_lshl_add_u64 v[146:147], s[6:7], 0, v[146:147]
	v_lshlrev_b64 v[138:139], 1, v[138:139]
	v_lshl_add_u64 v[150:151], v[146:147], 0, v[138:139]
	global_load_dwordx4 v[146:149], v[150:151], off
	v_mul_f32_e32 v125, 0xbfb8aa3b, v125
	v_mul_f32_e32 v123, 0xbfb8aa3b, v123
	v_mul_f32_e32 v126, 0xbfb8aa3b, v126
	v_mul_f32_e32 v127, 0xbfb8aa3b, v127
	v_mul_f32_e32 v120, 0xbfb8aa3b, v120
	v_mul_f32_e32 v121, 0xbfb8aa3b, v121
	v_mul_f32_e32 v122, 0xbfb8aa3b, v122
	v_exp_f32_e32 v124, v124
	v_exp_f32_e32 v125, v125
	v_exp_f32_e32 v123, v123
	v_exp_f32_e32 v126, v126
	v_exp_f32_e32 v127, v127
	v_exp_f32_e32 v170, v120
	v_exp_f32_e32 v171, v121
	v_exp_f32_e32 v122, v122
	v_add_f32_e32 v124, 1.0, v124
	v_add_f32_e32 v125, 1.0, v125
	v_add_f32_e32 v123, 1.0, v123
	v_lshlrev_b64 v[120:121], 12, v[140:141]
	v_add_f32_e32 v126, 1.0, v126
	v_add_f32_e32 v127, 1.0, v127
	v_add_f32_e32 v141, 1.0, v170
	v_add_f32_e32 v170, 1.0, v171
	v_add_f32_e32 v122, 1.0, v122
	v_rcp_f32_e32 v171, v124
	v_rcp_f32_e32 v172, v125
	v_rcp_f32_e32 v123, v123
	v_rcp_f32_e32 v126, v126
	v_rcp_f32_e32 v127, v127
	v_rcp_f32_e32 v141, v141
	v_rcp_f32_e32 v170, v170
	v_rcp_f32_e32 v122, v122
	v_lshl_add_u64 v[120:121], s[8:9], 0, v[120:121]
	v_lshl_add_u64 v[124:125], v[120:121], 0, v[138:139]
	v_mul_f32_e32 v116, 0xbfb8aa3b, v116
	v_mul_f32_e32 v117, 0xbfb8aa3b, v117
	v_mul_f32_e32 v115, 0xbfb8aa3b, v115
	v_mul_f32_e32 v118, 0xbfb8aa3b, v118
	v_mul_f32_e32 v119, 0xbfb8aa3b, v119
	v_mul_f32_e32 v112, 0xbfb8aa3b, v112
	v_mul_f32_e32 v113, 0xbfb8aa3b, v113
	v_mul_f32_e32 v114, 0xbfb8aa3b, v114
	v_exp_f32_e32 v115, v115
	v_exp_f32_e32 v118, v118
	v_exp_f32_e32 v119, v119
	v_exp_f32_e32 v112, v112
	v_exp_f32_e32 v113, v113
	v_exp_f32_e32 v114, v114
	v_add_f32_e32 v115, 1.0, v115
	v_add_f32_e32 v118, 1.0, v118
	v_add_f32_e32 v119, 1.0, v119
	v_add_f32_e32 v114, 1.0, v114
	v_rcp_f32_e32 v115, v115
	v_rcp_f32_e32 v114, v114
	v_mul_f32_e32 v108, 0xbfb8aa3b, v108
	v_mul_f32_e32 v109, 0xbfb8aa3b, v109
	v_mul_f32_e32 v107, 0xbfb8aa3b, v107
	v_mul_f32_e32 v110, 0xbfb8aa3b, v110
	v_mul_f32_e32 v111, 0xbfb8aa3b, v111
	v_mul_f32_e32 v104, 0xbfb8aa3b, v104
	v_mul_f32_e32 v105, 0xbfb8aa3b, v105
	v_mul_f32_e32 v106, 0xbfb8aa3b, v106
	v_exp_f32_e32 v108, v108
	v_exp_f32_e32 v109, v109
	v_exp_f32_e32 v107, v107
	v_exp_f32_e32 v110, v110
	v_exp_f32_e32 v111, v111
	v_exp_f32_e32 v104, v104
	v_exp_f32_e32 v105, v105
	v_exp_f32_e32 v106, v106
	v_add_f32_e32 v108, 1.0, v108
	v_add_f32_e32 v109, 1.0, v109
	v_add_f32_e32 v107, 1.0, v107
	v_add_f32_e32 v110, 1.0, v110
	v_add_f32_e32 v111, 1.0, v111
	v_add_f32_e32 v106, 1.0, v106
	v_rcp_f32_e32 v107, v107
	v_rcp_f32_e32 v110, v110
	v_rcp_f32_e32 v111, v111
	s_waitcnt vmcnt(0)
	v_lshlrev_b32_e32 v120, 16, v146
	v_and_b32_e32 v121, 0xffff0000, v146
	v_lshlrev_b32_e32 v174, 16, v149
	v_and_b32_e32 v149, 0xffff0000, v149
	v_lshlrev_b32_e32 v146, 16, v147
	v_and_b32_e32 v147, 0xffff0000, v147
	v_lshlrev_b32_e32 v173, 16, v148
	v_and_b32_e32 v148, 0xffff0000, v148
	v_mul_f32_e32 v120, v171, v120
	v_mul_f32_e32 v121, v172, v121
	v_mul_f32_e32 v123, v123, v149
	v_mul_f32_e32 v126, v126, v146
	v_mul_f32_e32 v127, v127, v147
	v_mul_f32_e32 v141, v141, v173
	v_mul_f32_e32 v146, v170, v148
	v_mul_f32_e32 v147, v122, v174
	v_cvt_pk_bf16_f32 v120, v120, v121
	v_cvt_pk_bf16_f32 v121, v126, v127
	v_cvt_pk_bf16_f32 v122, v141, v146
	v_cvt_pk_bf16_f32 v123, v147, v123
	global_store_dwordx4 v[124:125], v[120:123], off offset:2048
	global_load_dwordx4 v[120:123], v[150:151], off offset:256
	v_exp_f32_e32 v126, v116
	v_exp_f32_e32 v127, v117
	v_add_u32_e32 v116, 16, v140
	v_ashrrev_i32_e32 v117, 31, v116
	v_add_f32_e32 v126, 1.0, v126
	v_add_f32_e32 v127, 1.0, v127
	v_add_f32_e32 v141, 1.0, v112
	v_add_f32_e32 v146, 1.0, v113
	v_rcp_f32_e32 v126, v126
	v_rcp_f32_e32 v127, v127
	v_lshlrev_b64 v[112:113], 10, v[116:117]
	v_rcp_f32_e32 v147, v118
	v_rcp_f32_e32 v148, v119
	v_rcp_f32_e32 v141, v141
	v_rcp_f32_e32 v146, v146
	v_lshl_add_u64 v[112:113], s[6:7], 0, v[112:113]
	v_lshl_add_u64 v[118:119], v[112:113], 0, v[138:139]
	v_rcp_f32_e32 v106, v106
	v_mul_f32_e32 v100, 0xbfb8aa3b, v100
	v_mul_f32_e32 v101, 0xbfb8aa3b, v101
	v_mul_f32_e32 v99, 0xbfb8aa3b, v99
	v_mul_f32_e32 v102, 0xbfb8aa3b, v102
	v_mul_f32_e32 v103, 0xbfb8aa3b, v103
	v_mul_f32_e32 v96, 0xbfb8aa3b, v96
	v_mul_f32_e32 v97, 0xbfb8aa3b, v97
	v_mul_f32_e32 v98, 0xbfb8aa3b, v98
	v_exp_f32_e32 v99, v99
	v_exp_f32_e32 v102, v102
	v_exp_f32_e32 v103, v103
	v_exp_f32_e32 v96, v96
	v_exp_f32_e32 v97, v97
	v_exp_f32_e32 v98, v98
	v_add_f32_e32 v99, 1.0, v99
	v_add_f32_e32 v102, 1.0, v102
	v_add_f32_e32 v103, 1.0, v103
	v_add_f32_e32 v98, 1.0, v98
	v_rcp_f32_e32 v99, v99
	v_rcp_f32_e32 v98, v98
	v_mul_f32_e32 v92, 0xbfb8aa3b, v92
	v_mul_f32_e32 v93, 0xbfb8aa3b, v93
	v_mul_f32_e32 v91, 0xbfb8aa3b, v91
	v_mul_f32_e32 v94, 0xbfb8aa3b, v94
	v_mul_f32_e32 v95, 0xbfb8aa3b, v95
	v_mul_f32_e32 v88, 0xbfb8aa3b, v88
	v_mul_f32_e32 v89, 0xbfb8aa3b, v89
	v_mul_f32_e32 v90, 0xbfb8aa3b, v90
	v_exp_f32_e32 v92, v92
	v_exp_f32_e32 v93, v93
	v_exp_f32_e32 v91, v91
	v_exp_f32_e32 v94, v94
	v_exp_f32_e32 v95, v95
	v_exp_f32_e32 v88, v88
	v_exp_f32_e32 v89, v89
	v_exp_f32_e32 v90, v90
	v_add_f32_e32 v92, 1.0, v92
	v_add_f32_e32 v93, 1.0, v93
	v_add_f32_e32 v91, 1.0, v91
	v_add_f32_e32 v94, 1.0, v94
	v_add_f32_e32 v95, 1.0, v95
	v_add_f32_e32 v90, 1.0, v90
	v_rcp_f32_e32 v91, v91
	v_rcp_f32_e32 v94, v94
	v_rcp_f32_e32 v95, v95
	v_rcp_f32_e32 v90, v90
	v_mul_f32_e32 v84, 0xbfb8aa3b, v84
	v_mul_f32_e32 v85, 0xbfb8aa3b, v85
	v_mul_f32_e32 v83, 0xbfb8aa3b, v83
	v_mul_f32_e32 v86, 0xbfb8aa3b, v86
	v_mul_f32_e32 v87, 0xbfb8aa3b, v87
	v_mul_f32_e32 v80, 0xbfb8aa3b, v80
	v_mul_f32_e32 v81, 0xbfb8aa3b, v81
	v_mul_f32_e32 v82, 0xbfb8aa3b, v82
	v_exp_f32_e32 v83, v83
	v_exp_f32_e32 v86, v86
	v_exp_f32_e32 v87, v87
	v_exp_f32_e32 v80, v80
	v_exp_f32_e32 v81, v81
	v_exp_f32_e32 v82, v82
	v_add_f32_e32 v83, 1.0, v83
	s_waitcnt vmcnt(0)
; __device__ __forceinline__ unsigned cvt_pk_bf16(float lo, float hi) { unsigned r; asm volatile("v_cvt_pk_bf16_f32 %0, %1, %2" : "=v"(r) : "v"(lo), "v"(hi)); return r; }
; __device__ __forceinline__ float sigmoidf_(float x) { return __builtin_amdgcn_rcpf(1.0f + __expf(-x)); }
;     __device__ __forceinline__ void operator()(const f32x4 (&acc)[2][2][4][2], const Unit& u, int wr, int wc, int fr, int fq) const {
;     ...
;             for (int m = 0; m < 4; ++m) { const size_t row = (size_t)(row0 + ai * HALF + m * 16);
; #pragma unroll
;                 for (int bj = 0; bj < 2; ++bj) { const int c = col0 + bj * HALF;
;                     const u32x4 yv = *(const u32x4*)(Y + row * ldy + c);
;                     const f32x4 v0 = acc[ai][bj][m][0], v1 = acc[ai][bj][m][1];
;                     u32x4 w;
;                     w.x = cvt_pk_bf16(bflo(yv.x) * sigmoidf_(v0[0]), bfhi(yv.x) * sigmoidf_(v0[1]));
;                     w.y = cvt_pk_bf16(bflo(yv.y) * sigmoidf_(v0[2]), bfhi(yv.y) * sigmoidf_(v0[3]));
;                     w.z = cvt_pk_bf16(bflo(yv.z) * sigmoidf_(v1[0]), bfhi(yv.z) * sigmoidf_(v1[1]));
;                     w.w = cvt_pk_bf16(bflo(yv.w) * sigmoidf_(v1[2]), bfhi(yv.w) * sigmoidf_(v1[3]));
;                     *(u32x4*)(O + row * ldc + ocol0 + c) = w; } }
	v_lshlrev_b32_e32 v112, 16, v120
	v_and_b32_e32 v113, 0xffff0000, v120
	v_lshlrev_b32_e32 v150, 16, v123
	v_and_b32_e32 v123, 0xffff0000, v123
	v_lshlrev_b32_e32 v120, 16, v121
	v_and_b32_e32 v121, 0xffff0000, v121
	v_lshlrev_b32_e32 v149, 16, v122
	v_and_b32_e32 v122, 0xffff0000, v122
	v_mul_f32_e32 v112, v126, v112
	v_mul_f32_e32 v113, v127, v113
	v_mul_f32_e32 v115, v115, v123
	v_mul_f32_e32 v120, v147, v120
	v_mul_f32_e32 v121, v148, v121
	v_mul_f32_e32 v126, v141, v149
	v_mul_f32_e32 v122, v146, v122
	v_mul_f32_e32 v127, v114, v150
	v_cvt_pk_bf16_f32 v112, v112, v113
	v_cvt_pk_bf16_f32 v113, v120, v121
	v_cvt_pk_bf16_f32 v114, v126, v122
	v_cvt_pk_bf16_f32 v115, v127, v115
	global_store_dwordx4 v[124:125], v[112:115], off offset:2304
	global_load_dwordx4 v[112:115], v[118:119], off
	global_load_dwordx4 v[172:175], v[118:119], off offset:256
	v_add_u32_e32 v170, 32, v140
	v_ashrrev_i32_e32 v171, 31, v170
	v_lshlrev_b64 v[170:171], 10, v[170:171]
	v_lshl_add_u64 v[170:171], s[6:7], 0, v[170:171]
	v_lshl_add_u64 v[170:171], v[170:171], 0, v[138:139]
	global_load_dwordx4 v[176:179], v[170:171], off
	global_load_dwordx4 v[180:183], v[170:171], off offset:256
	v_add_u32_e32 v170, 48, v140
	v_ashrrev_i32_e32 v171, 31, v170
	v_lshlrev_b64 v[170:171], 10, v[170:171]
	v_lshl_add_u64 v[170:171], s[6:7], 0, v[170:171]
	v_lshl_add_u64 v[170:171], v[170:171], 0, v[138:139]
	global_load_dwordx4 v[184:187], v[170:171], off
	global_load_dwordx4 v[188:191], v[170:171], off offset:256
	v_add_u32_e32 v170, 0x80, v140
	v_ashrrev_i32_e32 v171, 31, v170
	v_lshlrev_b64 v[170:171], 10, v[170:171]
	v_lshl_add_u64 v[170:171], s[6:7], 0, v[170:171]
	v_lshl_add_u64 v[170:171], v[170:171], 0, v[138:139]
	global_load_dwordx4 v[200:203], v[170:171], off
	global_load_dwordx4 v[204:207], v[170:171], off offset:256
	v_add_u32_e32 v170, 0x90, v140
	v_ashrrev_i32_e32 v171, 31, v170
	v_lshlrev_b64 v[170:171], 10, v[170:171]
	v_lshl_add_u64 v[170:171], s[6:7], 0, v[170:171]
	v_lshl_add_u64 v[170:171], v[170:171], 0, v[138:139]
	global_load_dwordx4 v[208:211], v[170:171], off
	global_load_dwordx4 v[212:215], v[170:171], off offset:256
	v_add_u32_e32 v170, 0xa0, v140
	v_ashrrev_i32_e32 v171, 31, v170
	v_lshlrev_b64 v[170:171], 10, v[170:171]
	v_lshl_add_u64 v[170:171], s[6:7], 0, v[170:171]
	v_lshl_add_u64 v[170:171], v[170:171], 0, v[138:139]
	global_load_dwordx4 v[216:219], v[170:171], off
	global_load_dwordx4 v[220:223], v[170:171], off offset:256
	v_add_u32_e32 v170, 0xb0, v140
	v_ashrrev_i32_e32 v171, 31, v170
	v_lshlrev_b64 v[170:171], 10, v[170:171]
	v_lshl_add_u64 v[170:171], s[6:7], 0, v[170:171]
	v_lshl_add_u64 v[170:171], v[170:171], 0, v[138:139]
	global_load_dwordx4 v[224:227], v[170:171], off
	global_load_dwordx4 v[228:231], v[170:171], off offset:256
	v_add_f32_e32 v120, 1.0, v104
	v_add_f32_e32 v121, 1.0, v105
	v_lshlrev_b64 v[104:105], 12, v[116:117]
	v_rcp_f32_e32 v116, v108
	v_rcp_f32_e32 v117, v109
	v_rcp_f32_e32 v120, v120
	v_rcp_f32_e32 v121, v121
	v_lshl_add_u64 v[104:105], s[8:9], 0, v[104:105]
	v_lshl_add_u64 v[108:109], v[104:105], 0, v[138:139]
	v_add_f32_e32 v86, 1.0, v86
	v_add_f32_e32 v87, 1.0, v87
	v_add_f32_e32 v82, 1.0, v82
	v_rcp_f32_e32 v83, v83
	v_rcp_f32_e32 v82, v82
	v_mul_f32_e32 v76, 0xbfb8aa3b, v76
	v_mul_f32_e32 v77, 0xbfb8aa3b, v77
	v_mul_f32_e32 v75, 0xbfb8aa3b, v75
	v_mul_f32_e32 v78, 0xbfb8aa3b, v78
	v_mul_f32_e32 v79, 0xbfb8aa3b, v79
	v_mul_f32_e32 v72, 0xbfb8aa3b, v72
	v_mul_f32_e32 v73, 0xbfb8aa3b, v73
	v_mul_f32_e32 v74, 0xbfb8aa3b, v74
	v_exp_f32_e32 v76, v76
	v_exp_f32_e32 v77, v77
	v_exp_f32_e32 v75, v75
	v_exp_f32_e32 v78, v78
	v_exp_f32_e32 v79, v79
	v_exp_f32_e32 v72, v72
	v_exp_f32_e32 v73, v73
	v_exp_f32_e32 v74, v74
	v_add_f32_e32 v76, 1.0, v76
	v_add_f32_e32 v77, 1.0, v77
	v_add_f32_e32 v75, 1.0, v75
	v_add_f32_e32 v78, 1.0, v78
	v_add_f32_e32 v79, 1.0, v79
	v_add_f32_e32 v74, 1.0, v74
	v_rcp_f32_e32 v75, v75
	v_rcp_f32_e32 v78, v78
	v_rcp_f32_e32 v79, v79
	v_rcp_f32_e32 v74, v74
	v_mul_f32_e32 v68, 0xbfb8aa3b, v68
	v_mul_f32_e32 v69, 0xbfb8aa3b, v69
	v_mul_f32_e32 v67, 0xbfb8aa3b, v67
	v_mul_f32_e32 v70, 0xbfb8aa3b, v70
	v_mul_f32_e32 v71, 0xbfb8aa3b, v71
	v_mul_f32_e32 v64, 0xbfb8aa3b, v64
	v_mul_f32_e32 v65, 0xbfb8aa3b, v65
	v_mul_f32_e32 v66, 0xbfb8aa3b, v66
	v_exp_f32_e32 v67, v67
	v_exp_f32_e32 v70, v70
	v_exp_f32_e32 v71, v71
	v_exp_f32_e32 v64, v64
	v_exp_f32_e32 v65, v65
	v_exp_f32_e32 v66, v66
	v_add_f32_e32 v67, 1.0, v67
	v_add_f32_e32 v70, 1.0, v70
	v_add_f32_e32 v71, 1.0, v71
	v_add_f32_e32 v66, 1.0, v66
	v_rcp_f32_e32 v67, v67
	v_rcp_f32_e32 v66, v66
	v_mul_f32_e32 v60, 0xbfb8aa3b, v60
	v_mul_f32_e32 v61, 0xbfb8aa3b, v61
	v_mul_f32_e32 v59, 0xbfb8aa3b, v59
	v_mul_f32_e32 v62, 0xbfb8aa3b, v62
	v_mul_f32_e32 v63, 0xbfb8aa3b, v63
	v_mul_f32_e32 v56, 0xbfb8aa3b, v56
	v_mul_f32_e32 v57, 0xbfb8aa3b, v57
	v_mul_f32_e32 v58, 0xbfb8aa3b, v58
	v_exp_f32_e32 v60, v60
	v_exp_f32_e32 v61, v61
	v_exp_f32_e32 v59, v59
	v_exp_f32_e32 v62, v62
	v_exp_f32_e32 v63, v63
	v_exp_f32_e32 v56, v56
	v_exp_f32_e32 v57, v57
	v_exp_f32_e32 v58, v58
	v_add_f32_e32 v60, 1.0, v60
	v_add_f32_e32 v61, 1.0, v61
	v_add_f32_e32 v59, 1.0, v59
	s_waitcnt vmcnt(13)
; __device__ __forceinline__ unsigned cvt_pk_bf16(float lo, float hi) { unsigned r; asm volatile("v_cvt_pk_bf16_f32 %0, %1, %2" : "=v"(r) : "v"(lo), "v"(hi)); return r; }
; __device__ __forceinline__ float sigmoidf_(float x) { return __builtin_amdgcn_rcpf(1.0f + __expf(-x)); }
;     __device__ __forceinline__ void operator()(const f32x4 (&acc)[2][2][4][2], const Unit& u, int wr, int wc, int fr, int fq) const {
;     ...
;             for (int m = 0; m < 4; ++m) { const size_t row = (size_t)(row0 + ai * HALF + m * 16);
; #pragma unroll
;                 for (int bj = 0; bj < 2; ++bj) { const int c = col0 + bj * HALF;
;                     const u32x4 yv = *(const u32x4*)(Y + row * ldy + c);
;                     const f32x4 v0 = acc[ai][bj][m][0], v1 = acc[ai][bj][m][1];
;                     u32x4 w;
;                     w.x = cvt_pk_bf16(bflo(yv.x) * sigmoidf_(v0[0]), bfhi(yv.x) * sigmoidf_(v0[1]));
;                     w.y = cvt_pk_bf16(bflo(yv.y) * sigmoidf_(v0[2]), bfhi(yv.y) * sigmoidf_(v0[3]));
;                     w.z = cvt_pk_bf16(bflo(yv.z) * sigmoidf_(v1[0]), bfhi(yv.z) * sigmoidf_(v1[1]));
;                     w.w = cvt_pk_bf16(bflo(yv.w) * sigmoidf_(v1[2]), bfhi(yv.w) * sigmoidf_(v1[3]));
;                     *(u32x4*)(O + row * ldc + ocol0 + c) = w; } }
	v_lshlrev_b32_e32 v104, 16, v112
	v_and_b32_e32 v105, 0xffff0000, v112
	v_lshlrev_b32_e32 v123, 16, v115
	v_and_b32_e32 v115, 0xffff0000, v115
	v_lshlrev_b32_e32 v112, 16, v113
	v_and_b32_e32 v113, 0xffff0000, v113
	v_lshlrev_b32_e32 v122, 16, v114
	v_and_b32_e32 v114, 0xffff0000, v114
	v_mul_f32_e32 v104, v116, v104
	v_mul_f32_e32 v105, v117, v105
	v_mul_f32_e32 v107, v107, v115
	v_mul_f32_e32 v110, v110, v112
	v_mul_f32_e32 v111, v111, v113
	v_mul_f32_e32 v112, v120, v122
	v_mul_f32_e32 v113, v121, v114
	v_mul_f32_e32 v114, v106, v123
	v_cvt_pk_bf16_f32 v104, v104, v105
	v_cvt_pk_bf16_f32 v105, v110, v111
	v_cvt_pk_bf16_f32 v106, v112, v113
	v_cvt_pk_bf16_f32 v107, v114, v107
	global_store_dwordx4 v[108:109], v[104:107], off offset:2048
	v_exp_f32_e32 v110, v100
	v_exp_f32_e32 v111, v101
	v_add_u32_e32 v100, 32, v140
	v_ashrrev_i32_e32 v101, 31, v100
	v_add_f32_e32 v110, 1.0, v110
	v_add_f32_e32 v111, 1.0, v111
	v_add_f32_e32 v112, 1.0, v96
	v_add_f32_e32 v113, 1.0, v97
	v_rcp_f32_e32 v110, v110
	v_rcp_f32_e32 v111, v111
	v_lshlrev_b64 v[96:97], 10, v[100:101]
	v_rcp_f32_e32 v114, v102
	v_rcp_f32_e32 v115, v103
	v_rcp_f32_e32 v112, v112
	v_rcp_f32_e32 v113, v113
	v_lshl_add_u64 v[96:97], s[6:7], 0, v[96:97]
	v_lshl_add_u64 v[102:103], v[96:97], 0, v[138:139]
	v_add_f32_e32 v62, 1.0, v62
	v_add_f32_e32 v63, 1.0, v63
	v_add_f32_e32 v58, 1.0, v58
	v_rcp_f32_e32 v59, v59
	v_rcp_f32_e32 v62, v62
	v_rcp_f32_e32 v63, v63
	v_rcp_f32_e32 v58, v58
	v_mul_f32_e32 v52, 0xbfb8aa3b, v52
	v_mul_f32_e32 v53, 0xbfb8aa3b, v53
	v_mul_f32_e32 v51, 0xbfb8aa3b, v51
	v_mul_f32_e32 v54, 0xbfb8aa3b, v54
	v_mul_f32_e32 v55, 0xbfb8aa3b, v55
	v_mul_f32_e32 v48, 0xbfb8aa3b, v48
	v_mul_f32_e32 v49, 0xbfb8aa3b, v49
	v_mul_f32_e32 v50, 0xbfb8aa3b, v50
	v_exp_f32_e32 v51, v51
	v_exp_f32_e32 v54, v54
	v_exp_f32_e32 v55, v55
	v_exp_f32_e32 v48, v48
	v_exp_f32_e32 v49, v49
	v_exp_f32_e32 v50, v50
	v_add_f32_e32 v51, 1.0, v51
	v_add_f32_e32 v54, 1.0, v54
	v_add_f32_e32 v55, 1.0, v55
	v_add_f32_e32 v50, 1.0, v50
	v_rcp_f32_e32 v51, v51
	v_rcp_f32_e32 v50, v50
	v_mul_f32_e32 v44, 0xbfb8aa3b, v44
	v_mul_f32_e32 v45, 0xbfb8aa3b, v45
	v_mul_f32_e32 v43, 0xbfb8aa3b, v43
	v_mul_f32_e32 v46, 0xbfb8aa3b, v46
	v_mul_f32_e32 v47, 0xbfb8aa3b, v47
	v_mul_f32_e32 v40, 0xbfb8aa3b, v40
	v_mul_f32_e32 v41, 0xbfb8aa3b, v41
	v_mul_f32_e32 v42, 0xbfb8aa3b, v42
	v_exp_f32_e32 v44, v44
	v_exp_f32_e32 v45, v45
	v_exp_f32_e32 v43, v43
	v_exp_f32_e32 v46, v46
	v_exp_f32_e32 v47, v47
	v_exp_f32_e32 v40, v40
	v_exp_f32_e32 v41, v41
	v_exp_f32_e32 v42, v42
	v_add_f32_e32 v44, 1.0, v44
	v_add_f32_e32 v45, 1.0, v45
	v_add_f32_e32 v43, 1.0, v43
	v_add_f32_e32 v46, 1.0, v46
	v_add_f32_e32 v47, 1.0, v47
	v_add_f32_e32 v42, 1.0, v42
	v_rcp_f32_e32 v43, v43
	v_rcp_f32_e32 v46, v46
	v_rcp_f32_e32 v47, v47
	v_rcp_f32_e32 v42, v42
	v_mul_f32_e32 v36, 0xbfb8aa3b, v36
	v_mul_f32_e32 v37, 0xbfb8aa3b, v37
	v_mul_f32_e32 v35, 0xbfb8aa3b, v35
	v_mul_f32_e32 v38, 0xbfb8aa3b, v38
	v_mul_f32_e32 v39, 0xbfb8aa3b, v39
	v_mul_f32_e32 v32, 0xbfb8aa3b, v32
	v_mul_f32_e32 v33, 0xbfb8aa3b, v33
	v_mul_f32_e32 v34, 0xbfb8aa3b, v34
	v_exp_f32_e32 v35, v35
	s_waitcnt vmcnt(13)
	s_nop 1
	v_mov_b64_e32 v[104:105], v[172:173]
	v_mov_b64_e32 v[106:107], v[174:175]
	v_lshlrev_b32_e32 v96, 16, v104
	v_and_b32_e32 v97, 0xffff0000, v104
	v_lshlrev_b32_e32 v117, 16, v107
	v_and_b32_e32 v107, 0xffff0000, v107
	v_lshlrev_b32_e32 v104, 16, v105
	v_and_b32_e32 v105, 0xffff0000, v105
	v_lshlrev_b32_e32 v116, 16, v106
	v_and_b32_e32 v106, 0xffff0000, v106
	v_mul_f32_e32 v96, v110, v96
	v_mul_f32_e32 v97, v111, v97
	v_mul_f32_e32 v99, v99, v107
	v_mul_f32_e32 v104, v114, v104
	v_mul_f32_e32 v105, v115, v105
	v_mul_f32_e32 v110, v112, v116
	v_mul_f32_e32 v106, v113, v106
	v_mul_f32_e32 v111, v98, v117
	v_cvt_pk_bf16_f32 v96, v96, v97
	v_cvt_pk_bf16_f32 v97, v104, v105
	v_cvt_pk_bf16_f32 v98, v110, v106
	v_cvt_pk_bf16_f32 v99, v111, v99
	global_store_dwordx4 v[108:109], v[96:99], off offset:2304
	v_add_f32_e32 v104, 1.0, v88
	v_add_f32_e32 v105, 1.0, v89
	v_lshlrev_b64 v[88:89], 12, v[100:101]
	v_rcp_f32_e32 v100, v92
	v_rcp_f32_e32 v101, v93
	v_rcp_f32_e32 v104, v104
	v_rcp_f32_e32 v105, v105
	v_lshl_add_u64 v[88:89], s[8:9], 0, v[88:89]
	v_lshl_add_u64 v[92:93], v[88:89], 0, v[138:139]
	v_exp_f32_e32 v38, v38
	v_exp_f32_e32 v39, v39
	v_exp_f32_e32 v32, v32
	v_exp_f32_e32 v33, v33
	v_exp_f32_e32 v34, v34
	v_add_f32_e32 v35, 1.0, v35
	v_add_f32_e32 v38, 1.0, v38
	v_add_f32_e32 v39, 1.0, v39
	v_add_f32_e32 v34, 1.0, v34
	v_rcp_f32_e32 v35, v35
	v_rcp_f32_e32 v34, v34
	v_mul_f32_e32 v28, 0xbfb8aa3b, v28
	v_mul_f32_e32 v29, 0xbfb8aa3b, v29
	v_mul_f32_e32 v27, 0xbfb8aa3b, v27
	v_mul_f32_e32 v30, 0xbfb8aa3b, v30
	v_mul_f32_e32 v31, 0xbfb8aa3b, v31
	v_mul_f32_e32 v24, 0xbfb8aa3b, v24
	v_mul_f32_e32 v25, 0xbfb8aa3b, v25
	v_mul_f32_e32 v26, 0xbfb8aa3b, v26
	v_exp_f32_e32 v28, v28
	v_exp_f32_e32 v29, v29
	v_exp_f32_e32 v27, v27
	v_exp_f32_e32 v30, v30
	v_exp_f32_e32 v31, v31
	v_exp_f32_e32 v24, v24
	v_exp_f32_e32 v25, v25
	v_exp_f32_e32 v26, v26
	v_add_f32_e32 v28, 1.0, v28
	v_add_f32_e32 v29, 1.0, v29
	v_add_f32_e32 v27, 1.0, v27
	v_add_f32_e32 v30, 1.0, v30
	v_add_f32_e32 v31, 1.0, v31
	v_add_f32_e32 v26, 1.0, v26
	v_rcp_f32_e32 v27, v27
	v_rcp_f32_e32 v30, v30
	v_rcp_f32_e32 v31, v31
	v_rcp_f32_e32 v26, v26
	v_mul_f32_e32 v20, 0xbfb8aa3b, v20
	v_mul_f32_e32 v21, 0xbfb8aa3b, v21
	v_mul_f32_e32 v19, 0xbfb8aa3b, v19
	v_mul_f32_e32 v22, 0xbfb8aa3b, v22
	v_mul_f32_e32 v23, 0xbfb8aa3b, v23
	v_mul_f32_e32 v16, 0xbfb8aa3b, v16
	v_mul_f32_e32 v17, 0xbfb8aa3b, v17
	v_mul_f32_e32 v18, 0xbfb8aa3b, v18
	v_exp_f32_e32 v19, v19
	v_exp_f32_e32 v22, v22
	v_exp_f32_e32 v23, v23
	v_exp_f32_e32 v16, v16
	v_exp_f32_e32 v17, v17
	v_exp_f32_e32 v18, v18
	v_add_f32_e32 v19, 1.0, v19
	v_add_f32_e32 v22, 1.0, v22
	v_add_f32_e32 v23, 1.0, v23
	v_add_f32_e32 v18, 1.0, v18
	v_rcp_f32_e32 v19, v19
	v_rcp_f32_e32 v18, v18
	v_mul_f32_e32 v12, 0xbfb8aa3b, v12
	v_mul_f32_e32 v13, 0xbfb8aa3b, v13
	v_mul_f32_e32 v11, 0xbfb8aa3b, v11
	v_mul_f32_e32 v14, 0xbfb8aa3b, v14
	v_mul_f32_e32 v15, 0xbfb8aa3b, v15
	v_mul_f32_e32 v8, 0xbfb8aa3b, v8
	v_mul_f32_e32 v9, 0xbfb8aa3b, v9
	v_mul_f32_e32 v10, 0xbfb8aa3b, v10
	v_exp_f32_e32 v12, v12
	v_exp_f32_e32 v13, v13
	v_exp_f32_e32 v11, v11
	v_exp_f32_e32 v14, v14
	v_exp_f32_e32 v15, v15
	s_waitcnt vmcnt(13)
; __device__ __forceinline__ unsigned cvt_pk_bf16(float lo, float hi) { unsigned r; asm volatile("v_cvt_pk_bf16_f32 %0, %1, %2" : "=v"(r) : "v"(lo), "v"(hi)); return r; }
; __device__ __forceinline__ float sigmoidf_(float x) { return __builtin_amdgcn_rcpf(1.0f + __expf(-x)); }
;     __device__ __forceinline__ void operator()(const f32x4 (&acc)[2][2][4][2], const Unit& u, int wr, int wc, int fr, int fq) const {
;     ...
;             for (int m = 0; m < 4; ++m) { const size_t row = (size_t)(row0 + ai * HALF + m * 16);
; #pragma unroll
;                 for (int bj = 0; bj < 2; ++bj) { const int c = col0 + bj * HALF;
;                     const u32x4 yv = *(const u32x4*)(Y + row * ldy + c);
;                     const f32x4 v0 = acc[ai][bj][m][0], v1 = acc[ai][bj][m][1];
;                     u32x4 w;
;                     w.x = cvt_pk_bf16(bflo(yv.x) * sigmoidf_(v0[0]), bfhi(yv.x) * sigmoidf_(v0[1]));
;                     w.y = cvt_pk_bf16(bflo(yv.y) * sigmoidf_(v0[2]), bfhi(yv.y) * sigmoidf_(v0[3]));
;                     w.z = cvt_pk_bf16(bflo(yv.z) * sigmoidf_(v1[0]), bfhi(yv.z) * sigmoidf_(v1[1]));
;                     w.w = cvt_pk_bf16(bflo(yv.w) * sigmoidf_(v1[2]), bfhi(yv.w) * sigmoidf_(v1[3]));
;                     *(u32x4*)(O + row * ldc + ocol0 + c) = w; } }
	s_nop 1
	v_mov_b64_e32 v[96:97], v[176:177]
	v_mov_b64_e32 v[98:99], v[178:179]
	v_lshlrev_b32_e32 v88, 16, v96
	v_and_b32_e32 v89, 0xffff0000, v96
	v_lshlrev_b32_e32 v107, 16, v99
	v_and_b32_e32 v99, 0xffff0000, v99
	v_lshlrev_b32_e32 v96, 16, v97
	v_and_b32_e32 v97, 0xffff0000, v97
	v_lshlrev_b32_e32 v106, 16, v98
	v_and_b32_e32 v98, 0xffff0000, v98
	v_mul_f32_e32 v88, v100, v88
	v_mul_f32_e32 v89, v101, v89
	v_mul_f32_e32 v91, v91, v99
	v_mul_f32_e32 v94, v94, v96
	v_mul_f32_e32 v95, v95, v97
	v_mul_f32_e32 v96, v104, v106
	v_mul_f32_e32 v97, v105, v98
	v_mul_f32_e32 v98, v90, v107
	v_cvt_pk_bf16_f32 v88, v88, v89
	v_cvt_pk_bf16_f32 v89, v94, v95
	v_cvt_pk_bf16_f32 v90, v96, v97
	v_cvt_pk_bf16_f32 v91, v98, v91
	global_store_dwordx4 v[92:93], v[88:91], off offset:2048
	v_exp_f32_e32 v94, v84
	v_exp_f32_e32 v95, v85
	v_add_u32_e32 v84, 48, v140
	v_ashrrev_i32_e32 v85, 31, v84
	v_add_f32_e32 v94, 1.0, v94
	v_add_f32_e32 v95, 1.0, v95
	v_add_f32_e32 v96, 1.0, v80
	v_add_f32_e32 v97, 1.0, v81
	v_rcp_f32_e32 v94, v94
	v_rcp_f32_e32 v95, v95
	v_lshlrev_b64 v[80:81], 10, v[84:85]
	v_rcp_f32_e32 v98, v86
	v_rcp_f32_e32 v99, v87
	v_rcp_f32_e32 v96, v96
	v_rcp_f32_e32 v97, v97
	v_lshl_add_u64 v[80:81], s[6:7], 0, v[80:81]
	v_lshl_add_u64 v[86:87], v[80:81], 0, v[138:139]
	v_exp_f32_e32 v8, v8
	v_exp_f32_e32 v9, v9
	v_exp_f32_e32 v10, v10
	v_add_f32_e32 v12, 1.0, v12
	v_add_f32_e32 v13, 1.0, v13
	v_add_f32_e32 v11, 1.0, v11
	v_add_f32_e32 v14, 1.0, v14
	v_add_f32_e32 v15, 1.0, v15
	v_add_f32_e32 v10, 1.0, v10
	v_rcp_f32_e32 v11, v11
	v_rcp_f32_e32 v14, v14
	v_rcp_f32_e32 v15, v15
	v_rcp_f32_e32 v10, v10
	v_mul_f32_e32 v3, 0xbfb8aa3b, v3
	v_mul_f32_e32 v4, 0xbfb8aa3b, v4
	v_mul_f32_e32 v5, 0xbfb8aa3b, v5
	v_mul_f32_e32 v6, 0xbfb8aa3b, v6
	v_mul_f32_e32 v7, 0xbfb8aa3b, v7
	v_mul_f32_e32 v0, 0xbfb8aa3b, v0
	v_mul_f32_e32 v1, 0xbfb8aa3b, v1
	v_mul_f32_e32 v2, 0xbfb8aa3b, v2
	v_exp_f32_e32 v3, v3
	v_exp_f32_e32 v4, v4
	v_exp_f32_e32 v5, v5
	v_exp_f32_e32 v6, v6
	v_exp_f32_e32 v7, v7
	v_exp_f32_e32 v0, v0
	v_exp_f32_e32 v1, v1
	v_exp_f32_e32 v2, v2
	v_add_f32_e32 v3, 1.0, v3
	v_add_f32_e32 v4, 1.0, v4
	v_add_f32_e32 v5, 1.0, v5
	v_add_f32_e32 v6, 1.0, v6
	v_add_f32_e32 v7, 1.0, v7
	v_add_f32_e32 v0, 1.0, v0
	v_add_f32_e32 v1, 1.0, v1
	v_add_f32_e32 v2, 1.0, v2
	v_rcp_f32_e32 v3, v3
	v_rcp_f32_e32 v4, v4
	v_rcp_f32_e32 v5, v5
	v_rcp_f32_e32 v6, v6
	v_rcp_f32_e32 v7, v7
	v_rcp_f32_e32 v0, v0
	v_rcp_f32_e32 v1, v1
	v_rcp_f32_e32 v2, v2
	s_andn2_b64 vcc, exec, s[0:1]
	s_mov_b64 s[0:1], -1
	s_waitcnt vmcnt(13)
	s_nop 1
	v_mov_b64_e32 v[88:89], v[180:181]
	v_mov_b64_e32 v[90:91], v[182:183]
	v_lshlrev_b32_e32 v80, 16, v88
	v_and_b32_e32 v81, 0xffff0000, v88
	v_lshlrev_b32_e32 v101, 16, v91
	v_and_b32_e32 v91, 0xffff0000, v91
	v_lshlrev_b32_e32 v88, 16, v89
	v_and_b32_e32 v89, 0xffff0000, v89
	v_lshlrev_b32_e32 v100, 16, v90
	v_and_b32_e32 v90, 0xffff0000, v90
	v_mul_f32_e32 v80, v94, v80
	v_mul_f32_e32 v81, v95, v81
	v_mul_f32_e32 v83, v83, v91
	v_mul_f32_e32 v88, v98, v88
	v_mul_f32_e32 v89, v99, v89
	v_mul_f32_e32 v94, v96, v100
	v_mul_f32_e32 v90, v97, v90
	v_mul_f32_e32 v95, v82, v101
	v_cvt_pk_bf16_f32 v80, v80, v81
	v_cvt_pk_bf16_f32 v81, v88, v89
	v_cvt_pk_bf16_f32 v82, v94, v90
	v_cvt_pk_bf16_f32 v83, v95, v83
	global_store_dwordx4 v[92:93], v[80:83], off offset:2304
	v_add_f32_e32 v88, 1.0, v72
	v_add_f32_e32 v89, 1.0, v73
	v_lshlrev_b64 v[72:73], 12, v[84:85]
	v_rcp_f32_e32 v84, v76
	v_rcp_f32_e32 v85, v77
	v_rcp_f32_e32 v88, v88
	v_rcp_f32_e32 v89, v89
	v_lshl_add_u64 v[72:73], s[8:9], 0, v[72:73]
	v_lshl_add_u64 v[76:77], v[72:73], 0, v[138:139]
	s_waitcnt vmcnt(13)
	s_nop 1
	v_mov_b64_e32 v[80:81], v[184:185]
	v_mov_b64_e32 v[82:83], v[186:187]
	v_lshlrev_b32_e32 v72, 16, v80
	v_and_b32_e32 v73, 0xffff0000, v80
	v_lshlrev_b32_e32 v91, 16, v83
	v_and_b32_e32 v83, 0xffff0000, v83
	v_lshlrev_b32_e32 v80, 16, v81
	v_and_b32_e32 v81, 0xffff0000, v81
	v_lshlrev_b32_e32 v90, 16, v82
	v_and_b32_e32 v82, 0xffff0000, v82
	v_mul_f32_e32 v72, v84, v72
	v_mul_f32_e32 v73, v85, v73
	v_mul_f32_e32 v75, v75, v83
	v_mul_f32_e32 v78, v78, v80
	v_mul_f32_e32 v79, v79, v81
	v_mul_f32_e32 v80, v88, v90
	v_mul_f32_e32 v81, v89, v82
	v_mul_f32_e32 v82, v74, v91
	v_cvt_pk_bf16_f32 v72, v72, v73
	v_cvt_pk_bf16_f32 v73, v78, v79
	v_cvt_pk_bf16_f32 v74, v80, v81
	v_cvt_pk_bf16_f32 v75, v82, v75
	global_store_dwordx4 v[76:77], v[72:75], off offset:2048
	v_exp_f32_e32 v78, v68
	v_exp_f32_e32 v79, v69
	v_add_u32_e32 v68, 0x80, v140
	v_ashrrev_i32_e32 v69, 31, v68
	v_add_f32_e32 v78, 1.0, v78
	v_add_f32_e32 v79, 1.0, v79
	v_add_f32_e32 v80, 1.0, v64
	v_add_f32_e32 v81, 1.0, v65
	v_rcp_f32_e32 v78, v78
	v_rcp_f32_e32 v79, v79
	v_lshlrev_b64 v[64:65], 10, v[68:69]
	v_rcp_f32_e32 v82, v70
	v_rcp_f32_e32 v83, v71
	v_rcp_f32_e32 v80, v80
	v_rcp_f32_e32 v81, v81
	v_lshl_add_u64 v[64:65], s[6:7], 0, v[64:65]
	v_lshl_add_u64 v[70:71], v[64:65], 0, v[138:139]
	s_waitcnt vmcnt(13)
	s_nop 1
	v_mov_b64_e32 v[72:73], v[188:189]
	v_mov_b64_e32 v[74:75], v[190:191]
	v_lshlrev_b32_e32 v64, 16, v72
	v_and_b32_e32 v65, 0xffff0000, v72
	v_lshlrev_b32_e32 v85, 16, v75
	v_and_b32_e32 v75, 0xffff0000, v75
	v_lshlrev_b32_e32 v72, 16, v73
	v_and_b32_e32 v73, 0xffff0000, v73
	v_lshlrev_b32_e32 v84, 16, v74
	v_and_b32_e32 v74, 0xffff0000, v74
	v_mul_f32_e32 v64, v78, v64
	v_mul_f32_e32 v65, v79, v65
	v_mul_f32_e32 v67, v67, v75
	v_mul_f32_e32 v72, v82, v72
	v_mul_f32_e32 v73, v83, v73
	v_mul_f32_e32 v78, v80, v84
	v_mul_f32_e32 v74, v81, v74
	v_mul_f32_e32 v79, v66, v85
	v_cvt_pk_bf16_f32 v64, v64, v65
	v_cvt_pk_bf16_f32 v65, v72, v73
	v_cvt_pk_bf16_f32 v66, v78, v74
	v_cvt_pk_bf16_f32 v67, v79, v67
	global_store_dwordx4 v[76:77], v[64:67], off offset:2304
	v_add_f32_e32 v72, 1.0, v56
	v_add_f32_e32 v73, 1.0, v57
	v_lshlrev_b64 v[56:57], 12, v[68:69]
	v_rcp_f32_e32 v68, v60
	v_rcp_f32_e32 v69, v61
	v_rcp_f32_e32 v72, v72
	v_rcp_f32_e32 v73, v73
	v_lshl_add_u64 v[56:57], s[8:9], 0, v[56:57]
	v_lshl_add_u64 v[60:61], v[56:57], 0, v[138:139]
	s_waitcnt vmcnt(13)
; __device__ __forceinline__ unsigned cvt_pk_bf16(float lo, float hi) { unsigned r; asm volatile("v_cvt_pk_bf16_f32 %0, %1, %2" : "=v"(r) : "v"(lo), "v"(hi)); return r; }
; __device__ __forceinline__ float sigmoidf_(float x) { return __builtin_amdgcn_rcpf(1.0f + __expf(-x)); }
;     __device__ __forceinline__ void operator()(const f32x4 (&acc)[2][2][4][2], const Unit& u, int wr, int wc, int fr, int fq) const {
;     ...
;             for (int m = 0; m < 4; ++m) { const size_t row = (size_t)(row0 + ai * HALF + m * 16);
; #pragma unroll
;                 for (int bj = 0; bj < 2; ++bj) { const int c = col0 + bj * HALF;
;                     const u32x4 yv = *(const u32x4*)(Y + row * ldy + c);
;                     const f32x4 v0 = acc[ai][bj][m][0], v1 = acc[ai][bj][m][1];
;                     u32x4 w;
;                     w.x = cvt_pk_bf16(bflo(yv.x) * sigmoidf_(v0[0]), bfhi(yv.x) * sigmoidf_(v0[1]));
;                     w.y = cvt_pk_bf16(bflo(yv.y) * sigmoidf_(v0[2]), bfhi(yv.y) * sigmoidf_(v0[3]));
;                     w.z = cvt_pk_bf16(bflo(yv.z) * sigmoidf_(v1[0]), bfhi(yv.z) * sigmoidf_(v1[1]));
;                     w.w = cvt_pk_bf16(bflo(yv.w) * sigmoidf_(v1[2]), bfhi(yv.w) * sigmoidf_(v1[3]));
;                     *(u32x4*)(O + row * ldc + ocol0 + c) = w; } }
	s_nop 1
	v_mov_b64_e32 v[64:65], v[200:201]
	v_mov_b64_e32 v[66:67], v[202:203]
	v_lshlrev_b32_e32 v56, 16, v64
	v_and_b32_e32 v57, 0xffff0000, v64
	v_lshlrev_b32_e32 v75, 16, v67
	v_and_b32_e32 v67, 0xffff0000, v67
	v_lshlrev_b32_e32 v64, 16, v65
	v_and_b32_e32 v65, 0xffff0000, v65
	v_lshlrev_b32_e32 v74, 16, v66
	v_and_b32_e32 v66, 0xffff0000, v66
	v_mul_f32_e32 v56, v68, v56
	v_mul_f32_e32 v57, v69, v57
	v_mul_f32_e32 v59, v59, v67
	v_mul_f32_e32 v62, v62, v64
	v_mul_f32_e32 v63, v63, v65
	v_mul_f32_e32 v64, v72, v74
	v_mul_f32_e32 v65, v73, v66
	v_mul_f32_e32 v66, v58, v75
	v_cvt_pk_bf16_f32 v56, v56, v57
	v_cvt_pk_bf16_f32 v57, v62, v63
	v_cvt_pk_bf16_f32 v58, v64, v65
	v_cvt_pk_bf16_f32 v59, v66, v59
	global_store_dwordx4 v[60:61], v[56:59], off offset:2048
	v_exp_f32_e32 v62, v52
	v_exp_f32_e32 v63, v53
	v_add_u32_e32 v52, 0x90, v140
	v_ashrrev_i32_e32 v53, 31, v52
	v_add_f32_e32 v62, 1.0, v62
	v_add_f32_e32 v63, 1.0, v63
	v_add_f32_e32 v64, 1.0, v48
	v_add_f32_e32 v65, 1.0, v49
	v_rcp_f32_e32 v62, v62
	v_rcp_f32_e32 v63, v63
	v_lshlrev_b64 v[48:49], 10, v[52:53]
	v_rcp_f32_e32 v66, v54
	v_rcp_f32_e32 v67, v55
	v_rcp_f32_e32 v64, v64
	v_rcp_f32_e32 v65, v65
	v_lshl_add_u64 v[48:49], s[6:7], 0, v[48:49]
	v_lshl_add_u64 v[54:55], v[48:49], 0, v[138:139]
	s_waitcnt vmcnt(13)
	s_nop 1
	v_mov_b64_e32 v[56:57], v[204:205]
	v_mov_b64_e32 v[58:59], v[206:207]
	v_lshlrev_b32_e32 v48, 16, v56
	v_and_b32_e32 v49, 0xffff0000, v56
	v_lshlrev_b32_e32 v69, 16, v59
	v_and_b32_e32 v59, 0xffff0000, v59
	v_lshlrev_b32_e32 v56, 16, v57
	v_and_b32_e32 v57, 0xffff0000, v57
	v_lshlrev_b32_e32 v68, 16, v58
	v_and_b32_e32 v58, 0xffff0000, v58
	v_mul_f32_e32 v48, v62, v48
	v_mul_f32_e32 v49, v63, v49
	v_mul_f32_e32 v51, v51, v59
	v_mul_f32_e32 v56, v66, v56
	v_mul_f32_e32 v57, v67, v57
	v_mul_f32_e32 v62, v64, v68
	v_mul_f32_e32 v58, v65, v58
	v_mul_f32_e32 v63, v50, v69
	v_cvt_pk_bf16_f32 v48, v48, v49
	v_cvt_pk_bf16_f32 v49, v56, v57
	v_cvt_pk_bf16_f32 v50, v62, v58
	v_cvt_pk_bf16_f32 v51, v63, v51
	global_store_dwordx4 v[60:61], v[48:51], off offset:2304
	v_add_f32_e32 v56, 1.0, v40
	v_add_f32_e32 v57, 1.0, v41
	v_lshlrev_b64 v[40:41], 12, v[52:53]
	v_rcp_f32_e32 v52, v44
	v_rcp_f32_e32 v53, v45
	v_rcp_f32_e32 v56, v56
	v_rcp_f32_e32 v57, v57
	v_lshl_add_u64 v[40:41], s[8:9], 0, v[40:41]
	v_lshl_add_u64 v[44:45], v[40:41], 0, v[138:139]
	s_waitcnt vmcnt(13)
	s_nop 1
	v_mov_b64_e32 v[48:49], v[208:209]
	v_mov_b64_e32 v[50:51], v[210:211]
	v_lshlrev_b32_e32 v40, 16, v48
	v_and_b32_e32 v41, 0xffff0000, v48
	v_lshlrev_b32_e32 v59, 16, v51
	v_and_b32_e32 v51, 0xffff0000, v51
	v_lshlrev_b32_e32 v48, 16, v49
	v_and_b32_e32 v49, 0xffff0000, v49
	v_lshlrev_b32_e32 v58, 16, v50
	v_and_b32_e32 v50, 0xffff0000, v50
	v_mul_f32_e32 v40, v52, v40
	v_mul_f32_e32 v41, v53, v41
	v_mul_f32_e32 v43, v43, v51
	v_mul_f32_e32 v46, v46, v48
	v_mul_f32_e32 v47, v47, v49
	v_mul_f32_e32 v48, v56, v58
	v_mul_f32_e32 v49, v57, v50
	v_mul_f32_e32 v50, v42, v59
	v_cvt_pk_bf16_f32 v40, v40, v41
	v_cvt_pk_bf16_f32 v41, v46, v47
	v_cvt_pk_bf16_f32 v42, v48, v49
	v_cvt_pk_bf16_f32 v43, v50, v43
	global_store_dwordx4 v[44:45], v[40:43], off offset:2048
	v_exp_f32_e32 v46, v36
	v_exp_f32_e32 v47, v37
	v_add_u32_e32 v36, 0xa0, v140
	v_ashrrev_i32_e32 v37, 31, v36
	v_add_f32_e32 v46, 1.0, v46
	v_add_f32_e32 v47, 1.0, v47
	v_add_f32_e32 v48, 1.0, v32
	v_add_f32_e32 v49, 1.0, v33
	v_rcp_f32_e32 v46, v46
	v_rcp_f32_e32 v47, v47
	v_lshlrev_b64 v[32:33], 10, v[36:37]
	v_rcp_f32_e32 v50, v38
	v_rcp_f32_e32 v51, v39
	v_rcp_f32_e32 v48, v48
	v_rcp_f32_e32 v49, v49
	v_lshl_add_u64 v[32:33], s[6:7], 0, v[32:33]
	v_lshl_add_u64 v[38:39], v[32:33], 0, v[138:139]
	s_waitcnt vmcnt(13)
	s_nop 1
	v_mov_b64_e32 v[40:41], v[212:213]
	v_mov_b64_e32 v[42:43], v[214:215]
	v_lshlrev_b32_e32 v32, 16, v40
	v_and_b32_e32 v33, 0xffff0000, v40
	v_lshlrev_b32_e32 v53, 16, v43
	v_and_b32_e32 v43, 0xffff0000, v43
	v_lshlrev_b32_e32 v40, 16, v41
	v_and_b32_e32 v41, 0xffff0000, v41
	v_lshlrev_b32_e32 v52, 16, v42
	v_and_b32_e32 v42, 0xffff0000, v42
	v_mul_f32_e32 v32, v46, v32
	v_mul_f32_e32 v33, v47, v33
	v_mul_f32_e32 v35, v35, v43
	v_mul_f32_e32 v40, v50, v40
	v_mul_f32_e32 v41, v51, v41
	v_mul_f32_e32 v46, v48, v52
	v_mul_f32_e32 v42, v49, v42
	v_mul_f32_e32 v47, v34, v53
	v_cvt_pk_bf16_f32 v32, v32, v33
	v_cvt_pk_bf16_f32 v33, v40, v41
	v_cvt_pk_bf16_f32 v34, v46, v42
	v_cvt_pk_bf16_f32 v35, v47, v35
	global_store_dwordx4 v[44:45], v[32:35], off offset:2304
	v_add_f32_e32 v40, 1.0, v24
	v_add_f32_e32 v41, 1.0, v25
	v_lshlrev_b64 v[24:25], 12, v[36:37]
	v_rcp_f32_e32 v36, v28
	v_rcp_f32_e32 v37, v29
	v_rcp_f32_e32 v40, v40
	v_rcp_f32_e32 v41, v41
	v_lshl_add_u64 v[24:25], s[8:9], 0, v[24:25]
	v_lshl_add_u64 v[28:29], v[24:25], 0, v[138:139]
	s_waitcnt vmcnt(13)
; __device__ __forceinline__ unsigned cvt_pk_bf16(float lo, float hi) { unsigned r; asm volatile("v_cvt_pk_bf16_f32 %0, %1, %2" : "=v"(r) : "v"(lo), "v"(hi)); return r; }
; __device__ __forceinline__ float sigmoidf_(float x) { return __builtin_amdgcn_rcpf(1.0f + __expf(-x)); }
;     __device__ __forceinline__ void operator()(const f32x4 (&acc)[2][2][4][2], const Unit& u, int wr, int wc, int fr, int fq) const {
;     ...
;             for (int m = 0; m < 4; ++m) { const size_t row = (size_t)(row0 + ai * HALF + m * 16);
; #pragma unroll
;                 for (int bj = 0; bj < 2; ++bj) { const int c = col0 + bj * HALF;
;                     const u32x4 yv = *(const u32x4*)(Y + row * ldy + c);
;                     const f32x4 v0 = acc[ai][bj][m][0], v1 = acc[ai][bj][m][1];
;                     u32x4 w;
;                     w.x = cvt_pk_bf16(bflo(yv.x) * sigmoidf_(v0[0]), bfhi(yv.x) * sigmoidf_(v0[1]));
;                     w.y = cvt_pk_bf16(bflo(yv.y) * sigmoidf_(v0[2]), bfhi(yv.y) * sigmoidf_(v0[3]));
;                     w.z = cvt_pk_bf16(bflo(yv.z) * sigmoidf_(v1[0]), bfhi(yv.z) * sigmoidf_(v1[1]));
;                     w.w = cvt_pk_bf16(bflo(yv.w) * sigmoidf_(v1[2]), bfhi(yv.w) * sigmoidf_(v1[3]));
;                     *(u32x4*)(O + row * ldc + ocol0 + c) = w; } }
;     }
	s_nop 1
	v_mov_b64_e32 v[32:33], v[216:217]
	v_mov_b64_e32 v[34:35], v[218:219]
	v_lshlrev_b32_e32 v24, 16, v32
	v_and_b32_e32 v25, 0xffff0000, v32
	v_lshlrev_b32_e32 v43, 16, v35
	v_and_b32_e32 v35, 0xffff0000, v35
	v_lshlrev_b32_e32 v32, 16, v33
	v_and_b32_e32 v33, 0xffff0000, v33
	v_lshlrev_b32_e32 v42, 16, v34
	v_and_b32_e32 v34, 0xffff0000, v34
	v_mul_f32_e32 v24, v36, v24
	v_mul_f32_e32 v25, v37, v25
	v_mul_f32_e32 v27, v27, v35
	v_mul_f32_e32 v30, v30, v32
	v_mul_f32_e32 v31, v31, v33
	v_mul_f32_e32 v32, v40, v42
	v_mul_f32_e32 v33, v41, v34
	v_mul_f32_e32 v34, v26, v43
	v_cvt_pk_bf16_f32 v24, v24, v25
	v_cvt_pk_bf16_f32 v25, v30, v31
	v_cvt_pk_bf16_f32 v26, v32, v33
	v_cvt_pk_bf16_f32 v27, v34, v27
	global_store_dwordx4 v[28:29], v[24:27], off offset:2048
	v_exp_f32_e32 v30, v20
	v_exp_f32_e32 v31, v21
	v_add_u32_e32 v20, 0xb0, v140
	v_ashrrev_i32_e32 v21, 31, v20
	v_add_f32_e32 v30, 1.0, v30
	v_add_f32_e32 v31, 1.0, v31
	v_add_f32_e32 v32, 1.0, v16
	v_add_f32_e32 v33, 1.0, v17
	v_rcp_f32_e32 v30, v30
	v_rcp_f32_e32 v31, v31
	v_lshlrev_b64 v[16:17], 10, v[20:21]
	v_rcp_f32_e32 v34, v22
	v_rcp_f32_e32 v35, v23
	v_rcp_f32_e32 v32, v32
	v_rcp_f32_e32 v33, v33
	v_lshl_add_u64 v[16:17], s[6:7], 0, v[16:17]
	v_lshl_add_u64 v[22:23], v[16:17], 0, v[138:139]
	s_waitcnt vmcnt(13)
	s_nop 1
	v_mov_b64_e32 v[24:25], v[220:221]
	v_mov_b64_e32 v[26:27], v[222:223]
	v_lshlrev_b32_e32 v16, 16, v24
	v_and_b32_e32 v17, 0xffff0000, v24
	v_lshlrev_b32_e32 v37, 16, v27
	v_and_b32_e32 v27, 0xffff0000, v27
	v_lshlrev_b32_e32 v24, 16, v25
	v_and_b32_e32 v25, 0xffff0000, v25
	v_lshlrev_b32_e32 v36, 16, v26
	v_and_b32_e32 v26, 0xffff0000, v26
	v_mul_f32_e32 v16, v30, v16
	v_mul_f32_e32 v17, v31, v17
	v_mul_f32_e32 v19, v19, v27
	v_mul_f32_e32 v24, v34, v24
	v_mul_f32_e32 v25, v35, v25
	v_mul_f32_e32 v30, v32, v36
	v_mul_f32_e32 v26, v33, v26
	v_mul_f32_e32 v31, v18, v37
	v_cvt_pk_bf16_f32 v16, v16, v17
	v_cvt_pk_bf16_f32 v17, v24, v25
	v_cvt_pk_bf16_f32 v18, v30, v26
	v_cvt_pk_bf16_f32 v19, v31, v19
	global_store_dwordx4 v[28:29], v[16:19], off offset:2304
	v_add_f32_e32 v24, 1.0, v8
	v_add_f32_e32 v25, 1.0, v9
	v_lshlrev_b64 v[8:9], 12, v[20:21]
	v_rcp_f32_e32 v20, v12
	v_rcp_f32_e32 v21, v13
	v_rcp_f32_e32 v24, v24
	v_rcp_f32_e32 v25, v25
	v_lshl_add_u64 v[8:9], s[8:9], 0, v[8:9]
	v_lshl_add_u64 v[12:13], v[8:9], 0, v[138:139]
	s_waitcnt vmcnt(13)
	s_nop 1
	v_mov_b64_e32 v[16:17], v[224:225]
	v_mov_b64_e32 v[18:19], v[226:227]
	v_lshlrev_b32_e32 v8, 16, v16
	v_and_b32_e32 v9, 0xffff0000, v16
	v_lshlrev_b32_e32 v27, 16, v19
	v_and_b32_e32 v19, 0xffff0000, v19
	v_lshlrev_b32_e32 v16, 16, v17
	v_and_b32_e32 v17, 0xffff0000, v17
	v_lshlrev_b32_e32 v26, 16, v18
	v_and_b32_e32 v18, 0xffff0000, v18
	v_mul_f32_e32 v8, v20, v8
	v_mul_f32_e32 v9, v21, v9
	v_mul_f32_e32 v11, v11, v19
	v_mul_f32_e32 v14, v14, v16
	v_mul_f32_e32 v15, v15, v17
	v_mul_f32_e32 v16, v24, v26
	v_mul_f32_e32 v17, v25, v18
	v_mul_f32_e32 v18, v10, v27
	v_cvt_pk_bf16_f32 v8, v8, v9
	v_cvt_pk_bf16_f32 v9, v14, v15
	v_cvt_pk_bf16_f32 v10, v16, v17
	v_cvt_pk_bf16_f32 v11, v18, v11
	global_store_dwordx4 v[12:13], v[8:11], off offset:2048
	s_waitcnt vmcnt(13)
	s_nop 1
	v_mov_b64_e32 v[8:9], v[228:229]
	v_mov_b64_e32 v[10:11], v[230:231]
	v_lshlrev_b32_e32 v17, 16, v11
	v_and_b32_e32 v11, 0xffff0000, v11
	v_lshlrev_b32_e32 v14, 16, v8
	v_and_b32_e32 v8, 0xffff0000, v8
	v_lshlrev_b32_e32 v15, 16, v9
	v_and_b32_e32 v9, 0xffff0000, v9
	v_lshlrev_b32_e32 v16, 16, v10
	v_and_b32_e32 v10, 0xffff0000, v10
	v_mul_f32_e32 v3, v3, v11
	v_mul_f32_e32 v4, v4, v14
	v_mul_f32_e32 v5, v5, v8
	v_mul_f32_e32 v6, v6, v15
	v_mul_f32_e32 v7, v7, v9
	v_mul_f32_e32 v8, v0, v16
	v_mul_f32_e32 v9, v1, v10
	v_mul_f32_e32 v10, v2, v17
	v_cvt_pk_bf16_f32 v0, v4, v5
	v_cvt_pk_bf16_f32 v1, v6, v7
	v_cvt_pk_bf16_f32 v2, v8, v9
	v_cvt_pk_bf16_f32 v3, v10, v3
	global_store_dwordx4 v[12:13], v[0:3], off offset:2304
	s_cbranch_vccnz .LBB0_387
	s_andn2_b64 vcc, exec, s[4:5]
	s_cbranch_vccnz .LBB0_386
	s_barrier
	s_branch .LBB0_386

; #define PG8_STAGE(bufoff, gbase, voff) do { _Pragma("unroll") for (int _i = 0; _i < 2; ++_i) \
;         __builtin_amdgcn_global_load_lds((const unsigned*)((const char*)(gbase) + (voff)[_i]), (LAS unsigned*)(lds + (bufoff) + ldsw + _i * 8192), 16, 0, 0); } while (0)
; #define PG8_LDA(dst, b, h) do { _Pragma("unroll") for (int m = 0; m < 4; ++m) _Pragma("unroll") for (int k = 0; k < 2; ++k) dst[m][k] = *(const LAS bf16x8*)(lds + PG8_SA(b, h) + aoff + m * 2048 + k * 1024); } while (0)
; #define PG8_LDB(dst, b, h) do { _Pragma("unroll") for (int n = 0; n < 2; ++n) _Pragma("unroll") for (int k = 0; k < 2; ++k) dst[n][k] = *(const LAS bf16x8*)(lds + PG8_SB(b, h) + boff + n * 2048 + k * 1024); } while (0)
; #define PG8_WAIT_V(n) asm volatile("s_waitcnt vmcnt(" #n ")" ::: "memory")
; #define PG8_WAIT_L(n) asm volatile("s_waitcnt lgkmcnt(" #n ")" ::: "memory")
; #define PG8_BAR __builtin_amdgcn_s_barrier()
; #define PG8_SCHED __builtin_amdgcn_sched_barrier(0)
; template <class Epi, class Sched>
; __device__ __forceinline__ void gemm_phase(const int tid, LAS unsigned char* lds, const Gemm g, const Sched& S, const Epi& E) {
;     ...
;     for (;;) {
;         const bool has_next = S.next(ui + 1, nxt);
;         const char* nA = has_next ? (const char*)g.A + (size_t)nxt.pm * tstep : cA; const char* nB = has_next ? (const char*)g.Bt + (size_t)nxt.pn * tstep : cB;
;         for (int t = 0; t < nt; t += 2) {
;             const bool last = (t == nt - 2);
;             const char* a1 = cA + (size_t)(t + 1) * kstep;
;             const char* a2 = last ? nA : cA + (size_t)(t + 2) * kstep; const char* b2 = last ? nB : cB + (size_t)(t + 2) * kstep;
;             const char* a3 = a2 + kstep; const char* b3 = b2 + kstep;
;             if (last && has_next) S.a_ready(nxt);
;             PG8_LDB(B0, 0, 0); PG8_LDB(B1, 0, 1); PG8_SCHED; PG8_LDA(At, 0, 0); PG8_STAGE(PG8_SA(1, 1), a1 + hstep, voffA);
;             PG8_WAIT_V(8); PG8_WAIT_L(0); PG8_BAR; PG8_MMA(0, 0, At, B0); PG8_MMA(0, 1, At, B1); PG8_BAR; PG8_SCHED;
;             PG8_LDA(At, 0, 1); PG8_STAGE(PG8_SB(0, 0), b2, voffB); PG8_STAGE(PG8_SB(0, 1), b2 + hstep, voffB); PG8_STAGE(PG8_SA(0, 0), a2, voffA);
;             PG8_WAIT_V(8); PG8_WAIT_L(0); PG8_BAR; PG8_MMA(1, 0, At, B0); PG8_MMA(1, 1, At, B1); PG8_BAR; PG8_SCHED;
.LBB0_549:
	s_ashr_i32 s17, s16, 31
	s_lshl_b64 s[18:19], s[16:17], 20
	s_add_u32 s18, s41, s18
	s_addc_u32 s19, s55, s19
	s_and_b64 s[20:21], s[0:1], exec
	s_cselect_b32 s5, s19, s25
	s_cselect_b32 s17, s18, s24
	s_ashr_i32 s15, s14, 31
	s_lshl_b64 s[20:21], s[14:15], 20
	s_add_u32 s20, s39, s20
	s_addc_u32 s21, s40, s21
	s_and_b64 s[28:29], s[0:1], exec
	s_cselect_b32 s15, s21, s27
	s_cselect_b32 s23, s20, s26
	s_add_u32 s24, s24, 0x80080
	s_addc_u32 s25, s25, 0
	s_add_u32 s69, s26, 0x100
	v_mov_b32_e32 v0, 0
	s_addc_u32 s70, s27, 0
	s_mov_b32 s71, -2
	s_waitcnt lgkmcnt(0)
	s_add_u32 s26, s24, 0xfff80080
	s_addc_u32 s27, s25, -1
	s_add_i32 s72, 0, 0x10000
	s_cmp_eq_u32 s71, 28
	s_cselect_b32 s29, s5, s27
	s_cselect_b32 s28, s17, s26
	s_cselect_b32 s27, s15, s70
	s_cselect_b32 s26, s23, s69
	s_add_i32 s74, 0, 0x14000
	v_add_u32_e32 v140, s72, v201
	v_add_u32_e32 v184, s74, v201
	ds_read_b128 v[128:131], v140
	ds_read_b128 v[132:135], v140 offset:1024
	ds_read_b128 v[136:139], v140 offset:2048
	ds_read_b128 v[140:143], v140 offset:3072
	ds_read_b128 v[144:147], v184
	ds_read_b128 v[148:151], v184 offset:1024
	ds_read_b128 v[180:183], v184 offset:2048
	ds_read_b128 v[184:187], v184 offset:3072
	v_lshl_add_u64 v[232:233], s[24:25], 0, v[176:177]
	s_add_i32 m0, s57, 0xc000
	ds_read_b128 v[188:191], v202
	ds_read_b128 v[204:207], v202 offset:1024
	ds_read_b128 v[208:211], v202 offset:2048
	ds_read_b128 v[212:215], v202 offset:3072
	ds_read_b128 v[216:219], v202 offset:4096
	ds_read_b128 v[220:223], v202 offset:5120
	ds_read_b128 v[224:227], v202 offset:6144
	ds_read_b128 v[228:231], v202 offset:7168
	global_load_lds_dwordx4 v[232:233], off
	v_lshl_add_u64 v[232:233], s[24:25], 0, v[178:179]
	s_add_i32 m0, s57, 0xe000
	s_nop 0
	global_load_lds_dwordx4 v[232:233], off
	s_waitcnt vmcnt(8)
	s_waitcnt lgkmcnt(0)
	s_barrier
	s_setprio 1
	s_waitcnt lgkmcnt(0)
	v_mfma_f32_16x16x32_bf16 v[124:127], v[128:131], v[188:191], 0
	v_mfma_f32_16x16x32_bf16 v[120:123], v[136:139], v[188:191], 0
	v_mfma_f32_16x16x32_bf16 v[108:111], v[128:131], v[208:211], 0
	v_mfma_f32_16x16x32_bf16 v[104:107], v[136:139], v[208:211], 0
	v_mfma_f32_16x16x32_bf16 v[92:95], v[128:131], v[216:219], 0
	v_mfma_f32_16x16x32_bf16 v[88:91], v[136:139], v[216:219], 0
	v_mfma_f32_16x16x32_bf16 v[76:79], v[128:131], v[224:227], 0
	v_mfma_f32_16x16x32_bf16 v[72:75], v[136:139], v[224:227], 0
	v_mfma_f32_16x16x32_bf16 v[124:127], v[132:135], v[204:207], v[124:127]
	v_mfma_f32_16x16x32_bf16 v[120:123], v[140:143], v[204:207], v[120:123]
	v_mfma_f32_16x16x32_bf16 v[108:111], v[132:135], v[212:215], v[108:111]
	v_mfma_f32_16x16x32_bf16 v[104:107], v[140:143], v[212:215], v[104:107]
	v_mfma_f32_16x16x32_bf16 v[92:95], v[132:135], v[220:223], v[92:95]
	v_mfma_f32_16x16x32_bf16 v[88:91], v[140:143], v[220:223], v[88:91]
	v_mfma_f32_16x16x32_bf16 v[76:79], v[132:135], v[228:231], v[76:79]
	v_mfma_f32_16x16x32_bf16 v[72:75], v[140:143], v[228:231], v[72:75]
	s_setprio 0
	s_setprio 1
	v_mfma_f32_16x16x32_bf16 v[116:119], v[144:147], v[188:191], 0
	v_mfma_f32_16x16x32_bf16 v[112:115], v[180:183], v[188:191], 0
	v_mfma_f32_16x16x32_bf16 v[100:103], v[144:147], v[208:211], 0
	v_mfma_f32_16x16x32_bf16 v[96:99], v[180:183], v[208:211], 0
	v_mfma_f32_16x16x32_bf16 v[84:87], v[144:147], v[216:219], 0
	v_mfma_f32_16x16x32_bf16 v[80:83], v[180:183], v[216:219], 0
	v_mfma_f32_16x16x32_bf16 v[68:71], v[144:147], v[224:227], 0
	v_mfma_f32_16x16x32_bf16 v[64:67], v[180:183], v[224:227], 0
	v_mfma_f32_16x16x32_bf16 v[116:119], v[148:151], v[204:207], v[116:119]
	v_mfma_f32_16x16x32_bf16 v[112:115], v[184:187], v[204:207], v[112:115]
	v_mfma_f32_16x16x32_bf16 v[100:103], v[148:151], v[212:215], v[100:103]
	v_mfma_f32_16x16x32_bf16 v[96:99], v[184:187], v[212:215], v[96:99]
	v_mfma_f32_16x16x32_bf16 v[84:87], v[148:151], v[220:223], v[84:87]
	v_mfma_f32_16x16x32_bf16 v[80:83], v[184:187], v[220:223], v[80:83]
	v_mfma_f32_16x16x32_bf16 v[68:71], v[148:151], v[228:231], v[68:71]
	v_mfma_f32_16x16x32_bf16 v[64:67], v[184:187], v[228:231], v[64:67]
	s_setprio 0
	s_barrier
	s_add_i32 s72, s72, s56
	v_lshl_add_u64 v[232:233], s[26:27], 0, v[152:153]
	s_mov_b32 m0, s72
	ds_read_b128 v[188:191], v202 offset:16384
	ds_read_b128 v[204:207], v202 offset:17408
	ds_read_b128 v[208:211], v202 offset:18432
	ds_read_b128 v[212:215], v202 offset:19456
	ds_read_b128 v[216:219], v202 offset:20480
	ds_read_b128 v[220:223], v202 offset:21504
	ds_read_b128 v[224:227], v202 offset:22528
	ds_read_b128 v[228:231], v202 offset:23552
	global_load_lds_dwordx4 v[232:233], off
	s_add_i32 m0, s72, 0x2000
	s_add_u32 s72, s26, 0x80000
	v_lshl_add_u64 v[234:235], s[26:27], 0, v[174:175]
	s_addc_u32 s73, s27, 0
	s_add_i32 s74, s74, s56
	global_load_lds_dwordx4 v[234:235], off
	v_lshl_add_u64 v[236:237], s[72:73], 0, v[152:153]
	s_mov_b32 m0, s74
	v_lshl_add_u64 v[238:239], s[28:29], 0, v[172:173]
	global_load_lds_dwordx4 v[236:237], off
	v_lshl_add_u64 v[236:237], s[72:73], 0, v[174:175]
	s_add_i32 m0, s74, 0x2000
	s_nop 0
	global_load_lds_dwordx4 v[236:237], off
	v_lshl_add_u64 v[236:237], s[28:29], 0, v[170:171]
	s_mov_b32 m0, s57
	s_nop 0
	global_load_lds_dwordx4 v[236:237], off
	s_mov_b32 m0, s58
	s_nop 0
	global_load_lds_dwordx4 v[238:239], off
	s_waitcnt vmcnt(8)
	s_waitcnt lgkmcnt(0)
	s_barrier
; #define PG8_STAGE(bufoff, gbase, voff) do { _Pragma("unroll") for (int _i = 0; _i < 2; ++_i) \
;         __builtin_amdgcn_global_load_lds((const unsigned*)((const char*)(gbase) + (voff)[_i]), (LAS unsigned*)(lds + (bufoff) + ldsw + _i * 8192), 16, 0, 0); } while (0)
; #define PG8_LDA(dst, b, h) do { _Pragma("unroll") for (int m = 0; m < 4; ++m) _Pragma("unroll") for (int k = 0; k < 2; ++k) dst[m][k] = *(const LAS bf16x8*)(lds + PG8_SA(b, h) + aoff + m * 2048 + k * 1024); } while (0)
; #define PG8_LDB(dst, b, h) do { _Pragma("unroll") for (int n = 0; n < 2; ++n) _Pragma("unroll") for (int k = 0; k < 2; ++k) dst[n][k] = *(const LAS bf16x8*)(lds + PG8_SB(b, h) + boff + n * 2048 + k * 1024); } while (0)
; #define PG8_MMA(ai, bj, At, Bt) do { __builtin_amdgcn_s_setprio(1); _Pragma("unroll") for (int m = 0; m < 4; ++m) _Pragma("unroll") for (int n = 0; n < 2; ++n) _Pragma("unroll") for (int k = 0; k < 2; ++k) \
;         acc[ai][bj][m][n] = __builtin_amdgcn_mfma_f32_16x16x32_bf16(Bt[n][k], At[m][k], acc[ai][bj][m][n], 0, 0, 0); __builtin_amdgcn_s_setprio(0); } while (0)
; #define PG8_WAIT_V(n) asm volatile("s_waitcnt vmcnt(" #n ")" ::: "memory")
; #define PG8_WAIT_L(n) asm volatile("s_waitcnt lgkmcnt(" #n ")" ::: "memory")
; #define PG8_BAR __builtin_amdgcn_s_barrier()
; #define PG8_SCHED __builtin_amdgcn_sched_barrier(0)
; template <class Epi, class Sched>
; __device__ __forceinline__ void gemm_phase(const int tid, LAS unsigned char* lds, const Gemm g, const Sched& S, const Epi& E) {
;     ...
;             PG8_WAIT_V(8); PG8_WAIT_L(0); PG8_BAR; PG8_MMA(0, 0, At, B0); PG8_MMA(0, 1, At, B1); PG8_BAR; PG8_SCHED;
;             PG8_LDA(At, 0, 1); PG8_STAGE(PG8_SB(0, 0), b2, voffB); PG8_STAGE(PG8_SB(0, 1), b2 + hstep, voffB); PG8_STAGE(PG8_SA(0, 0), a2, voffA);
;             PG8_WAIT_V(8); PG8_WAIT_L(0); PG8_BAR; PG8_MMA(1, 0, At, B0); PG8_MMA(1, 1, At, B1); PG8_BAR; PG8_SCHED;
;             PG8_LDB(B0, 1, 0); PG8_LDB(B1, 1, 1); PG8_SCHED; PG8_LDA(At, 1, 0); PG8_STAGE(PG8_SA(0, 1), a2 + hstep, voffA);
;             PG8_WAIT_V(8); PG8_WAIT_L(0); PG8_BAR; PG8_MMA(0, 0, At, B0); PG8_MMA(0, 1, At, B1); PG8_BAR; PG8_SCHED;
	s_setprio 1
	s_waitcnt lgkmcnt(0)
	v_mfma_f32_16x16x32_bf16 v[60:63], v[128:131], v[188:191], 0
	v_mfma_f32_16x16x32_bf16 v[56:59], v[136:139], v[188:191], 0
	v_mfma_f32_16x16x32_bf16 v[44:47], v[128:131], v[208:211], 0
	v_mfma_f32_16x16x32_bf16 v[40:43], v[136:139], v[208:211], 0
	v_mfma_f32_16x16x32_bf16 v[28:31], v[128:131], v[216:219], 0
	v_mfma_f32_16x16x32_bf16 v[24:27], v[136:139], v[216:219], 0
	v_mfma_f32_16x16x32_bf16 v[12:15], v[128:131], v[224:227], 0
	v_mfma_f32_16x16x32_bf16 v[8:11], v[136:139], v[224:227], 0
	v_mfma_f32_16x16x32_bf16 v[60:63], v[132:135], v[204:207], v[60:63]
	v_mfma_f32_16x16x32_bf16 v[56:59], v[140:143], v[204:207], v[56:59]
	v_mfma_f32_16x16x32_bf16 v[44:47], v[132:135], v[212:215], v[44:47]
	v_mfma_f32_16x16x32_bf16 v[40:43], v[140:143], v[212:215], v[40:43]
	v_mfma_f32_16x16x32_bf16 v[28:31], v[132:135], v[220:223], v[28:31]
	v_mfma_f32_16x16x32_bf16 v[24:27], v[140:143], v[220:223], v[24:27]
	v_mfma_f32_16x16x32_bf16 v[12:15], v[132:135], v[228:231], v[12:15]
	v_mfma_f32_16x16x32_bf16 v[8:11], v[140:143], v[228:231], v[8:11]
	s_setprio 0
	s_setprio 1
	v_mfma_f32_16x16x32_bf16 v[52:55], v[144:147], v[188:191], 0
	v_mfma_f32_16x16x32_bf16 v[48:51], v[180:183], v[188:191], 0
	v_mfma_f32_16x16x32_bf16 v[36:39], v[144:147], v[208:211], 0
	v_mfma_f32_16x16x32_bf16 v[32:35], v[180:183], v[208:211], 0
	v_mfma_f32_16x16x32_bf16 v[20:23], v[144:147], v[216:219], 0
	v_mfma_f32_16x16x32_bf16 v[16:19], v[180:183], v[216:219], 0
	v_mfma_f32_16x16x32_bf16 v[4:7], v[144:147], v[224:227], 0
	v_mfma_f32_16x16x32_bf16 v[0:3], v[180:183], v[224:227], 0
	v_mfma_f32_16x16x32_bf16 v[52:55], v[148:151], v[204:207], v[52:55]
	v_mfma_f32_16x16x32_bf16 v[48:51], v[184:187], v[204:207], v[48:51]
	v_mfma_f32_16x16x32_bf16 v[36:39], v[148:151], v[212:215], v[36:39]
	v_mfma_f32_16x16x32_bf16 v[32:35], v[184:187], v[212:215], v[32:35]
	v_mfma_f32_16x16x32_bf16 v[20:23], v[148:151], v[220:223], v[20:23]
	v_mfma_f32_16x16x32_bf16 v[16:19], v[184:187], v[220:223], v[16:19]
	v_mfma_f32_16x16x32_bf16 v[4:7], v[148:151], v[228:231], v[4:7]
	v_mfma_f32_16x16x32_bf16 v[0:3], v[184:187], v[228:231], v[0:3]
	s_setprio 0
	s_barrier
	s_add_i32 s72, 0, 0x18000
	s_add_i32 s73, 0, 0x1c000
	v_add_u32_e32 v140, s72, v201
	v_add_u32_e32 v184, s73, v201
	ds_read_b128 v[128:131], v140
	ds_read_b128 v[132:135], v140 offset:1024
	ds_read_b128 v[136:139], v140 offset:2048
	ds_read_b128 v[140:143], v140 offset:3072
	ds_read_b128 v[144:147], v184
	ds_read_b128 v[148:151], v184 offset:1024
	ds_read_b128 v[180:183], v184 offset:2048
	ds_read_b128 v[184:187], v184 offset:3072
	s_add_u32 s28, s28, 0x80000
	s_addc_u32 s29, s29, 0
	s_mov_b32 m0, s59
	v_lshl_add_u64 v[240:241], s[28:29], 0, v[170:171]
	ds_read_b128 v[188:191], v202 offset:32768
	ds_read_b128 v[204:207], v202 offset:33792
	ds_read_b128 v[208:211], v202 offset:34816
	ds_read_b128 v[212:215], v202 offset:35840
	ds_read_b128 v[216:219], v202 offset:36864
	ds_read_b128 v[220:223], v202 offset:37888
	ds_read_b128 v[224:227], v202 offset:38912
	ds_read_b128 v[228:231], v202 offset:39936
	global_load_lds_dwordx4 v[240:241], off
	v_lshl_add_u64 v[240:241], s[28:29], 0, v[172:173]
	s_mov_b32 m0, s60
	s_nop 0
	global_load_lds_dwordx4 v[240:241], off
	s_waitcnt vmcnt(8)
	s_waitcnt lgkmcnt(0)
	s_barrier
	s_setprio 1
	s_waitcnt lgkmcnt(0)
	v_mfma_f32_16x16x32_bf16 v[124:127], v[128:131], v[188:191], v[124:127]
	v_mfma_f32_16x16x32_bf16 v[120:123], v[136:139], v[188:191], v[120:123]
	v_mfma_f32_16x16x32_bf16 v[108:111], v[128:131], v[208:211], v[108:111]
	v_mfma_f32_16x16x32_bf16 v[104:107], v[136:139], v[208:211], v[104:107]
	v_mfma_f32_16x16x32_bf16 v[92:95], v[128:131], v[216:219], v[92:95]
	v_mfma_f32_16x16x32_bf16 v[88:91], v[136:139], v[216:219], v[88:91]
	v_mfma_f32_16x16x32_bf16 v[76:79], v[128:131], v[224:227], v[76:79]
	v_mfma_f32_16x16x32_bf16 v[72:75], v[136:139], v[224:227], v[72:75]
	v_mfma_f32_16x16x32_bf16 v[124:127], v[132:135], v[204:207], v[124:127]
	v_mfma_f32_16x16x32_bf16 v[120:123], v[140:143], v[204:207], v[120:123]
	v_mfma_f32_16x16x32_bf16 v[108:111], v[132:135], v[212:215], v[108:111]
	v_mfma_f32_16x16x32_bf16 v[104:107], v[140:143], v[212:215], v[104:107]
	v_mfma_f32_16x16x32_bf16 v[92:95], v[132:135], v[220:223], v[92:95]
	v_mfma_f32_16x16x32_bf16 v[88:91], v[140:143], v[220:223], v[88:91]
	v_mfma_f32_16x16x32_bf16 v[76:79], v[132:135], v[228:231], v[76:79]
	v_mfma_f32_16x16x32_bf16 v[72:75], v[140:143], v[228:231], v[72:75]
	s_setprio 0
	s_setprio 1
	v_mfma_f32_16x16x32_bf16 v[116:119], v[144:147], v[188:191], v[116:119]
	v_mfma_f32_16x16x32_bf16 v[112:115], v[180:183], v[188:191], v[112:115]
	v_mfma_f32_16x16x32_bf16 v[100:103], v[144:147], v[208:211], v[100:103]
	v_mfma_f32_16x16x32_bf16 v[96:99], v[180:183], v[208:211], v[96:99]
	v_mfma_f32_16x16x32_bf16 v[84:87], v[144:147], v[216:219], v[84:87]
	v_mfma_f32_16x16x32_bf16 v[80:83], v[180:183], v[216:219], v[80:83]
	v_mfma_f32_16x16x32_bf16 v[68:71], v[144:147], v[224:227], v[68:71]
	v_mfma_f32_16x16x32_bf16 v[64:67], v[180:183], v[224:227], v[64:67]
	v_mfma_f32_16x16x32_bf16 v[116:119], v[148:151], v[204:207], v[116:119]
	v_mfma_f32_16x16x32_bf16 v[112:115], v[184:187], v[204:207], v[112:115]
	v_mfma_f32_16x16x32_bf16 v[100:103], v[148:151], v[212:215], v[100:103]
	v_mfma_f32_16x16x32_bf16 v[96:99], v[184:187], v[212:215], v[96:99]
	v_mfma_f32_16x16x32_bf16 v[84:87], v[148:151], v[220:223], v[84:87]
	v_mfma_f32_16x16x32_bf16 v[80:83], v[184:187], v[220:223], v[80:83]
	v_mfma_f32_16x16x32_bf16 v[68:71], v[148:151], v[228:231], v[68:71]
	v_mfma_f32_16x16x32_bf16 v[64:67], v[184:187], v[228:231], v[64:67]
	s_setprio 0
	s_barrier
; #define PG8_STAGE(bufoff, gbase, voff) do { _Pragma("unroll") for (int _i = 0; _i < 2; ++_i) \
;         __builtin_amdgcn_global_load_lds((const unsigned*)((const char*)(gbase) + (voff)[_i]), (LAS unsigned*)(lds + (bufoff) + ldsw + _i * 8192), 16, 0, 0); } while (0)
; #define PG8_LDA(dst, b, h) do { _Pragma("unroll") for (int m = 0; m < 4; ++m) _Pragma("unroll") for (int k = 0; k < 2; ++k) dst[m][k] = *(const LAS bf16x8*)(lds + PG8_SA(b, h) + aoff + m * 2048 + k * 1024); } while (0)
; #define PG8_MMA(ai, bj, At, Bt) do { __builtin_amdgcn_s_setprio(1); _Pragma("unroll") for (int m = 0; m < 4; ++m) _Pragma("unroll") for (int n = 0; n < 2; ++n) _Pragma("unroll") for (int k = 0; k < 2; ++k) \
;         acc[ai][bj][m][n] = __builtin_amdgcn_mfma_f32_16x16x32_bf16(Bt[n][k], At[m][k], acc[ai][bj][m][n], 0, 0, 0); __builtin_amdgcn_s_setprio(0); } while (0)
; #define PG8_WAIT_V(n) asm volatile("s_waitcnt vmcnt(" #n ")" ::: "memory")
; #define PG8_WAIT_L(n) asm volatile("s_waitcnt lgkmcnt(" #n ")" ::: "memory")
; #define PG8_BAR __builtin_amdgcn_s_barrier()
; #define PG8_SCHED __builtin_amdgcn_sched_barrier(0)
; template <class Epi, class Sched>
; __device__ __forceinline__ void gemm_phase(const int tid, LAS unsigned char* lds, const Gemm g, const Sched& S, const Epi& E) {
;     ...
;         for (int t = 0; t < nt; t += 2) {
;             const bool last = (t == nt - 2);
;             const char* a1 = cA + (size_t)(t + 1) * kstep;
;             const char* a2 = last ? nA : cA + (size_t)(t + 2) * kstep; const char* b2 = last ? nB : cB + (size_t)(t + 2) * kstep;
;             const char* a3 = a2 + kstep; const char* b3 = b2 + kstep;
;     ...
;             PG8_LDA(At, 1, 1); PG8_STAGE(PG8_SB(1, 0), b3, voffB); PG8_STAGE(PG8_SB(1, 1), b3 + hstep, voffB); PG8_STAGE(PG8_SA(1, 0), a3, voffA);
;             PG8_WAIT_V(8); PG8_WAIT_L(0); PG8_BAR; PG8_MMA(1, 0, At, B0); PG8_MMA(1, 1, At, B1); PG8_BAR; PG8_SCHED;
	s_add_i32 s28, s72, s56
	v_lshl_add_u64 v[232:233], v[232:233], 0, s[34:35]
	s_mov_b32 m0, s28
	ds_read_b128 v[188:191], v202 offset:49152
	ds_read_b128 v[204:207], v202 offset:50176
	ds_read_b128 v[208:211], v202 offset:51200
	ds_read_b128 v[212:215], v202 offset:52224
	ds_read_b128 v[216:219], v202 offset:53248
	ds_read_b128 v[220:223], v202 offset:54272
	ds_read_b128 v[224:227], v202 offset:55296
	ds_read_b128 v[228:231], v202 offset:56320
	global_load_lds_dwordx4 v[232:233], off
	s_add_i32 m0, s28, 0x2000
	s_add_u32 s26, s26, 0x80080
	v_lshl_add_u64 v[232:233], v[234:235], 0, s[34:35]
	s_addc_u32 s27, s27, 0
	s_add_i32 s28, s73, s56
	global_load_lds_dwordx4 v[232:233], off
	v_lshl_add_u64 v[232:233], s[26:27], 0, v[152:153]
	s_mov_b32 m0, s28
	s_nop 0
	global_load_lds_dwordx4 v[232:233], off
	v_lshl_add_u64 v[232:233], s[26:27], 0, v[174:175]
	s_add_i32 m0, s28, 0x2000
	s_nop 0
	global_load_lds_dwordx4 v[232:233], off
	v_lshl_add_u64 v[232:233], v[236:237], 0, s[34:35]
	s_mov_b32 m0, s64
	s_nop 0
	global_load_lds_dwordx4 v[232:233], off
	v_lshl_add_u64 v[232:233], v[238:239], 0, s[34:35]
	s_mov_b32 m0, s65
	s_nop 0
	global_load_lds_dwordx4 v[232:233], off
	s_waitcnt vmcnt(8)
	s_waitcnt lgkmcnt(0)
	s_barrier
	s_setprio 1
	s_waitcnt lgkmcnt(0)
	v_mfma_f32_16x16x32_bf16 v[60:63], v[128:131], v[188:191], v[60:63]
	v_mfma_f32_16x16x32_bf16 v[56:59], v[136:139], v[188:191], v[56:59]
	v_mfma_f32_16x16x32_bf16 v[44:47], v[128:131], v[208:211], v[44:47]
	v_mfma_f32_16x16x32_bf16 v[40:43], v[136:139], v[208:211], v[40:43]
	v_mfma_f32_16x16x32_bf16 v[28:31], v[128:131], v[216:219], v[28:31]
	v_mfma_f32_16x16x32_bf16 v[24:27], v[136:139], v[216:219], v[24:27]
	v_mfma_f32_16x16x32_bf16 v[12:15], v[128:131], v[224:227], v[12:15]
	v_mfma_f32_16x16x32_bf16 v[8:11], v[136:139], v[224:227], v[8:11]
	v_mfma_f32_16x16x32_bf16 v[60:63], v[132:135], v[204:207], v[60:63]
	v_mfma_f32_16x16x32_bf16 v[56:59], v[140:143], v[204:207], v[56:59]
	v_mfma_f32_16x16x32_bf16 v[44:47], v[132:135], v[212:215], v[44:47]
	v_mfma_f32_16x16x32_bf16 v[40:43], v[140:143], v[212:215], v[40:43]
	v_mfma_f32_16x16x32_bf16 v[28:31], v[132:135], v[220:223], v[28:31]
	v_mfma_f32_16x16x32_bf16 v[24:27], v[140:143], v[220:223], v[24:27]
	v_mfma_f32_16x16x32_bf16 v[12:15], v[132:135], v[228:231], v[12:15]
	v_mfma_f32_16x16x32_bf16 v[8:11], v[140:143], v[228:231], v[8:11]
	s_setprio 0
	s_setprio 1
	v_mfma_f32_16x16x32_bf16 v[52:55], v[144:147], v[188:191], v[52:55]
	v_mfma_f32_16x16x32_bf16 v[48:51], v[180:183], v[188:191], v[48:51]
	v_mfma_f32_16x16x32_bf16 v[36:39], v[144:147], v[208:211], v[36:39]
	v_mfma_f32_16x16x32_bf16 v[32:35], v[180:183], v[208:211], v[32:35]
	v_mfma_f32_16x16x32_bf16 v[20:23], v[144:147], v[216:219], v[20:23]
	v_mfma_f32_16x16x32_bf16 v[16:19], v[180:183], v[216:219], v[16:19]
	v_mfma_f32_16x16x32_bf16 v[4:7], v[144:147], v[224:227], v[4:7]
	v_mfma_f32_16x16x32_bf16 v[0:3], v[180:183], v[224:227], v[0:3]
	v_mfma_f32_16x16x32_bf16 v[52:55], v[148:151], v[204:207], v[52:55]
	v_mfma_f32_16x16x32_bf16 v[48:51], v[184:187], v[204:207], v[48:51]
	v_mfma_f32_16x16x32_bf16 v[36:39], v[148:151], v[212:215], v[36:39]
	v_mfma_f32_16x16x32_bf16 v[32:35], v[184:187], v[212:215], v[32:35]
	v_mfma_f32_16x16x32_bf16 v[20:23], v[148:151], v[220:223], v[20:23]
	v_mfma_f32_16x16x32_bf16 v[16:19], v[184:187], v[220:223], v[16:19]
	v_mfma_f32_16x16x32_bf16 v[4:7], v[148:151], v[228:231], v[4:7]
	v_mfma_f32_16x16x32_bf16 v[0:3], v[184:187], v[228:231], v[0:3]
	s_setprio 0
	s_barrier
	s_add_i32 s71, s71, 2
	s_add_u32 s24, s24, 0x100
	s_addc_u32 s25, s25, 0
	s_add_u32 s69, s69, 0x100
	s_addc_u32 s70, s70, 0
	s_cmp_gt_u32 s71, 29

; __device__ __forceinline__ unsigned cvt_pk_bf16(float lo, float hi) { unsigned r; asm volatile("v_cvt_pk_bf16_f32 %0, %1, %2" : "=v"(r) : "v"(lo), "v"(hi)); return r; }
;     __device__ __forceinline__ void operator()(const f32x4 (&acc)[2][2][4][2], const Unit& u, int wr, int wc, int fr, int fq) const {
;     ...
;                 for (int bj = 0; bj < 2; ++bj) xv[m][bj] = *(const u32x4*)(X + (size_t)(row0 + ai * HALF + m * 16) * ldc + col0 + bj * HALF);
;             asm volatile("" ::: "memory");
; #pragma unroll
;             for (int m = 0; m < 4; ++m) { const int row = row0 + ai * HALF + m * 16; bf16_t* rowp = X + (size_t)row * ldc + col0;
;                 float part = 0.f;
; #pragma unroll
;                 for (int bj = 0; bj < 2; ++bj) { const u32x4 x4 = xv[m][bj];
;                     const f32x4 a0 = acc[ai][bj][m][0], a1 = acc[ai][bj][m][1];
;                     const float f0 = bflo(x4.x) + a0[0], f1 = bfhi(x4.x) + a0[1], f2 = bflo(x4.y) + a0[2], f3 = bfhi(x4.y) + a0[3];
;                     const float f4 = bflo(x4.z) + a1[0], f5 = bfhi(x4.z) + a1[1], f6 = bflo(x4.w) + a1[2], f7 = bfhi(x4.w) + a1[3];
;                     part += (f0 * f0 + f1 * f1) + (f2 * f2 + f3 * f3) + (f4 * f4 + f5 * f5) + (f6 * f6 + f7 * f7);
;                     u32x4 w; w.x = cvt_pk_bf16(f0, f1); w.y = cvt_pk_bf16(f2, f3); w.z = cvt_pk_bf16(f4, f5); w.w = cvt_pk_bf16(f6, f7);
;                     *(u32x4*)(rowp + bj * HALF) = w; }
;                 part += __shfl_xor(part, 16); part += __shfl_xor(part, 32);
;                 if (fq == 0) SS[(size_t)row * 32 + u.pn * 4 + wc] = part; }
.LBB0_561:
	s_or_b64 exec, exec, s[4:5]
	v_add_u32_e32 v98, 0x80, v184
	v_ashrrev_i32_e32 v99, 31, v98
	v_lshlrev_b64 v[100:101], 12, v[98:99]
	s_waitcnt lgkmcnt(0)
	v_lshl_add_u64 v[64:65], v[182:183], 0, v[100:101]
	s_waitcnt vmcnt(12)
	v_mov_b64_e32 v[102:103], v[222:223]
	v_mov_b64_e32 v[104:105], v[224:225]
	v_mov_b64_e32 v[88:89], v[226:227]
	v_mov_b64_e32 v[90:91], v[228:229]
	v_add_u32_e32 v96, 0x90, v184
	v_ashrrev_i32_e32 v97, 31, v96
	v_lshlrev_b64 v[64:65], 12, v[96:97]
	v_add_u32_e32 v94, 0xa0, v184
	v_lshl_add_u64 v[64:65], v[182:183], 0, v[64:65]
	v_ashrrev_i32_e32 v95, 31, v94
	v_mov_b64_e32 v[84:85], v[230:231]
	v_mov_b64_e32 v[86:87], v[232:233]
	v_mov_b64_e32 v[80:81], v[234:235]
	v_mov_b64_e32 v[82:83], v[236:237]
	v_lshlrev_b64 v[64:65], 12, v[94:95]
	v_add_u32_e32 v92, 0xb0, v184
	v_lshl_add_u64 v[64:65], v[182:183], 0, v[64:65]
	v_ashrrev_i32_e32 v93, 31, v92
	v_mov_b64_e32 v[76:77], v[238:239]
	v_mov_b64_e32 v[78:79], v[240:241]
	v_mov_b64_e32 v[72:73], v[244:245]
	v_mov_b64_e32 v[74:75], v[246:247]
	v_lshlrev_b64 v[64:65], 12, v[92:93]
	v_lshl_add_u64 v[64:65], v[182:183], 0, v[64:65]
	v_mov_b64_e32 v[68:69], v[248:249]
	v_mov_b64_e32 v[70:71], v[250:251]
	s_nop 0
	v_mov_b64_e32 v[64:65], v[252:253]
	v_mov_b64_e32 v[66:67], v[254:255]
	v_lshl_add_u64 v[100:101], s[8:9], 0, v[100:101]
	v_lshl_add_u64 v[100:101], v[180:181], 1, v[100:101]
	v_lshlrev_b32_e32 v106, 16, v102
	v_and_b32_e32 v102, 0xffff0000, v102
	v_add_f32_e32 v61, v61, v102
	v_lshlrev_b32_e32 v102, 16, v103
	v_add_f32_e32 v62, v62, v102
	v_and_b32_e32 v102, 0xffff0000, v103
	v_add_f32_e32 v63, v63, v102
	v_lshlrev_b32_e32 v102, 16, v104
	v_add_f32_e32 v102, v56, v102
	v_and_b32_e32 v56, 0xffff0000, v104
	v_add_f32_e32 v103, v57, v56
	v_lshlrev_b32_e32 v56, 16, v105
	v_add_f32_e32 v104, v58, v56
	v_and_b32_e32 v56, 0xffff0000, v105
	v_add_f32_e32 v60, v60, v106
	v_add_f32_e32 v59, v59, v56
	v_mul_f32_e32 v56, v61, v61
	v_mul_f32_e32 v57, v63, v63
	v_fmac_f32_e32 v56, v60, v60
	v_fmac_f32_e32 v57, v62, v62
	v_add_f32_e32 v56, v56, v57
	v_mul_f32_e32 v57, v103, v103
	v_fmac_f32_e32 v57, v102, v102
	v_add_f32_e32 v56, v57, v56
	v_mul_f32_e32 v57, v59, v59
	v_fmac_f32_e32 v57, v104, v104
	v_add_f32_e32 v105, v57, v56
	v_cvt_pk_bf16_f32 v56, v60, v61
	v_cvt_pk_bf16_f32 v57, v62, v63
	v_cvt_pk_bf16_f32 v58, v102, v103
	v_cvt_pk_bf16_f32 v59, v104, v59
	global_store_dwordx4 v[100:101], v[56:59], off
	s_nop 0
	v_lshlrev_b32_e32 v56, 16, v88
	v_add_f32_e32 v52, v52, v56
	v_and_b32_e32 v56, 0xffff0000, v88
	v_add_f32_e32 v53, v53, v56
	v_lshlrev_b32_e32 v56, 16, v89
	v_add_f32_e32 v54, v54, v56
	v_and_b32_e32 v56, 0xffff0000, v89
	v_add_f32_e32 v55, v55, v56
	v_lshlrev_b32_e32 v56, 16, v90
	v_add_f32_e32 v56, v48, v56
	v_and_b32_e32 v48, 0xffff0000, v90
	v_add_f32_e32 v57, v49, v48
	v_lshlrev_b32_e32 v48, 16, v91
	v_add_f32_e32 v58, v50, v48
	v_and_b32_e32 v48, 0xffff0000, v91
	v_add_f32_e32 v51, v51, v48
	v_mul_f32_e32 v48, v53, v53
	v_mul_f32_e32 v49, v55, v55
	v_fmac_f32_e32 v48, v52, v52
	v_fmac_f32_e32 v49, v54, v54
	v_add_f32_e32 v48, v48, v49
	v_mul_f32_e32 v49, v57, v57
	v_fmac_f32_e32 v49, v56, v56
	v_add_f32_e32 v48, v49, v48
	v_mul_f32_e32 v49, v51, v51
	v_fmac_f32_e32 v49, v58, v58
	v_add_f32_e32 v48, v49, v48
	v_add_f32_e32 v59, v105, v48
	v_cvt_pk_bf16_f32 v48, v52, v53
	v_cvt_pk_bf16_f32 v49, v54, v55
	v_cvt_pk_bf16_f32 v50, v56, v57
	v_cvt_pk_bf16_f32 v51, v58, v51
	global_store_dwordx4 v[100:101], v[48:51], off offset:256
	ds_bpermute_b32 v48, v112, v59
	s_waitcnt lgkmcnt(0)
	v_add_f32_e32 v48, v59, v48
	ds_bpermute_b32 v49, v113, v48
	s_and_saveexec_b64 s[4:5], vcc
	s_cbranch_execz .LBB0_563
	v_lshlrev_b64 v[50:51], 7, v[98:99]
	v_lshl_add_u64 v[50:51], s[10:11], 0, v[50:51]
	v_lshl_add_u64 v[50:51], s[22:23], 2, v[50:51]
	s_lshl_b32 s76, s61, 2
	v_lshl_add_u64 v[50:51], v[50:51], 0, s[76:77]
	s_waitcnt lgkmcnt(0)
	v_add_f32_e32 v48, v48, v49
	global_store_dword v[50:51], v48, off

; #define PG8_STAGE(bufoff, gbase, voff) do { _Pragma("unroll") for (int _i = 0; _i < 2; ++_i) \
;         __builtin_amdgcn_global_load_lds((const unsigned*)((const char*)(gbase) + (voff)[_i]), (LAS unsigned*)(lds + (bufoff) + ldsw + _i * 8192), 16, 0, 0); } while (0)
; #define PG8_LDA(dst, b, h) do { _Pragma("unroll") for (int m = 0; m < 4; ++m) _Pragma("unroll") for (int k = 0; k < 2; ++k) dst[m][k] = *(const LAS bf16x8*)(lds + PG8_SA(b, h) + aoff + m * 2048 + k * 1024); } while (0)
; #define PG8_LDB(dst, b, h) do { _Pragma("unroll") for (int n = 0; n < 2; ++n) _Pragma("unroll") for (int k = 0; k < 2; ++k) dst[n][k] = *(const LAS bf16x8*)(lds + PG8_SB(b, h) + boff + n * 2048 + k * 1024); } while (0)
; #define PG8_WAIT_V(n) asm volatile("s_waitcnt vmcnt(" #n ")" ::: "memory")
; #define PG8_WAIT_L(n) asm volatile("s_waitcnt lgkmcnt(" #n ")" ::: "memory")
; template <class Epi, class Sched>
; __device__ __forceinline__ void gemm_phase(const int tid, LAS unsigned char* lds, const Gemm g, const Sched& S, const Epi& E) {
;     ...
;         const char* nA = has_next ? (const char*)g.A + (size_t)nxt.pm * tstep : cA; const char* nB = has_next ? (const char*)g.Bt + (size_t)nxt.pn * tstep : cB;
;         for (int t = 0; t < nt; t += 2) {
;             const bool last = (t == nt - 2);
;             const char* a1 = cA + (size_t)(t + 1) * kstep;
;             const char* a2 = last ? nA : cA + (size_t)(t + 2) * kstep; const char* b2 = last ? nB : cB + (size_t)(t + 2) * kstep;
;             const char* a3 = a2 + kstep; const char* b3 = b2 + kstep;
;             if (last && has_next) S.a_ready(nxt);
;             PG8_LDB(B0, 0, 0); PG8_LDB(B1, 0, 1); PG8_SCHED; PG8_LDA(At, 0, 0); PG8_STAGE(PG8_SA(1, 1), a1 + hstep, voffA);
;             PG8_WAIT_V(8); PG8_WAIT_L(0); PG8_BAR; PG8_MMA(0, 0, At, B0); PG8_MMA(0, 1, At, B1); PG8_BAR; PG8_SCHED;
;             PG8_LDA(At, 0, 1); PG8_STAGE(PG8_SB(0, 0), b2, voffB); PG8_STAGE(PG8_SB(0, 1), b2 + hstep, voffB); PG8_STAGE(PG8_SA(0, 0), a2, voffA);
;             PG8_WAIT_V(8); PG8_WAIT_L(0); PG8_BAR; PG8_MMA(1, 0, At, B0); PG8_MMA(1, 1, At, B1); PG8_BAR; PG8_SCHED;
;     ...
;         for (int a = 0; a < 2; ++a)
; #pragma unroll
;             for (int b = 0; b < 2; ++b)
; #pragma unroll
;                 for (int m = 0; m < 4; ++m)
; #pragma unroll
;                     for (int n = 0; n < 2; ++n) acc[a][b][m][n] = (f32x4){0.f, 0.f, 0.f, 0.f};
.LBB0_669:
	s_ashr_i32 s15, s14, 31
	s_lshl_b64 s[16:17], s[14:15], 20
	s_add_u32 s16, s56, s16
	s_addc_u32 s17, s57, s17
	s_and_b64 s[18:19], s[0:1], exec
	s_cselect_b32 s15, s17, s23
	s_cselect_b32 s68, s16, s22
	s_ashr_i32 s13, s12, 31
	s_lshl_b64 s[18:19], s[12:13], 20
	s_add_u32 s18, s41, s18
	s_addc_u32 s19, s55, s19
	s_and_b64 s[26:27], s[0:1], exec
	s_cselect_b32 s13, s19, s25
	s_cselect_b32 s69, s18, s24
	s_add_u32 s22, s22, 0x80080
	s_addc_u32 s23, s23, 0
	s_add_u32 s70, s24, 0x100
	v_mov_b32_e32 v0, 0
	s_addc_u32 s71, s25, 0
	s_mov_b32 s72, -2
	s_add_u32 s24, s22, 0xfff80080
	s_addc_u32 s25, s23, -1
	s_add_i32 s73, 0, 0x10000
	s_cmp_eq_u32 s72, 28
	s_cselect_b32 s27, s15, s25
	s_cselect_b32 s26, s68, s24
	s_cselect_b32 s25, s13, s71
	s_cselect_b32 s24, s69, s70
	s_add_i32 s76, 0, 0x14000
	v_add_u32_e32 v172, s73, v170
	v_add_u32_e32 v188, s76, v170
	ds_read_b128 v[138:141], v172
	ds_read_b128 v[142:145], v172 offset:1024
	ds_read_b128 v[146:149], v172 offset:2048
	ds_read_b128 v[172:175], v172 offset:3072
	ds_read_b128 v[176:179], v188
	ds_read_b128 v[180:183], v188 offset:1024
	ds_read_b128 v[184:187], v188 offset:2048
	ds_read_b128 v[188:191], v188 offset:3072
	v_lshl_add_u64 v[232:233], s[22:23], 0, v[134:135]
	s_add_i32 m0, s58, 0xc000
	ds_read_b128 v[200:203], v171
	ds_read_b128 v[204:207], v171 offset:1024
	ds_read_b128 v[208:211], v171 offset:2048
	ds_read_b128 v[212:215], v171 offset:3072
	ds_read_b128 v[216:219], v171 offset:4096
	ds_read_b128 v[220:223], v171 offset:5120
	ds_read_b128 v[224:227], v171 offset:6144
	ds_read_b128 v[228:231], v171 offset:7168
	global_load_lds_dwordx4 v[232:233], off
	v_lshl_add_u64 v[232:233], s[22:23], 0, v[136:137]
	s_add_i32 m0, s58, 0xe000
	s_nop 0
	global_load_lds_dwordx4 v[232:233], off
	s_waitcnt vmcnt(8)
	s_waitcnt lgkmcnt(0)
	s_barrier
	s_setprio 1
	s_waitcnt lgkmcnt(0)
	v_mfma_f32_16x16x32_bf16 v[124:127], v[138:141], v[200:203], 0
	v_mfma_f32_16x16x32_bf16 v[116:119], v[146:149], v[200:203], 0
	v_mfma_f32_16x16x32_bf16 v[108:111], v[138:141], v[208:211], 0
	v_mfma_f32_16x16x32_bf16 v[100:103], v[146:149], v[208:211], 0
	v_mfma_f32_16x16x32_bf16 v[92:95], v[138:141], v[216:219], 0
	v_mfma_f32_16x16x32_bf16 v[84:87], v[146:149], v[216:219], 0
	v_mfma_f32_16x16x32_bf16 v[76:79], v[138:141], v[224:227], 0
	v_mfma_f32_16x16x32_bf16 v[68:71], v[146:149], v[224:227], 0
	v_mfma_f32_16x16x32_bf16 v[124:127], v[142:145], v[204:207], v[124:127]
	v_mfma_f32_16x16x32_bf16 v[116:119], v[172:175], v[204:207], v[116:119]
	v_mfma_f32_16x16x32_bf16 v[108:111], v[142:145], v[212:215], v[108:111]
	v_mfma_f32_16x16x32_bf16 v[100:103], v[172:175], v[212:215], v[100:103]
	v_mfma_f32_16x16x32_bf16 v[92:95], v[142:145], v[220:223], v[92:95]
	v_mfma_f32_16x16x32_bf16 v[84:87], v[172:175], v[220:223], v[84:87]
	v_mfma_f32_16x16x32_bf16 v[76:79], v[142:145], v[228:231], v[76:79]
	v_mfma_f32_16x16x32_bf16 v[68:71], v[172:175], v[228:231], v[68:71]
	s_setprio 0
	s_setprio 1
	v_mfma_f32_16x16x32_bf16 v[120:123], v[176:179], v[200:203], 0
	v_mfma_f32_16x16x32_bf16 v[112:115], v[184:187], v[200:203], 0
	v_mfma_f32_16x16x32_bf16 v[104:107], v[176:179], v[208:211], 0
	v_mfma_f32_16x16x32_bf16 v[96:99], v[184:187], v[208:211], 0
	v_mfma_f32_16x16x32_bf16 v[88:91], v[176:179], v[216:219], 0
	v_mfma_f32_16x16x32_bf16 v[80:83], v[184:187], v[216:219], 0
	v_mfma_f32_16x16x32_bf16 v[72:75], v[176:179], v[224:227], 0
	v_mfma_f32_16x16x32_bf16 v[64:67], v[184:187], v[224:227], 0
	v_mfma_f32_16x16x32_bf16 v[120:123], v[180:183], v[204:207], v[120:123]
	v_mfma_f32_16x16x32_bf16 v[112:115], v[188:191], v[204:207], v[112:115]
	v_mfma_f32_16x16x32_bf16 v[104:107], v[180:183], v[212:215], v[104:107]
	v_mfma_f32_16x16x32_bf16 v[96:99], v[188:191], v[212:215], v[96:99]
	v_mfma_f32_16x16x32_bf16 v[88:91], v[180:183], v[220:223], v[88:91]
	v_mfma_f32_16x16x32_bf16 v[80:83], v[188:191], v[220:223], v[80:83]
	v_mfma_f32_16x16x32_bf16 v[72:75], v[180:183], v[228:231], v[72:75]
	v_mfma_f32_16x16x32_bf16 v[64:67], v[188:191], v[228:231], v[64:67]
	s_setprio 0
	s_barrier
	s_add_i32 s73, s73, s40
	v_lshl_add_u64 v[232:233], s[24:25], 0, v[152:153]
	s_mov_b32 m0, s73
	ds_read_b128 v[200:203], v171 offset:16384
	ds_read_b128 v[204:207], v171 offset:17408
	ds_read_b128 v[208:211], v171 offset:18432
	ds_read_b128 v[212:215], v171 offset:19456
	ds_read_b128 v[216:219], v171 offset:20480
	ds_read_b128 v[220:223], v171 offset:21504
	ds_read_b128 v[224:227], v171 offset:22528
	ds_read_b128 v[228:231], v171 offset:23552
	global_load_lds_dwordx4 v[232:233], off
	s_add_i32 m0, s73, 0x2000
	s_add_u32 s74, s24, 0x80000
	v_lshl_add_u64 v[234:235], s[24:25], 0, v[128:129]
	s_addc_u32 s75, s25, 0
	s_add_i32 s73, s76, s40
	global_load_lds_dwordx4 v[234:235], off
	v_lshl_add_u64 v[236:237], s[74:75], 0, v[152:153]
	s_mov_b32 m0, s73
	v_lshl_add_u64 v[238:239], s[26:27], 0, v[130:131]
	global_load_lds_dwordx4 v[236:237], off
	v_lshl_add_u64 v[236:237], s[74:75], 0, v[128:129]
	s_add_i32 m0, s73, 0x2000
	s_nop 0
	global_load_lds_dwordx4 v[236:237], off
	v_lshl_add_u64 v[236:237], s[26:27], 0, v[132:133]
	s_mov_b32 m0, s58
	s_nop 0
	global_load_lds_dwordx4 v[236:237], off
	s_mov_b32 m0, s59
	s_nop 0
	global_load_lds_dwordx4 v[238:239], off
	s_waitcnt vmcnt(8)
	s_waitcnt lgkmcnt(0)
	s_barrier
; #define PG8_STAGE(bufoff, gbase, voff) do { _Pragma("unroll") for (int _i = 0; _i < 2; ++_i) \
;         __builtin_amdgcn_global_load_lds((const unsigned*)((const char*)(gbase) + (voff)[_i]), (LAS unsigned*)(lds + (bufoff) + ldsw + _i * 8192), 16, 0, 0); } while (0)
; #define PG8_LDA(dst, b, h) do { _Pragma("unroll") for (int m = 0; m < 4; ++m) _Pragma("unroll") for (int k = 0; k < 2; ++k) dst[m][k] = *(const LAS bf16x8*)(lds + PG8_SA(b, h) + aoff + m * 2048 + k * 1024); } while (0)
; #define PG8_LDB(dst, b, h) do { _Pragma("unroll") for (int n = 0; n < 2; ++n) _Pragma("unroll") for (int k = 0; k < 2; ++k) dst[n][k] = *(const LAS bf16x8*)(lds + PG8_SB(b, h) + boff + n * 2048 + k * 1024); } while (0)
; #define PG8_MMA(ai, bj, At, Bt) do { __builtin_amdgcn_s_setprio(1); _Pragma("unroll") for (int m = 0; m < 4; ++m) _Pragma("unroll") for (int n = 0; n < 2; ++n) _Pragma("unroll") for (int k = 0; k < 2; ++k) \
;         acc[ai][bj][m][n] = __builtin_amdgcn_mfma_f32_16x16x32_bf16(Bt[n][k], At[m][k], acc[ai][bj][m][n], 0, 0, 0); __builtin_amdgcn_s_setprio(0); } while (0)
; #define PG8_WAIT_V(n) asm volatile("s_waitcnt vmcnt(" #n ")" ::: "memory")
; #define PG8_WAIT_L(n) asm volatile("s_waitcnt lgkmcnt(" #n ")" ::: "memory")
; #define PG8_BAR __builtin_amdgcn_s_barrier()
; #define PG8_SCHED __builtin_amdgcn_sched_barrier(0)
; template <class Epi, class Sched>
; __device__ __forceinline__ void gemm_phase(const int tid, LAS unsigned char* lds, const Gemm g, const Sched& S, const Epi& E) {
;     ...
;             PG8_WAIT_V(8); PG8_WAIT_L(0); PG8_BAR; PG8_MMA(1, 0, At, B0); PG8_MMA(1, 1, At, B1); PG8_BAR; PG8_SCHED;
;             PG8_LDB(B0, 1, 0); PG8_LDB(B1, 1, 1); PG8_SCHED; PG8_LDA(At, 1, 0); PG8_STAGE(PG8_SA(0, 1), a2 + hstep, voffA);
;             PG8_WAIT_V(8); PG8_WAIT_L(0); PG8_BAR; PG8_MMA(0, 0, At, B0); PG8_MMA(0, 1, At, B1); PG8_BAR; PG8_SCHED;
;             PG8_LDA(At, 1, 1); PG8_STAGE(PG8_SB(1, 0), b3, voffB); PG8_STAGE(PG8_SB(1, 1), b3 + hstep, voffB); PG8_STAGE(PG8_SA(1, 0), a3, voffA);
;             PG8_WAIT_V(8); PG8_WAIT_L(0); PG8_BAR; PG8_MMA(1, 0, At, B0); PG8_MMA(1, 1, At, B1); PG8_BAR; PG8_SCHED;
	s_setprio 1
	s_waitcnt lgkmcnt(0)
	v_mfma_f32_16x16x32_bf16 v[60:63], v[138:141], v[200:203], 0
	v_mfma_f32_16x16x32_bf16 v[52:55], v[146:149], v[200:203], 0
	v_mfma_f32_16x16x32_bf16 v[44:47], v[138:141], v[208:211], 0
	v_mfma_f32_16x16x32_bf16 v[36:39], v[146:149], v[208:211], 0
	v_mfma_f32_16x16x32_bf16 v[28:31], v[138:141], v[216:219], 0
	v_mfma_f32_16x16x32_bf16 v[20:23], v[146:149], v[216:219], 0
	v_mfma_f32_16x16x32_bf16 v[12:15], v[138:141], v[224:227], 0
	v_mfma_f32_16x16x32_bf16 v[4:7], v[146:149], v[224:227], 0
	v_mfma_f32_16x16x32_bf16 v[60:63], v[142:145], v[204:207], v[60:63]
	v_mfma_f32_16x16x32_bf16 v[52:55], v[172:175], v[204:207], v[52:55]
	v_mfma_f32_16x16x32_bf16 v[44:47], v[142:145], v[212:215], v[44:47]
	v_mfma_f32_16x16x32_bf16 v[36:39], v[172:175], v[212:215], v[36:39]
	v_mfma_f32_16x16x32_bf16 v[28:31], v[142:145], v[220:223], v[28:31]
	v_mfma_f32_16x16x32_bf16 v[20:23], v[172:175], v[220:223], v[20:23]
	v_mfma_f32_16x16x32_bf16 v[12:15], v[142:145], v[228:231], v[12:15]
	v_mfma_f32_16x16x32_bf16 v[4:7], v[172:175], v[228:231], v[4:7]
	s_setprio 0
	s_setprio 1
	v_mfma_f32_16x16x32_bf16 v[56:59], v[176:179], v[200:203], 0
	v_mfma_f32_16x16x32_bf16 v[48:51], v[184:187], v[200:203], 0
	v_mfma_f32_16x16x32_bf16 v[40:43], v[176:179], v[208:211], 0
	v_mfma_f32_16x16x32_bf16 v[32:35], v[184:187], v[208:211], 0
	v_mfma_f32_16x16x32_bf16 v[24:27], v[176:179], v[216:219], 0
	v_mfma_f32_16x16x32_bf16 v[16:19], v[184:187], v[216:219], 0
	v_mfma_f32_16x16x32_bf16 v[8:11], v[176:179], v[224:227], 0
	v_mfma_f32_16x16x32_bf16 v[0:3], v[184:187], v[224:227], 0
	v_mfma_f32_16x16x32_bf16 v[56:59], v[180:183], v[204:207], v[56:59]
	v_mfma_f32_16x16x32_bf16 v[48:51], v[188:191], v[204:207], v[48:51]
	v_mfma_f32_16x16x32_bf16 v[40:43], v[180:183], v[212:215], v[40:43]
	v_mfma_f32_16x16x32_bf16 v[32:35], v[188:191], v[212:215], v[32:35]
	v_mfma_f32_16x16x32_bf16 v[24:27], v[180:183], v[220:223], v[24:27]
	v_mfma_f32_16x16x32_bf16 v[16:19], v[188:191], v[220:223], v[16:19]
	v_mfma_f32_16x16x32_bf16 v[8:11], v[180:183], v[228:231], v[8:11]
	v_mfma_f32_16x16x32_bf16 v[0:3], v[188:191], v[228:231], v[0:3]
	s_setprio 0
	s_barrier
	s_add_i32 s73, 0, 0x18000
	s_add_i32 s74, 0, 0x1c000
	v_add_u32_e32 v172, s73, v170
	v_add_u32_e32 v188, s74, v170
	ds_read_b128 v[138:141], v172
	ds_read_b128 v[142:145], v172 offset:1024
	ds_read_b128 v[146:149], v172 offset:2048
	ds_read_b128 v[172:175], v172 offset:3072
	ds_read_b128 v[176:179], v188
	ds_read_b128 v[180:183], v188 offset:1024
	ds_read_b128 v[184:187], v188 offset:2048
	ds_read_b128 v[188:191], v188 offset:3072
	s_add_u32 s26, s26, 0x80000
	s_addc_u32 s27, s27, 0
	s_mov_b32 m0, s60
	v_lshl_add_u64 v[240:241], s[26:27], 0, v[132:133]
	ds_read_b128 v[200:203], v171 offset:32768
	ds_read_b128 v[204:207], v171 offset:33792
	ds_read_b128 v[208:211], v171 offset:34816
	ds_read_b128 v[212:215], v171 offset:35840
	ds_read_b128 v[216:219], v171 offset:36864
	ds_read_b128 v[220:223], v171 offset:37888
	ds_read_b128 v[224:227], v171 offset:38912
	ds_read_b128 v[228:231], v171 offset:39936
	global_load_lds_dwordx4 v[240:241], off
	v_lshl_add_u64 v[240:241], s[26:27], 0, v[130:131]
	s_mov_b32 m0, s61
	s_nop 0
	global_load_lds_dwordx4 v[240:241], off
	s_waitcnt vmcnt(8)
	s_waitcnt lgkmcnt(0)
	s_barrier
	s_setprio 1
	s_waitcnt lgkmcnt(0)
	v_mfma_f32_16x16x32_bf16 v[124:127], v[138:141], v[200:203], v[124:127]
	v_mfma_f32_16x16x32_bf16 v[116:119], v[146:149], v[200:203], v[116:119]
	v_mfma_f32_16x16x32_bf16 v[108:111], v[138:141], v[208:211], v[108:111]
	v_mfma_f32_16x16x32_bf16 v[100:103], v[146:149], v[208:211], v[100:103]
	v_mfma_f32_16x16x32_bf16 v[92:95], v[138:141], v[216:219], v[92:95]
	v_mfma_f32_16x16x32_bf16 v[84:87], v[146:149], v[216:219], v[84:87]
	v_mfma_f32_16x16x32_bf16 v[76:79], v[138:141], v[224:227], v[76:79]
	v_mfma_f32_16x16x32_bf16 v[68:71], v[146:149], v[224:227], v[68:71]
	v_mfma_f32_16x16x32_bf16 v[124:127], v[142:145], v[204:207], v[124:127]
	v_mfma_f32_16x16x32_bf16 v[116:119], v[172:175], v[204:207], v[116:119]
	v_mfma_f32_16x16x32_bf16 v[108:111], v[142:145], v[212:215], v[108:111]
	v_mfma_f32_16x16x32_bf16 v[100:103], v[172:175], v[212:215], v[100:103]
	v_mfma_f32_16x16x32_bf16 v[92:95], v[142:145], v[220:223], v[92:95]
	v_mfma_f32_16x16x32_bf16 v[84:87], v[172:175], v[220:223], v[84:87]
	v_mfma_f32_16x16x32_bf16 v[76:79], v[142:145], v[228:231], v[76:79]
	v_mfma_f32_16x16x32_bf16 v[68:71], v[172:175], v[228:231], v[68:71]
	s_setprio 0
	s_setprio 1
	v_mfma_f32_16x16x32_bf16 v[120:123], v[176:179], v[200:203], v[120:123]
	v_mfma_f32_16x16x32_bf16 v[112:115], v[184:187], v[200:203], v[112:115]
	v_mfma_f32_16x16x32_bf16 v[104:107], v[176:179], v[208:211], v[104:107]
	v_mfma_f32_16x16x32_bf16 v[96:99], v[184:187], v[208:211], v[96:99]
	v_mfma_f32_16x16x32_bf16 v[88:91], v[176:179], v[216:219], v[88:91]
	v_mfma_f32_16x16x32_bf16 v[80:83], v[184:187], v[216:219], v[80:83]
	v_mfma_f32_16x16x32_bf16 v[72:75], v[176:179], v[224:227], v[72:75]
	v_mfma_f32_16x16x32_bf16 v[64:67], v[184:187], v[224:227], v[64:67]
	v_mfma_f32_16x16x32_bf16 v[120:123], v[180:183], v[204:207], v[120:123]
	v_mfma_f32_16x16x32_bf16 v[112:115], v[188:191], v[204:207], v[112:115]
	v_mfma_f32_16x16x32_bf16 v[104:107], v[180:183], v[212:215], v[104:107]
	v_mfma_f32_16x16x32_bf16 v[96:99], v[188:191], v[212:215], v[96:99]
	v_mfma_f32_16x16x32_bf16 v[88:91], v[180:183], v[220:223], v[88:91]
	v_mfma_f32_16x16x32_bf16 v[80:83], v[188:191], v[220:223], v[80:83]
	v_mfma_f32_16x16x32_bf16 v[72:75], v[180:183], v[228:231], v[72:75]
	v_mfma_f32_16x16x32_bf16 v[64:67], v[188:191], v[228:231], v[64:67]
	s_setprio 0
	s_barrier
; #define PG8_STAGE(bufoff, gbase, voff) do { _Pragma("unroll") for (int _i = 0; _i < 2; ++_i) \
;         __builtin_amdgcn_global_load_lds((const unsigned*)((const char*)(gbase) + (voff)[_i]), (LAS unsigned*)(lds + (bufoff) + ldsw + _i * 8192), 16, 0, 0); } while (0)
; #define PG8_LDA(dst, b, h) do { _Pragma("unroll") for (int m = 0; m < 4; ++m) _Pragma("unroll") for (int k = 0; k < 2; ++k) dst[m][k] = *(const LAS bf16x8*)(lds + PG8_SA(b, h) + aoff + m * 2048 + k * 1024); } while (0)
; #define PG8_MMA(ai, bj, At, Bt) do { __builtin_amdgcn_s_setprio(1); _Pragma("unroll") for (int m = 0; m < 4; ++m) _Pragma("unroll") for (int n = 0; n < 2; ++n) _Pragma("unroll") for (int k = 0; k < 2; ++k) \
;         acc[ai][bj][m][n] = __builtin_amdgcn_mfma_f32_16x16x32_bf16(Bt[n][k], At[m][k], acc[ai][bj][m][n], 0, 0, 0); __builtin_amdgcn_s_setprio(0); } while (0)
; #define PG8_WAIT_V(n) asm volatile("s_waitcnt vmcnt(" #n ")" ::: "memory")
; #define PG8_WAIT_L(n) asm volatile("s_waitcnt lgkmcnt(" #n ")" ::: "memory")
; #define PG8_BAR __builtin_amdgcn_s_barrier()
; #define PG8_SCHED __builtin_amdgcn_sched_barrier(0)
; template <class Epi, class Sched>
; __device__ __forceinline__ void gemm_phase(const int tid, LAS unsigned char* lds, const Gemm g, const Sched& S, const Epi& E) {
;     ...
;         for (int t = 0; t < nt; t += 2) {
;             const bool last = (t == nt - 2);
;             const char* a1 = cA + (size_t)(t + 1) * kstep;
;             const char* a2 = last ? nA : cA + (size_t)(t + 2) * kstep; const char* b2 = last ? nB : cB + (size_t)(t + 2) * kstep;
;             const char* a3 = a2 + kstep; const char* b3 = b2 + kstep;
;     ...
;             PG8_LDA(At, 1, 1); PG8_STAGE(PG8_SB(1, 0), b3, voffB); PG8_STAGE(PG8_SB(1, 1), b3 + hstep, voffB); PG8_STAGE(PG8_SA(1, 0), a3, voffA);
;             PG8_WAIT_V(8); PG8_WAIT_L(0); PG8_BAR; PG8_MMA(1, 0, At, B0); PG8_MMA(1, 1, At, B1); PG8_BAR; PG8_SCHED;
	s_add_i32 s26, s73, s40
	v_lshl_add_u64 v[232:233], v[232:233], 0, s[34:35]
	s_mov_b32 m0, s26
	ds_read_b128 v[200:203], v171 offset:49152
	ds_read_b128 v[204:207], v171 offset:50176
	ds_read_b128 v[208:211], v171 offset:51200
	ds_read_b128 v[212:215], v171 offset:52224
	ds_read_b128 v[216:219], v171 offset:53248
	ds_read_b128 v[220:223], v171 offset:54272
	ds_read_b128 v[224:227], v171 offset:55296
	ds_read_b128 v[228:231], v171 offset:56320
	global_load_lds_dwordx4 v[232:233], off
	s_add_i32 m0, s26, 0x2000
	s_add_u32 s24, s24, 0x80080
	v_lshl_add_u64 v[232:233], v[234:235], 0, s[34:35]
	s_addc_u32 s25, s25, 0
	s_add_i32 s26, s74, s40
	global_load_lds_dwordx4 v[232:233], off
	v_lshl_add_u64 v[232:233], s[24:25], 0, v[152:153]
	s_mov_b32 m0, s26
	s_nop 0
	global_load_lds_dwordx4 v[232:233], off
	v_lshl_add_u64 v[232:233], s[24:25], 0, v[128:129]
	s_add_i32 m0, s26, 0x2000
	s_nop 0
	global_load_lds_dwordx4 v[232:233], off
	v_lshl_add_u64 v[232:233], v[236:237], 0, s[34:35]
	s_mov_b32 m0, s64
	s_nop 0
	global_load_lds_dwordx4 v[232:233], off
	v_lshl_add_u64 v[232:233], v[238:239], 0, s[34:35]
	s_mov_b32 m0, s65
	s_nop 0
	global_load_lds_dwordx4 v[232:233], off
	s_waitcnt vmcnt(8)
	s_waitcnt lgkmcnt(0)
	s_barrier
	s_setprio 1
	s_waitcnt lgkmcnt(0)
	v_mfma_f32_16x16x32_bf16 v[60:63], v[138:141], v[200:203], v[60:63]
	v_mfma_f32_16x16x32_bf16 v[52:55], v[146:149], v[200:203], v[52:55]
	v_mfma_f32_16x16x32_bf16 v[44:47], v[138:141], v[208:211], v[44:47]
	v_mfma_f32_16x16x32_bf16 v[36:39], v[146:149], v[208:211], v[36:39]
	v_mfma_f32_16x16x32_bf16 v[28:31], v[138:141], v[216:219], v[28:31]
	v_mfma_f32_16x16x32_bf16 v[20:23], v[146:149], v[216:219], v[20:23]
	v_mfma_f32_16x16x32_bf16 v[12:15], v[138:141], v[224:227], v[12:15]
	v_mfma_f32_16x16x32_bf16 v[4:7], v[146:149], v[224:227], v[4:7]
	v_mfma_f32_16x16x32_bf16 v[60:63], v[142:145], v[204:207], v[60:63]
	v_mfma_f32_16x16x32_bf16 v[52:55], v[172:175], v[204:207], v[52:55]
	v_mfma_f32_16x16x32_bf16 v[44:47], v[142:145], v[212:215], v[44:47]
	v_mfma_f32_16x16x32_bf16 v[36:39], v[172:175], v[212:215], v[36:39]
	v_mfma_f32_16x16x32_bf16 v[28:31], v[142:145], v[220:223], v[28:31]
	v_mfma_f32_16x16x32_bf16 v[20:23], v[172:175], v[220:223], v[20:23]
	v_mfma_f32_16x16x32_bf16 v[12:15], v[142:145], v[228:231], v[12:15]
	v_mfma_f32_16x16x32_bf16 v[4:7], v[172:175], v[228:231], v[4:7]
	s_setprio 0
	s_setprio 1
	v_mfma_f32_16x16x32_bf16 v[56:59], v[176:179], v[200:203], v[56:59]
	v_mfma_f32_16x16x32_bf16 v[48:51], v[184:187], v[200:203], v[48:51]
	v_mfma_f32_16x16x32_bf16 v[40:43], v[176:179], v[208:211], v[40:43]
	v_mfma_f32_16x16x32_bf16 v[32:35], v[184:187], v[208:211], v[32:35]
	v_mfma_f32_16x16x32_bf16 v[24:27], v[176:179], v[216:219], v[24:27]
	v_mfma_f32_16x16x32_bf16 v[16:19], v[184:187], v[216:219], v[16:19]
	v_mfma_f32_16x16x32_bf16 v[8:11], v[176:179], v[224:227], v[8:11]
	v_mfma_f32_16x16x32_bf16 v[0:3], v[184:187], v[224:227], v[0:3]
	v_mfma_f32_16x16x32_bf16 v[56:59], v[180:183], v[204:207], v[56:59]
	v_mfma_f32_16x16x32_bf16 v[48:51], v[188:191], v[204:207], v[48:51]
	v_mfma_f32_16x16x32_bf16 v[40:43], v[180:183], v[212:215], v[40:43]
	v_mfma_f32_16x16x32_bf16 v[32:35], v[188:191], v[212:215], v[32:35]
	v_mfma_f32_16x16x32_bf16 v[24:27], v[180:183], v[220:223], v[24:27]
	v_mfma_f32_16x16x32_bf16 v[16:19], v[188:191], v[220:223], v[16:19]
	v_mfma_f32_16x16x32_bf16 v[8:11], v[180:183], v[228:231], v[8:11]
	v_mfma_f32_16x16x32_bf16 v[0:3], v[188:191], v[228:231], v[0:3]
	s_setprio 0
	s_barrier
	s_add_i32 s72, s72, 2
	s_add_u32 s22, s22, 0x100
	s_addc_u32 s23, s23, 0
	s_add_u32 s70, s70, 0x100
	s_addc_u32 s71, s71, 0
	s_cmp_gt_u32 s72, 29

; #define PG8_STAGE(bufoff, gbase, voff) do { _Pragma("unroll") for (int _i = 0; _i < 2; ++_i) \
;         __builtin_amdgcn_global_load_lds((const unsigned*)((const char*)(gbase) + (voff)[_i]), (LAS unsigned*)(lds + (bufoff) + ldsw + _i * 8192), 16, 0, 0); } while (0)
; #define PG8_LDA(dst, b, h) do { _Pragma("unroll") for (int m = 0; m < 4; ++m) _Pragma("unroll") for (int k = 0; k < 2; ++k) dst[m][k] = *(const LAS bf16x8*)(lds + PG8_SA(b, h) + aoff + m * 2048 + k * 1024); } while (0)
; #define PG8_LDB(dst, b, h) do { _Pragma("unroll") for (int n = 0; n < 2; ++n) _Pragma("unroll") for (int k = 0; k < 2; ++k) dst[n][k] = *(const LAS bf16x8*)(lds + PG8_SB(b, h) + boff + n * 2048 + k * 1024); } while (0)
; #define PG8_WAIT_V(n) asm volatile("s_waitcnt vmcnt(" #n ")" ::: "memory")
; #define PG8_WAIT_L(n) asm volatile("s_waitcnt lgkmcnt(" #n ")" ::: "memory")
; template <class Epi, class Sched>
; __device__ __forceinline__ void gemm_phase(const int tid, LAS unsigned char* lds, const Gemm g, const Sched& S, const Epi& E) {
;     ...
;         const char* nA = has_next ? (const char*)g.A + (size_t)nxt.pm * tstep : cA; const char* nB = has_next ? (const char*)g.Bt + (size_t)nxt.pn * tstep : cB;
;         for (int t = 0; t < nt; t += 2) {
;             const bool last = (t == nt - 2);
;             const char* a1 = cA + (size_t)(t + 1) * kstep;
;             const char* a2 = last ? nA : cA + (size_t)(t + 2) * kstep; const char* b2 = last ? nB : cB + (size_t)(t + 2) * kstep;
;             const char* a3 = a2 + kstep; const char* b3 = b2 + kstep;
;             if (last && has_next) S.a_ready(nxt);
;             PG8_LDB(B0, 0, 0); PG8_LDB(B1, 0, 1); PG8_SCHED; PG8_LDA(At, 0, 0); PG8_STAGE(PG8_SA(1, 1), a1 + hstep, voffA);
;             PG8_WAIT_V(8); PG8_WAIT_L(0); PG8_BAR; PG8_MMA(0, 0, At, B0); PG8_MMA(0, 1, At, B1); PG8_BAR; PG8_SCHED;
;             PG8_LDA(At, 0, 1); PG8_STAGE(PG8_SB(0, 0), b2, voffB); PG8_STAGE(PG8_SB(0, 1), b2 + hstep, voffB); PG8_STAGE(PG8_SA(0, 0), a2, voffA);
;             PG8_WAIT_V(8); PG8_WAIT_L(0); PG8_BAR; PG8_MMA(1, 0, At, B0); PG8_MMA(1, 1, At, B1); PG8_BAR; PG8_SCHED;
;     ...
;         for (int a = 0; a < 2; ++a)
; #pragma unroll
;             for (int b = 0; b < 2; ++b)
; #pragma unroll
;                 for (int m = 0; m < 4; ++m)
; #pragma unroll
;                     for (int n = 0; n < 2; ++n) acc[a][b][m][n] = (f32x4){0.f, 0.f, 0.f, 0.f};
.LBB0_762:
	s_add_u32 s67, s20, 0x100
	v_mov_b32_e32 v0, 0
	s_addc_u32 s68, s21, 0
	s_mov_b32 s69, -2
	s_waitcnt lgkmcnt(0)
	s_add_u32 s4, s18, 0x100
	s_addc_u32 s5, s19, 0
	s_add_i32 s70, 0, 0x10000
	s_cmpk_eq_i32 s69, 0x54
	s_cselect_b32 s23, s15, s5
	s_cselect_b32 s22, s14, s4
	s_cselect_b32 s21, s17, s68
	s_cselect_b32 s20, s16, s67
	s_add_i32 s71, 0, 0x14000
	v_add_u32_e32 v140, s70, v201
	v_add_u32_e32 v184, s71, v201
	ds_read_b128 v[128:131], v140
	ds_read_b128 v[132:135], v140 offset:1024
	ds_read_b128 v[136:139], v140 offset:2048
	ds_read_b128 v[140:143], v140 offset:3072
	ds_read_b128 v[144:147], v184
	ds_read_b128 v[148:151], v184 offset:1024
	ds_read_b128 v[180:183], v184 offset:2048
	ds_read_b128 v[184:187], v184 offset:3072
	v_lshl_add_u64 v[232:233], s[18:19], 0, v[176:177]
	s_add_i32 m0, s38, 0xc000
	ds_read_b128 v[188:191], v202
	ds_read_b128 v[204:207], v202 offset:1024
	ds_read_b128 v[208:211], v202 offset:2048
	ds_read_b128 v[212:215], v202 offset:3072
	ds_read_b128 v[216:219], v202 offset:4096
	ds_read_b128 v[220:223], v202 offset:5120
	ds_read_b128 v[224:227], v202 offset:6144
	ds_read_b128 v[228:231], v202 offset:7168
	global_load_lds_dwordx4 v[232:233], off
	v_lshl_add_u64 v[232:233], s[18:19], 0, v[178:179]
	s_add_i32 m0, s38, 0xe000
	s_nop 0
	global_load_lds_dwordx4 v[232:233], off
	s_waitcnt vmcnt(8)
	s_waitcnt lgkmcnt(0)
	s_barrier
	s_setprio 1
	s_waitcnt lgkmcnt(0)
	v_mfma_f32_16x16x32_bf16 v[124:127], v[128:131], v[188:191], 0
	v_mfma_f32_16x16x32_bf16 v[120:123], v[136:139], v[188:191], 0
	v_mfma_f32_16x16x32_bf16 v[108:111], v[128:131], v[208:211], 0
	v_mfma_f32_16x16x32_bf16 v[104:107], v[136:139], v[208:211], 0
	v_mfma_f32_16x16x32_bf16 v[92:95], v[128:131], v[216:219], 0
	v_mfma_f32_16x16x32_bf16 v[88:91], v[136:139], v[216:219], 0
	v_mfma_f32_16x16x32_bf16 v[76:79], v[128:131], v[224:227], 0
	v_mfma_f32_16x16x32_bf16 v[72:75], v[136:139], v[224:227], 0
	v_mfma_f32_16x16x32_bf16 v[124:127], v[132:135], v[204:207], v[124:127]
	v_mfma_f32_16x16x32_bf16 v[120:123], v[140:143], v[204:207], v[120:123]
	v_mfma_f32_16x16x32_bf16 v[108:111], v[132:135], v[212:215], v[108:111]
	v_mfma_f32_16x16x32_bf16 v[104:107], v[140:143], v[212:215], v[104:107]
	v_mfma_f32_16x16x32_bf16 v[92:95], v[132:135], v[220:223], v[92:95]
	v_mfma_f32_16x16x32_bf16 v[88:91], v[140:143], v[220:223], v[88:91]
	v_mfma_f32_16x16x32_bf16 v[76:79], v[132:135], v[228:231], v[76:79]
	v_mfma_f32_16x16x32_bf16 v[72:75], v[140:143], v[228:231], v[72:75]
	s_setprio 0
	s_setprio 1
	v_mfma_f32_16x16x32_bf16 v[116:119], v[144:147], v[188:191], 0
	v_mfma_f32_16x16x32_bf16 v[112:115], v[180:183], v[188:191], 0
	v_mfma_f32_16x16x32_bf16 v[100:103], v[144:147], v[208:211], 0
	v_mfma_f32_16x16x32_bf16 v[96:99], v[180:183], v[208:211], 0
	v_mfma_f32_16x16x32_bf16 v[84:87], v[144:147], v[216:219], 0
	v_mfma_f32_16x16x32_bf16 v[80:83], v[180:183], v[216:219], 0
	v_mfma_f32_16x16x32_bf16 v[68:71], v[144:147], v[224:227], 0
	v_mfma_f32_16x16x32_bf16 v[64:67], v[180:183], v[224:227], 0
	v_mfma_f32_16x16x32_bf16 v[116:119], v[148:151], v[204:207], v[116:119]
	v_mfma_f32_16x16x32_bf16 v[112:115], v[184:187], v[204:207], v[112:115]
	v_mfma_f32_16x16x32_bf16 v[100:103], v[148:151], v[212:215], v[100:103]
	v_mfma_f32_16x16x32_bf16 v[96:99], v[184:187], v[212:215], v[96:99]
	v_mfma_f32_16x16x32_bf16 v[84:87], v[148:151], v[220:223], v[84:87]
	v_mfma_f32_16x16x32_bf16 v[80:83], v[184:187], v[220:223], v[80:83]
	v_mfma_f32_16x16x32_bf16 v[68:71], v[148:151], v[228:231], v[68:71]
	v_mfma_f32_16x16x32_bf16 v[64:67], v[184:187], v[228:231], v[64:67]
	s_setprio 0
	s_barrier
	s_add_i32 s18, s70, s31
	v_lshl_add_u64 v[232:233], s[20:21], 0, v[152:153]
	s_mov_b32 m0, s18
	ds_read_b128 v[188:191], v202 offset:16384
	ds_read_b128 v[204:207], v202 offset:17408
	ds_read_b128 v[208:211], v202 offset:18432
	ds_read_b128 v[212:215], v202 offset:19456
	ds_read_b128 v[216:219], v202 offset:20480
	ds_read_b128 v[220:223], v202 offset:21504
	ds_read_b128 v[224:227], v202 offset:22528
	ds_read_b128 v[228:231], v202 offset:23552
	global_load_lds_dwordx4 v[232:233], off
	s_add_i32 m0, s18, 0x2000
	s_add_u32 s18, s20, 0x160000
	v_lshl_add_u64 v[234:235], s[20:21], 0, v[174:175]
	s_addc_u32 s19, s21, 0
	s_add_i32 s70, s71, s31
	global_load_lds_dwordx4 v[234:235], off
	v_lshl_add_u64 v[236:237], s[18:19], 0, v[152:153]
	s_mov_b32 m0, s70
	v_lshl_add_u64 v[238:239], s[22:23], 0, v[172:173]
	global_load_lds_dwordx4 v[236:237], off
	v_lshl_add_u64 v[236:237], s[18:19], 0, v[174:175]
	s_add_i32 m0, s70, 0x2000
	s_nop 0
	global_load_lds_dwordx4 v[236:237], off
	v_lshl_add_u64 v[236:237], s[22:23], 0, v[170:171]
	s_mov_b32 m0, s38
	s_nop 0
	global_load_lds_dwordx4 v[236:237], off
	s_mov_b32 m0, s39
	s_nop 0
	global_load_lds_dwordx4 v[238:239], off
	s_waitcnt vmcnt(8)
	s_waitcnt lgkmcnt(0)
	s_barrier
; #define PG8_STAGE(bufoff, gbase, voff) do { _Pragma("unroll") for (int _i = 0; _i < 2; ++_i) \
;         __builtin_amdgcn_global_load_lds((const unsigned*)((const char*)(gbase) + (voff)[_i]), (LAS unsigned*)(lds + (bufoff) + ldsw + _i * 8192), 16, 0, 0); } while (0)
; #define PG8_LDA(dst, b, h) do { _Pragma("unroll") for (int m = 0; m < 4; ++m) _Pragma("unroll") for (int k = 0; k < 2; ++k) dst[m][k] = *(const LAS bf16x8*)(lds + PG8_SA(b, h) + aoff + m * 2048 + k * 1024); } while (0)
; #define PG8_LDB(dst, b, h) do { _Pragma("unroll") for (int n = 0; n < 2; ++n) _Pragma("unroll") for (int k = 0; k < 2; ++k) dst[n][k] = *(const LAS bf16x8*)(lds + PG8_SB(b, h) + boff + n * 2048 + k * 1024); } while (0)
; #define PG8_MMA(ai, bj, At, Bt) do { __builtin_amdgcn_s_setprio(1); _Pragma("unroll") for (int m = 0; m < 4; ++m) _Pragma("unroll") for (int n = 0; n < 2; ++n) _Pragma("unroll") for (int k = 0; k < 2; ++k) \
;         acc[ai][bj][m][n] = __builtin_amdgcn_mfma_f32_16x16x32_bf16(Bt[n][k], At[m][k], acc[ai][bj][m][n], 0, 0, 0); __builtin_amdgcn_s_setprio(0); } while (0)
; #define PG8_WAIT_V(n) asm volatile("s_waitcnt vmcnt(" #n ")" ::: "memory")
; #define PG8_WAIT_L(n) asm volatile("s_waitcnt lgkmcnt(" #n ")" ::: "memory")
; #define PG8_BAR __builtin_amdgcn_s_barrier()
; #define PG8_SCHED __builtin_amdgcn_sched_barrier(0)
; template <class Epi, class Sched>
; __device__ __forceinline__ void gemm_phase(const int tid, LAS unsigned char* lds, const Gemm g, const Sched& S, const Epi& E) {
;     ...
;             PG8_WAIT_V(8); PG8_WAIT_L(0); PG8_BAR; PG8_MMA(1, 0, At, B0); PG8_MMA(1, 1, At, B1); PG8_BAR; PG8_SCHED;
;             PG8_LDB(B0, 1, 0); PG8_LDB(B1, 1, 1); PG8_SCHED; PG8_LDA(At, 1, 0); PG8_STAGE(PG8_SA(0, 1), a2 + hstep, voffA);
;             PG8_WAIT_V(8); PG8_WAIT_L(0); PG8_BAR; PG8_MMA(0, 0, At, B0); PG8_MMA(0, 1, At, B1); PG8_BAR; PG8_SCHED;
;             PG8_LDA(At, 1, 1); PG8_STAGE(PG8_SB(1, 0), b3, voffB); PG8_STAGE(PG8_SB(1, 1), b3 + hstep, voffB); PG8_STAGE(PG8_SA(1, 0), a3, voffA);
;             PG8_WAIT_V(8); PG8_WAIT_L(0); PG8_BAR; PG8_MMA(1, 0, At, B0); PG8_MMA(1, 1, At, B1); PG8_BAR; PG8_SCHED;
	s_setprio 1
	s_waitcnt lgkmcnt(0)
	v_mfma_f32_16x16x32_bf16 v[60:63], v[128:131], v[188:191], 0
	v_mfma_f32_16x16x32_bf16 v[56:59], v[136:139], v[188:191], 0
	v_mfma_f32_16x16x32_bf16 v[44:47], v[128:131], v[208:211], 0
	v_mfma_f32_16x16x32_bf16 v[40:43], v[136:139], v[208:211], 0
	v_mfma_f32_16x16x32_bf16 v[28:31], v[128:131], v[216:219], 0
	v_mfma_f32_16x16x32_bf16 v[24:27], v[136:139], v[216:219], 0
	v_mfma_f32_16x16x32_bf16 v[12:15], v[128:131], v[224:227], 0
	v_mfma_f32_16x16x32_bf16 v[8:11], v[136:139], v[224:227], 0
	v_mfma_f32_16x16x32_bf16 v[60:63], v[132:135], v[204:207], v[60:63]
	v_mfma_f32_16x16x32_bf16 v[56:59], v[140:143], v[204:207], v[56:59]
	v_mfma_f32_16x16x32_bf16 v[44:47], v[132:135], v[212:215], v[44:47]
	v_mfma_f32_16x16x32_bf16 v[40:43], v[140:143], v[212:215], v[40:43]
	v_mfma_f32_16x16x32_bf16 v[28:31], v[132:135], v[220:223], v[28:31]
	v_mfma_f32_16x16x32_bf16 v[24:27], v[140:143], v[220:223], v[24:27]
	v_mfma_f32_16x16x32_bf16 v[12:15], v[132:135], v[228:231], v[12:15]
	v_mfma_f32_16x16x32_bf16 v[8:11], v[140:143], v[228:231], v[8:11]
	s_setprio 0
	s_setprio 1
	v_mfma_f32_16x16x32_bf16 v[52:55], v[144:147], v[188:191], 0
	v_mfma_f32_16x16x32_bf16 v[48:51], v[180:183], v[188:191], 0
	v_mfma_f32_16x16x32_bf16 v[36:39], v[144:147], v[208:211], 0
	v_mfma_f32_16x16x32_bf16 v[32:35], v[180:183], v[208:211], 0
	v_mfma_f32_16x16x32_bf16 v[20:23], v[144:147], v[216:219], 0
	v_mfma_f32_16x16x32_bf16 v[16:19], v[180:183], v[216:219], 0
	v_mfma_f32_16x16x32_bf16 v[4:7], v[144:147], v[224:227], 0
	v_mfma_f32_16x16x32_bf16 v[0:3], v[180:183], v[224:227], 0
	v_mfma_f32_16x16x32_bf16 v[52:55], v[148:151], v[204:207], v[52:55]
	v_mfma_f32_16x16x32_bf16 v[48:51], v[184:187], v[204:207], v[48:51]
	v_mfma_f32_16x16x32_bf16 v[36:39], v[148:151], v[212:215], v[36:39]
	v_mfma_f32_16x16x32_bf16 v[32:35], v[184:187], v[212:215], v[32:35]
	v_mfma_f32_16x16x32_bf16 v[20:23], v[148:151], v[220:223], v[20:23]
	v_mfma_f32_16x16x32_bf16 v[16:19], v[184:187], v[220:223], v[16:19]
	v_mfma_f32_16x16x32_bf16 v[4:7], v[148:151], v[228:231], v[4:7]
	v_mfma_f32_16x16x32_bf16 v[0:3], v[184:187], v[228:231], v[0:3]
	s_setprio 0
	s_barrier
	s_add_i32 s70, 0, 0x18000
	s_add_i32 s71, 0, 0x1c000
	v_add_u32_e32 v140, s70, v201
	v_add_u32_e32 v184, s71, v201
	ds_read_b128 v[128:131], v140
	ds_read_b128 v[132:135], v140 offset:1024
	ds_read_b128 v[136:139], v140 offset:2048
	ds_read_b128 v[140:143], v140 offset:3072
	ds_read_b128 v[144:147], v184
	ds_read_b128 v[148:151], v184 offset:1024
	ds_read_b128 v[180:183], v184 offset:2048
	ds_read_b128 v[184:187], v184 offset:3072
	s_add_u32 s18, s22, 0x160000
	s_addc_u32 s19, s23, 0
	s_mov_b32 m0, s40
	v_lshl_add_u64 v[240:241], s[18:19], 0, v[170:171]
	ds_read_b128 v[188:191], v202 offset:32768
	ds_read_b128 v[204:207], v202 offset:33792
	ds_read_b128 v[208:211], v202 offset:34816
	ds_read_b128 v[212:215], v202 offset:35840
	ds_read_b128 v[216:219], v202 offset:36864
	ds_read_b128 v[220:223], v202 offset:37888
	ds_read_b128 v[224:227], v202 offset:38912
	ds_read_b128 v[228:231], v202 offset:39936
	global_load_lds_dwordx4 v[240:241], off
	v_lshl_add_u64 v[240:241], s[18:19], 0, v[172:173]
	s_mov_b32 m0, s41
	s_nop 0
	global_load_lds_dwordx4 v[240:241], off
	s_waitcnt vmcnt(8)
	s_waitcnt lgkmcnt(0)
	s_barrier
	s_setprio 1
	s_waitcnt lgkmcnt(0)
	v_mfma_f32_16x16x32_bf16 v[124:127], v[128:131], v[188:191], v[124:127]
	v_mfma_f32_16x16x32_bf16 v[120:123], v[136:139], v[188:191], v[120:123]
	v_mfma_f32_16x16x32_bf16 v[108:111], v[128:131], v[208:211], v[108:111]
	v_mfma_f32_16x16x32_bf16 v[104:107], v[136:139], v[208:211], v[104:107]
	v_mfma_f32_16x16x32_bf16 v[92:95], v[128:131], v[216:219], v[92:95]
	v_mfma_f32_16x16x32_bf16 v[88:91], v[136:139], v[216:219], v[88:91]
	v_mfma_f32_16x16x32_bf16 v[76:79], v[128:131], v[224:227], v[76:79]
	v_mfma_f32_16x16x32_bf16 v[72:75], v[136:139], v[224:227], v[72:75]
	v_mfma_f32_16x16x32_bf16 v[124:127], v[132:135], v[204:207], v[124:127]
	v_mfma_f32_16x16x32_bf16 v[120:123], v[140:143], v[204:207], v[120:123]
	v_mfma_f32_16x16x32_bf16 v[108:111], v[132:135], v[212:215], v[108:111]
	v_mfma_f32_16x16x32_bf16 v[104:107], v[140:143], v[212:215], v[104:107]
	v_mfma_f32_16x16x32_bf16 v[92:95], v[132:135], v[220:223], v[92:95]
	v_mfma_f32_16x16x32_bf16 v[88:91], v[140:143], v[220:223], v[88:91]
	v_mfma_f32_16x16x32_bf16 v[76:79], v[132:135], v[228:231], v[76:79]
	v_mfma_f32_16x16x32_bf16 v[72:75], v[140:143], v[228:231], v[72:75]
	s_setprio 0
	s_setprio 1
	v_mfma_f32_16x16x32_bf16 v[116:119], v[144:147], v[188:191], v[116:119]
	v_mfma_f32_16x16x32_bf16 v[112:115], v[180:183], v[188:191], v[112:115]
	v_mfma_f32_16x16x32_bf16 v[100:103], v[144:147], v[208:211], v[100:103]
	v_mfma_f32_16x16x32_bf16 v[96:99], v[180:183], v[208:211], v[96:99]
	v_mfma_f32_16x16x32_bf16 v[84:87], v[144:147], v[216:219], v[84:87]
	v_mfma_f32_16x16x32_bf16 v[80:83], v[180:183], v[216:219], v[80:83]
	v_mfma_f32_16x16x32_bf16 v[68:71], v[144:147], v[224:227], v[68:71]
	v_mfma_f32_16x16x32_bf16 v[64:67], v[180:183], v[224:227], v[64:67]
	v_mfma_f32_16x16x32_bf16 v[116:119], v[148:151], v[204:207], v[116:119]
	v_mfma_f32_16x16x32_bf16 v[112:115], v[184:187], v[204:207], v[112:115]
	v_mfma_f32_16x16x32_bf16 v[100:103], v[148:151], v[212:215], v[100:103]
	v_mfma_f32_16x16x32_bf16 v[96:99], v[184:187], v[212:215], v[96:99]
	v_mfma_f32_16x16x32_bf16 v[84:87], v[148:151], v[220:223], v[84:87]
	v_mfma_f32_16x16x32_bf16 v[80:83], v[184:187], v[220:223], v[80:83]
	v_mfma_f32_16x16x32_bf16 v[68:71], v[148:151], v[228:231], v[68:71]
	v_mfma_f32_16x16x32_bf16 v[64:67], v[184:187], v[228:231], v[64:67]
	s_setprio 0
	s_barrier
; #define PG8_STAGE(bufoff, gbase, voff) do { _Pragma("unroll") for (int _i = 0; _i < 2; ++_i) \
;         __builtin_amdgcn_global_load_lds((const unsigned*)((const char*)(gbase) + (voff)[_i]), (LAS unsigned*)(lds + (bufoff) + ldsw + _i * 8192), 16, 0, 0); } while (0)
; #define PG8_LDA(dst, b, h) do { _Pragma("unroll") for (int m = 0; m < 4; ++m) _Pragma("unroll") for (int k = 0; k < 2; ++k) dst[m][k] = *(const LAS bf16x8*)(lds + PG8_SA(b, h) + aoff + m * 2048 + k * 1024); } while (0)
; #define PG8_MMA(ai, bj, At, Bt) do { __builtin_amdgcn_s_setprio(1); _Pragma("unroll") for (int m = 0; m < 4; ++m) _Pragma("unroll") for (int n = 0; n < 2; ++n) _Pragma("unroll") for (int k = 0; k < 2; ++k) \
;         acc[ai][bj][m][n] = __builtin_amdgcn_mfma_f32_16x16x32_bf16(Bt[n][k], At[m][k], acc[ai][bj][m][n], 0, 0, 0); __builtin_amdgcn_s_setprio(0); } while (0)
; #define PG8_WAIT_V(n) asm volatile("s_waitcnt vmcnt(" #n ")" ::: "memory")
; #define PG8_WAIT_L(n) asm volatile("s_waitcnt lgkmcnt(" #n ")" ::: "memory")
; #define PG8_BAR __builtin_amdgcn_s_barrier()
; #define PG8_SCHED __builtin_amdgcn_sched_barrier(0)
; template <class Epi, class Sched>
; __device__ __forceinline__ void gemm_phase(const int tid, LAS unsigned char* lds, const Gemm g, const Sched& S, const Epi& E) {
;     ...
;         for (int t = 0; t < nt; t += 2) {
;     ...
;             PG8_LDA(At, 1, 1); PG8_STAGE(PG8_SB(1, 0), b3, voffB); PG8_STAGE(PG8_SB(1, 1), b3 + hstep, voffB); PG8_STAGE(PG8_SA(1, 0), a3, voffA);
;             PG8_WAIT_V(8); PG8_WAIT_L(0); PG8_BAR; PG8_MMA(1, 0, At, B0); PG8_MMA(1, 1, At, B1); PG8_BAR; PG8_SCHED;
;         }
	s_add_i32 s18, s70, s31
	v_lshl_add_u64 v[232:233], v[232:233], 0, s[34:35]
	s_mov_b32 m0, s18
	ds_read_b128 v[188:191], v202 offset:49152
	ds_read_b128 v[204:207], v202 offset:50176
	ds_read_b128 v[208:211], v202 offset:51200
	ds_read_b128 v[212:215], v202 offset:52224
	ds_read_b128 v[216:219], v202 offset:53248
	ds_read_b128 v[220:223], v202 offset:54272
	ds_read_b128 v[224:227], v202 offset:55296
	ds_read_b128 v[228:231], v202 offset:56320
	global_load_lds_dwordx4 v[232:233], off
	s_add_i32 m0, s18, 0x2000
	s_add_u32 s18, s20, 0x160080
	v_lshl_add_u64 v[232:233], v[234:235], 0, s[34:35]
	s_addc_u32 s19, s21, 0
	s_add_i32 s20, s71, s31
	global_load_lds_dwordx4 v[232:233], off
	v_lshl_add_u64 v[232:233], s[18:19], 0, v[152:153]
	s_mov_b32 m0, s20
	s_nop 0
	global_load_lds_dwordx4 v[232:233], off
	v_lshl_add_u64 v[232:233], s[18:19], 0, v[174:175]
	s_add_i32 m0, s20, 0x2000
	s_nop 0
	global_load_lds_dwordx4 v[232:233], off
	v_lshl_add_u64 v[232:233], v[236:237], 0, s[34:35]
	s_mov_b32 m0, s58
	s_nop 0
	global_load_lds_dwordx4 v[232:233], off
	v_lshl_add_u64 v[232:233], v[238:239], 0, s[34:35]
	s_mov_b32 m0, s59
	s_nop 0
	global_load_lds_dwordx4 v[232:233], off
	s_waitcnt vmcnt(8)
	s_waitcnt lgkmcnt(0)
	s_barrier
	s_setprio 1
	s_waitcnt lgkmcnt(0)
	v_mfma_f32_16x16x32_bf16 v[60:63], v[128:131], v[188:191], v[60:63]
	v_mfma_f32_16x16x32_bf16 v[56:59], v[136:139], v[188:191], v[56:59]
	v_mfma_f32_16x16x32_bf16 v[44:47], v[128:131], v[208:211], v[44:47]
	v_mfma_f32_16x16x32_bf16 v[40:43], v[136:139], v[208:211], v[40:43]
	v_mfma_f32_16x16x32_bf16 v[28:31], v[128:131], v[216:219], v[28:31]
	v_mfma_f32_16x16x32_bf16 v[24:27], v[136:139], v[216:219], v[24:27]
	v_mfma_f32_16x16x32_bf16 v[12:15], v[128:131], v[224:227], v[12:15]
	v_mfma_f32_16x16x32_bf16 v[8:11], v[136:139], v[224:227], v[8:11]
	v_mfma_f32_16x16x32_bf16 v[60:63], v[132:135], v[204:207], v[60:63]
	v_mfma_f32_16x16x32_bf16 v[56:59], v[140:143], v[204:207], v[56:59]
	v_mfma_f32_16x16x32_bf16 v[44:47], v[132:135], v[212:215], v[44:47]
	v_mfma_f32_16x16x32_bf16 v[40:43], v[140:143], v[212:215], v[40:43]
	v_mfma_f32_16x16x32_bf16 v[28:31], v[132:135], v[220:223], v[28:31]
	v_mfma_f32_16x16x32_bf16 v[24:27], v[140:143], v[220:223], v[24:27]
	v_mfma_f32_16x16x32_bf16 v[12:15], v[132:135], v[228:231], v[12:15]
	v_mfma_f32_16x16x32_bf16 v[8:11], v[140:143], v[228:231], v[8:11]
	s_setprio 0
	s_setprio 1
	v_mfma_f32_16x16x32_bf16 v[52:55], v[144:147], v[188:191], v[52:55]
	v_mfma_f32_16x16x32_bf16 v[48:51], v[180:183], v[188:191], v[48:51]
	v_mfma_f32_16x16x32_bf16 v[36:39], v[144:147], v[208:211], v[36:39]
	v_mfma_f32_16x16x32_bf16 v[32:35], v[180:183], v[208:211], v[32:35]
	v_mfma_f32_16x16x32_bf16 v[20:23], v[144:147], v[216:219], v[20:23]
	v_mfma_f32_16x16x32_bf16 v[16:19], v[180:183], v[216:219], v[16:19]
	v_mfma_f32_16x16x32_bf16 v[4:7], v[144:147], v[224:227], v[4:7]
	v_mfma_f32_16x16x32_bf16 v[0:3], v[180:183], v[224:227], v[0:3]
	v_mfma_f32_16x16x32_bf16 v[52:55], v[148:151], v[204:207], v[52:55]
	v_mfma_f32_16x16x32_bf16 v[48:51], v[184:187], v[204:207], v[48:51]
	v_mfma_f32_16x16x32_bf16 v[36:39], v[148:151], v[212:215], v[36:39]
	v_mfma_f32_16x16x32_bf16 v[32:35], v[184:187], v[212:215], v[32:35]
	v_mfma_f32_16x16x32_bf16 v[20:23], v[148:151], v[220:223], v[20:23]
	v_mfma_f32_16x16x32_bf16 v[16:19], v[184:187], v[220:223], v[16:19]
	v_mfma_f32_16x16x32_bf16 v[4:7], v[148:151], v[228:231], v[4:7]
	v_mfma_f32_16x16x32_bf16 v[0:3], v[184:187], v[228:231], v[0:3]
	s_setprio 0
	s_barrier
	s_add_i32 s69, s69, 2
	s_add_u32 s67, s67, 0x100
	s_addc_u32 s68, s68, 0
	s_cmpk_gt_u32 s69, 0x55
	s_mov_b64 s[18:19], s[4:5]

; __device__ __forceinline__ unsigned cvt_pk_bf16(float lo, float hi) { unsigned r; asm volatile("v_cvt_pk_bf16_f32 %0, %1, %2" : "=v"(r) : "v"(lo), "v"(hi)); return r; }
;     __device__ __forceinline__ void operator()(const f32x4 (&acc)[2][2][4][2], const Unit& u, int wr, int wc, int fr, int fq) const {
;     ...
;                 for (int bj = 0; bj < 2; ++bj) xv[m][bj] = *(const u32x4*)(X + (size_t)(row0 + ai * HALF + m * 16) * ldc + col0 + bj * HALF);
;             asm volatile("" ::: "memory");
; #pragma unroll
;             for (int m = 0; m < 4; ++m) { const int row = row0 + ai * HALF + m * 16; bf16_t* rowp = X + (size_t)row * ldc + col0;
;                 float part = 0.f;
; #pragma unroll
;                 for (int bj = 0; bj < 2; ++bj) { const u32x4 x4 = xv[m][bj];
;                     const f32x4 a0 = acc[ai][bj][m][0], a1 = acc[ai][bj][m][1];
;                     const float f0 = bflo(x4.x) + a0[0], f1 = bfhi(x4.x) + a0[1], f2 = bflo(x4.y) + a0[2], f3 = bfhi(x4.y) + a0[3];
;                     const float f4 = bflo(x4.z) + a1[0], f5 = bfhi(x4.z) + a1[1], f6 = bflo(x4.w) + a1[2], f7 = bfhi(x4.w) + a1[3];
;                     part += (f0 * f0 + f1 * f1) + (f2 * f2 + f3 * f3) + (f4 * f4 + f5 * f5) + (f6 * f6 + f7 * f7);
;                     u32x4 w; w.x = cvt_pk_bf16(f0, f1); w.y = cvt_pk_bf16(f2, f3); w.z = cvt_pk_bf16(f4, f5); w.w = cvt_pk_bf16(f6, f7);
;                     *(u32x4*)(rowp + bj * HALF) = w; }
;                 part += __shfl_xor(part, 16); part += __shfl_xor(part, 32);
;                 if (fq == 0) SS[(size_t)row * 32 + u.pn * 4 + wc] = part; }
.LBB0_774:
	s_or_b64 exec, exec, s[4:5]
	v_add_u32_e32 v98, 0x80, v184
	v_ashrrev_i32_e32 v99, 31, v98
	v_lshlrev_b64 v[100:101], 12, v[98:99]
	s_waitcnt lgkmcnt(0)
	v_lshl_add_u64 v[64:65], v[182:183], 0, v[100:101]
	s_waitcnt vmcnt(12)
	v_mov_b64_e32 v[102:103], v[222:223]
	v_mov_b64_e32 v[104:105], v[224:225]
	v_mov_b64_e32 v[88:89], v[226:227]
	v_mov_b64_e32 v[90:91], v[228:229]
	v_add_u32_e32 v96, 0x90, v184
	v_ashrrev_i32_e32 v97, 31, v96
	v_lshlrev_b64 v[64:65], 12, v[96:97]
	v_add_u32_e32 v94, 0xa0, v184
	v_lshl_add_u64 v[64:65], v[182:183], 0, v[64:65]
	v_ashrrev_i32_e32 v95, 31, v94
	v_mov_b64_e32 v[84:85], v[230:231]
	v_mov_b64_e32 v[86:87], v[232:233]
	v_mov_b64_e32 v[80:81], v[234:235]
	v_mov_b64_e32 v[82:83], v[236:237]
	v_lshlrev_b64 v[64:65], 12, v[94:95]
	v_add_u32_e32 v92, 0xb0, v184
	v_lshl_add_u64 v[64:65], v[182:183], 0, v[64:65]
	v_ashrrev_i32_e32 v93, 31, v92
	v_mov_b64_e32 v[76:77], v[238:239]
	v_mov_b64_e32 v[78:79], v[240:241]
	v_mov_b64_e32 v[72:73], v[244:245]
	v_mov_b64_e32 v[74:75], v[246:247]
	v_lshlrev_b64 v[64:65], 12, v[92:93]
	v_lshl_add_u64 v[64:65], v[182:183], 0, v[64:65]
	v_mov_b64_e32 v[68:69], v[248:249]
	v_mov_b64_e32 v[70:71], v[250:251]
	s_nop 0
	v_mov_b64_e32 v[64:65], v[252:253]
	v_mov_b64_e32 v[66:67], v[254:255]
	v_lshl_add_u64 v[100:101], s[8:9], 0, v[100:101]
	v_lshl_add_u64 v[100:101], v[180:181], 1, v[100:101]
	v_lshlrev_b32_e32 v106, 16, v102
	v_and_b32_e32 v102, 0xffff0000, v102
	v_add_f32_e32 v61, v61, v102
	v_lshlrev_b32_e32 v102, 16, v103
	v_add_f32_e32 v62, v62, v102
	v_and_b32_e32 v102, 0xffff0000, v103
	v_add_f32_e32 v63, v63, v102
	v_lshlrev_b32_e32 v102, 16, v104
	v_add_f32_e32 v102, v56, v102
	v_and_b32_e32 v56, 0xffff0000, v104
	v_add_f32_e32 v103, v57, v56
	v_lshlrev_b32_e32 v56, 16, v105
	v_add_f32_e32 v104, v58, v56
	v_and_b32_e32 v56, 0xffff0000, v105
	v_add_f32_e32 v60, v60, v106
	v_add_f32_e32 v59, v59, v56
	v_mul_f32_e32 v56, v61, v61
	v_mul_f32_e32 v57, v63, v63
	v_fmac_f32_e32 v56, v60, v60
	v_fmac_f32_e32 v57, v62, v62
	v_add_f32_e32 v56, v56, v57
	v_mul_f32_e32 v57, v103, v103
	v_fmac_f32_e32 v57, v102, v102
	v_add_f32_e32 v56, v57, v56
	v_mul_f32_e32 v57, v59, v59
	v_fmac_f32_e32 v57, v104, v104
	v_add_f32_e32 v105, v57, v56
	v_cvt_pk_bf16_f32 v56, v60, v61
	v_cvt_pk_bf16_f32 v57, v62, v63
	v_cvt_pk_bf16_f32 v58, v102, v103
	v_cvt_pk_bf16_f32 v59, v104, v59
	global_store_dwordx4 v[100:101], v[56:59], off
	s_nop 0
	v_lshlrev_b32_e32 v56, 16, v88
	v_add_f32_e32 v52, v52, v56
	v_and_b32_e32 v56, 0xffff0000, v88
	v_add_f32_e32 v53, v53, v56
	v_lshlrev_b32_e32 v56, 16, v89
	v_add_f32_e32 v54, v54, v56
	v_and_b32_e32 v56, 0xffff0000, v89
	v_add_f32_e32 v55, v55, v56
	v_lshlrev_b32_e32 v56, 16, v90
	v_add_f32_e32 v56, v48, v56
	v_and_b32_e32 v48, 0xffff0000, v90
	v_add_f32_e32 v57, v49, v48
	v_lshlrev_b32_e32 v48, 16, v91
	v_add_f32_e32 v58, v50, v48
	v_and_b32_e32 v48, 0xffff0000, v91
	v_add_f32_e32 v51, v51, v48
	v_mul_f32_e32 v48, v53, v53
	v_mul_f32_e32 v49, v55, v55
	v_fmac_f32_e32 v48, v52, v52
	v_fmac_f32_e32 v49, v54, v54
	v_add_f32_e32 v48, v48, v49
	v_mul_f32_e32 v49, v57, v57
	v_fmac_f32_e32 v49, v56, v56
	v_add_f32_e32 v48, v49, v48
	v_mul_f32_e32 v49, v51, v51
	v_fmac_f32_e32 v49, v58, v58
	v_add_f32_e32 v48, v49, v48
	v_add_f32_e32 v59, v105, v48
	v_cvt_pk_bf16_f32 v48, v52, v53
	v_cvt_pk_bf16_f32 v49, v54, v55
	v_cvt_pk_bf16_f32 v50, v56, v57
	v_cvt_pk_bf16_f32 v51, v58, v51
	global_store_dwordx4 v[100:101], v[48:51], off offset:256
	ds_bpermute_b32 v48, v112, v59
	s_waitcnt lgkmcnt(0)
	v_add_f32_e32 v48, v59, v48
	ds_bpermute_b32 v49, v113, v48
	s_and_saveexec_b64 s[4:5], vcc
	s_cbranch_execz .LBB0_776
	v_lshlrev_b64 v[50:51], 7, v[98:99]
	v_lshl_add_u64 v[50:51], s[10:11], 0, v[50:51]
	v_lshl_add_u64 v[50:51], s[18:19], 2, v[50:51]
	s_lshl_b32 s76, s55, 2
	v_lshl_add_u64 v[50:51], v[50:51], 0, s[76:77]
	s_waitcnt lgkmcnt(0)
	v_add_f32_e32 v48, v48, v49
	global_store_dword v[50:51], v48, off

; __device__ __forceinline__ void phase_final(const bf16_t* X, const float* SS, const float* g, float* out, const Ctx cx) {
;     ...
;     for (int m = gw; m < T; m += NGW) {
;         const float rs = 1.0f / sqrtf(wave_sum(lane < 32 ? SS[(size_t)m * 32 + lane] : 0.f) * (1.0f / DM) + EPS);
; #pragma unroll
;         for (int j = 0; j < 4; ++j) { const u32x4 w = *(const u32x4*)(X + (size_t)m * DM + j * 512 + lane * 8);
;             const f32x4 g0 = *(const f32x4*)(g + j * 512 + lane * 8), g1 = *(const f32x4*)(g + j * 512 + lane * 8 + 4);
;             f32x4 o0, o1; o0.x = bflo(w.x) * rs * g0.x; o0.y = bfhi(w.x) * rs * g0.y; o0.z = bflo(w.y) * rs * g0.z; o0.w = bfhi(w.y) * rs * g0.w;
;             o1.x = bflo(w.z) * rs * g1.x; o1.y = bfhi(w.z) * rs * g1.y; o1.z = bflo(w.w) * rs * g1.z; o1.w = bfhi(w.w) * rs * g1.w;
;             float* op = out + (size_t)m * DM + j * 512 + lane * 8; *(f32x4*)op = o0; *(f32x4*)(op + 4) = o1; }
;     }
.LBB0_848:
	s_or_b64 exec, exec, s[2:3]
	global_load_dwordx4 v[90:93], v[8:9], off
	global_load_dwordx4 v[94:97], v[8:9], off offset:1024
	global_load_dwordx4 v[98:101], v[8:9], off offset:2048
	global_load_dwordx4 v[102:105], v[8:9], off offset:3072
	s_waitcnt vmcnt(3)
	v_mov_b64_e32 v[22:23], v[90:91]
	v_mov_b64_e32 v[24:25], v[92:93]
	v_mov_b64_e32 v[26:27], v[50:51]
	v_mov_b64_e32 v[28:29], v[52:53]
	v_mov_b64_e32 v[30:31], v[54:55]
	v_mov_b64_e32 v[32:33], v[56:57]
	ds_bpermute_b32 v21, v12, v20
	s_add_i32 s4, s4, s6
	v_lshl_add_u64 v[6:7], v[6:7], 0, s[8:9]
	s_cmp_lt_i32 s4, 0x8000
	s_waitcnt lgkmcnt(0)
	v_add_f32_e32 v20, v20, v21
	ds_bpermute_b32 v21, v13, v20
	s_waitcnt lgkmcnt(0)
	v_add_f32_e32 v20, v20, v21
	ds_bpermute_b32 v21, v14, v20
	s_waitcnt lgkmcnt(0)
	v_add_f32_e32 v20, v20, v21
	ds_bpermute_b32 v21, v15, v20
	s_waitcnt lgkmcnt(0)
	v_add_f32_e32 v20, v20, v21
	ds_bpermute_b32 v21, v16, v20
	s_waitcnt lgkmcnt(0)
	v_add_f32_e32 v20, v20, v21
	ds_bpermute_b32 v21, v17, v20
	s_waitcnt lgkmcnt(0)
	v_add_f32_e32 v20, v20, v21
	v_fmamk_f32 v20, v20, 0x3a000000, v18
	v_mul_f32_e32 v21, 0x4f800000, v20
	v_cmp_gt_f32_e32 vcc, s5, v20
	s_nop 1
	v_cndmask_b32_e32 v20, v20, v21, vcc
	v_sqrt_f32_e32 v21, v20
	s_nop 0
	v_add_u32_e32 v34, -1, v21
	v_add_u32_e32 v35, 1, v21
	v_fma_f32 v36, -v34, v21, v20
	v_fma_f32 v37, -v35, v21, v20
	v_cmp_ge_f32_e64 s[2:3], 0, v36
	s_nop 1
	v_cndmask_b32_e64 v21, v21, v34, s[2:3]
	v_cmp_lt_f32_e64 s[2:3], 0, v37
	s_nop 1
	v_cndmask_b32_e64 v21, v21, v35, s[2:3]
	v_mul_f32_e32 v34, 0x37800000, v21
	v_cndmask_b32_e32 v21, v21, v34, vcc
	v_cmp_class_f32_e32 vcc, v20, v19
	s_nop 1
	v_cndmask_b32_e32 v20, v21, v20, vcc
	v_div_scale_f32 v21, s[2:3], v20, v20, 1.0
	v_rcp_f32_e32 v34, v21
	v_div_scale_f32 v35, vcc, 1.0, v20, 1.0
	v_fma_f32 v36, -v21, v34, 1.0
	v_fmac_f32_e32 v34, v36, v34
	v_mul_f32_e32 v36, v35, v34
	v_fma_f32 v37, -v21, v36, v35
	v_fmac_f32_e32 v36, v37, v34
	v_fma_f32 v21, -v21, v36, v35
	v_div_fmas_f32 v21, v21, v34, v36
	v_div_fixup_f32 v34, v21, v20, 1.0
	v_lshlrev_b32_e32 v20, 16, v22
	v_and_b32_e32 v21, 0xffff0000, v22
	v_lshlrev_b32_e32 v22, 16, v23
	v_and_b32_e32 v23, 0xffff0000, v23
	v_lshlrev_b32_e32 v36, 16, v24
	v_and_b32_e32 v37, 0xffff0000, v24
	v_lshlrev_b32_e32 v24, 16, v25
	v_and_b32_e32 v25, 0xffff0000, v25
	v_pk_mul_f32 v[20:21], v[34:35], v[20:21] op_sel_hi:[0,1]
	v_pk_mul_f32 v[22:23], v[34:35], v[22:23] op_sel_hi:[0,1]
	v_pk_mul_f32 v[36:37], v[34:35], v[36:37] op_sel_hi:[0,1]
	v_pk_mul_f32 v[38:39], v[34:35], v[24:25] op_sel_hi:[0,1]
	v_pk_mul_f32 v[20:21], v[26:27], v[20:21]
	v_pk_mul_f32 v[22:23], v[28:29], v[22:23]
	v_pk_mul_f32 v[24:25], v[30:31], v[36:37]
	v_pk_mul_f32 v[26:27], v[32:33], v[38:39]
	global_store_dwordx4 v[10:11], v[20:23], off offset:-4096
	global_store_dwordx4 v[10:11], v[24:27], off offset:-4080
	s_nop 0
	s_waitcnt vmcnt(4)
	v_mov_b64_e32 v[20:21], v[94:95]
	v_mov_b64_e32 v[22:23], v[96:97]
	v_lshlrev_b32_e32 v32, 16, v20
	v_and_b32_e32 v33, 0xffff0000, v20
	v_lshlrev_b32_e32 v20, 16, v21
	v_and_b32_e32 v21, 0xffff0000, v21
	v_lshlrev_b32_e32 v36, 16, v22
	v_and_b32_e32 v37, 0xffff0000, v22
	v_lshlrev_b32_e32 v22, 16, v23
	v_and_b32_e32 v23, 0xffff0000, v23
	v_pk_mul_f32 v[32:33], v[34:35], v[32:33] op_sel_hi:[0,1]
	v_pk_mul_f32 v[38:39], v[34:35], v[20:21] op_sel_hi:[0,1]
	v_pk_mul_f32 v[36:37], v[34:35], v[36:37] op_sel_hi:[0,1]
	v_pk_mul_f32 v[40:41], v[34:35], v[22:23] op_sel_hi:[0,1]
	v_mov_b64_e32 v[24:25], v[58:59]
	v_mov_b64_e32 v[26:27], v[60:61]
	v_pk_mul_f32 v[20:21], v[24:25], v[32:33]
	v_pk_mul_f32 v[22:23], v[26:27], v[38:39]
	v_mov_b64_e32 v[28:29], v[62:63]
	v_mov_b64_e32 v[30:31], v[64:65]
	v_pk_mul_f32 v[24:25], v[28:29], v[36:37]
	v_pk_mul_f32 v[26:27], v[30:31], v[40:41]
	global_store_dwordx4 v[10:11], v[20:23], off offset:-2048
	global_store_dwordx4 v[10:11], v[24:27], off offset:-2032
	s_nop 0
	s_waitcnt vmcnt(5)
	v_mov_b64_e32 v[20:21], v[98:99]
	v_mov_b64_e32 v[22:23], v[100:101]
	v_lshlrev_b32_e32 v32, 16, v20
	v_and_b32_e32 v33, 0xffff0000, v20
	v_lshlrev_b32_e32 v20, 16, v21
	v_and_b32_e32 v21, 0xffff0000, v21
	v_lshlrev_b32_e32 v36, 16, v22
	v_and_b32_e32 v37, 0xffff0000, v22
	v_lshlrev_b32_e32 v22, 16, v23
	v_and_b32_e32 v23, 0xffff0000, v23
	v_pk_mul_f32 v[32:33], v[34:35], v[32:33] op_sel_hi:[0,1]
	v_pk_mul_f32 v[38:39], v[34:35], v[20:21] op_sel_hi:[0,1]
	v_pk_mul_f32 v[36:37], v[34:35], v[36:37] op_sel_hi:[0,1]
	v_pk_mul_f32 v[40:41], v[34:35], v[22:23] op_sel_hi:[0,1]
	v_mov_b64_e32 v[24:25], v[66:67]
	v_mov_b64_e32 v[26:27], v[68:69]
	v_pk_mul_f32 v[20:21], v[24:25], v[32:33]
	v_pk_mul_f32 v[22:23], v[26:27], v[38:39]
	v_mov_b64_e32 v[28:29], v[70:71]
	v_mov_b64_e32 v[30:31], v[72:73]
	v_pk_mul_f32 v[24:25], v[28:29], v[36:37]
	v_pk_mul_f32 v[26:27], v[30:31], v[40:41]
	global_store_dwordx4 v[10:11], v[20:23], off
	global_store_dwordx4 v[10:11], v[24:27], off offset:16
	s_nop 0
	v_lshl_add_u64 v[8:9], v[8:9], 0, s[10:11]
	s_waitcnt vmcnt(6)
	v_mov_b64_e32 v[20:21], v[102:103]
	v_mov_b64_e32 v[22:23], v[104:105]
	v_lshlrev_b32_e32 v32, 16, v20
	v_and_b32_e32 v33, 0xffff0000, v20
	v_lshlrev_b32_e32 v20, 16, v21
	v_and_b32_e32 v21, 0xffff0000, v21
	v_lshlrev_b32_e32 v36, 16, v22
	v_and_b32_e32 v37, 0xffff0000, v22
	v_lshlrev_b32_e32 v22, 16, v23
	v_and_b32_e32 v23, 0xffff0000, v23
	v_pk_mul_f32 v[32:33], v[34:35], v[32:33] op_sel_hi:[0,1]
	v_pk_mul_f32 v[38:39], v[34:35], v[20:21] op_sel_hi:[0,1]
	v_pk_mul_f32 v[36:37], v[34:35], v[36:37] op_sel_hi:[0,1]
	v_pk_mul_f32 v[34:35], v[34:35], v[22:23] op_sel_hi:[0,1]
	v_mov_b64_e32 v[24:25], v[74:75]
	v_mov_b64_e32 v[26:27], v[76:77]
	v_pk_mul_f32 v[20:21], v[24:25], v[32:33]
	v_pk_mul_f32 v[22:23], v[26:27], v[38:39]
	v_mov_b64_e32 v[28:29], v[78:79]
	v_mov_b64_e32 v[30:31], v[80:81]
	v_pk_mul_f32 v[24:25], v[28:29], v[36:37]
	v_pk_mul_f32 v[26:27], v[30:31], v[34:35]
	global_store_dwordx4 v[10:11], v[20:23], off offset:2048
	global_store_dwordx4 v[10:11], v[24:27], off offset:2064
	v_lshl_add_u64 v[10:11], v[10:11], 0, s[12:13]
	s_cbranch_scc0 .LBB0_851
